# EpiConv stores coalesced: bf16 outputs lane-transposed with ds_bpermute_b32 and n=0/n=1 halves merged into one 16-byte store per lane (64 contiguous bytes per token row)
# baseline (speedup 1.0000x reference)
; #define PG8_LAS __attribute__((address_space(3)))
;     __device__ __forceinline__ void operator()(const f32x4 (&acc)[2][2][4][2], const Unit& u, int wr, int wc, int fr, int fq) const {
;     ...
;         const bool edge = (tstart <= 0) || (tstart + 256 >= T);
;         const int ch0 = 128 * u.pn + 32 * wc + 8 * fq;
;         f32x4 w0[2], w1[2], w2[2], bb[2];
; #pragma unroll
;         for (int bj = 0; bj < 2; ++bj) { const int col = bj * 2816 + ch0;
;             w0[bj] = *(const f32x4*)(cw + col); w1[bj] = *(const f32x4*)(cw + 5632 + col); w2[bj] = *(const f32x4*)(cw + 11264 + col); bb[bj] = *(const f32x4*)(cb + col); }
; #pragma unroll
;         for (int ai = 0; ai < 2; ++ai) { const int blk = ai * 2 + wr;
;             if (fr == 0) {
; #pragma unroll
;                 for (int bj = 0; bj < 2; ++bj)
; #pragma unroll
;                     for (int n = 0; n < 2; ++n) *(PG8_LAS f32x4*)(xb + ((((blk * 2 + 0) * 4 + wc) * 4 + fq) * 16 + (bj * 2 + n) * 4)) = acc[ai][bj][0][n]; }
;             if (fr == 15) {
; #pragma unroll
;                 for (int bj = 0; bj < 2; ++bj)
; #pragma unroll
;                     for (int n = 0; n < 2; ++n) *(PG8_LAS f32x4*)(xb + ((((blk * 2 + 1) * 4 + wc) * 4 + fq) * 16 + (bj * 2 + n) * 4)) = acc[ai][bj][3][n]; } }
;         asm volatile("s_waitcnt lgkmcnt(0)" ::: "memory"); __builtin_amdgcn_s_barrier(); asm volatile("" ::: "memory");
;         const f32x4 zero4 = {0.f, 0.f, 0.f, 0.f};
; #pragma unroll
;         for (int n = 0; n < 2; ++n) {
;             if (n == 1) {
; #pragma unroll
;                 for (int bj = 0; bj < 2; ++bj) { const int col = bj * 2816 + ch0 + 4;
;                     w0[bj] = *(const f32x4*)(cw + col); w1[bj] = *(const f32x4*)(cw + 5632 + col); w2[bj] = *(const f32x4*)(cw + 11264 + col); bb[bj] = *(const f32x4*)(cb + col); } }
; #pragma unroll
;             for (int ai = 0; ai < 2; ++ai) { const int blk = ai * 2 + wr;
; #pragma unroll
;                 for (int m = 0; m < 4; ++m) { const int r = 128 * ai + 64 * wr + 16 * m + fr, t = tstart + r;
;                     const bool upok = t >= 1, dnok = (t + 1) < T, store_ok = (r >= vlo) && (r < vhi) && (t < T);
.LBB0_705:
	v_lshl_or_b32 v248, s2, 7, v229
	v_lshlrev_b32_e32 v247, 1, v248
	v_lshlrev_b32_e32 v248, 2, v248
	v_add_u32_e32 v249, 0x2c00, v248
	global_load_dwordx4 v[106:109], v248, s[62:63]
	global_load_dwordx4 v[110:113], v248, s[66:67]
	global_load_dwordx4 v[114:117], v248, s[68:69]
	global_load_dwordx4 v[118:121], v248, s[64:65]
	global_load_dwordx4 v[122:125], v249, s[62:63]
	global_load_dwordx4 v[126:129], v249, s[66:67]
	global_load_dwordx4 v[130:133], v249, s[68:69]
	global_load_dwordx4 v[134:137], v249, s[64:65]
	v_readlane_b32 s10, v254, 4
	v_readlane_b32 s11, v254, 5
	s_add_i32 s0, s78, s48
	s_mulk_i32 s0, 0x1600
	s_movk_i32 s29, 0x1600
	s_add_i32 s28, s93, -1
	v_add_u32_e32 v247, s0, v247
	v_mov_b32_e32 v202, 0
	v_mov_b32_e32 v203, 0
	v_and_b32_e32 v250, 7, v226
	v_lshlrev_b32_e32 v250, 3, v250
	v_add_u32_e32 v250, 0x27000, v250
	ds_write_b64 v250, v[202:203]
	s_mov_b64 exec, s[6:7]
	ds_write_b128 v238, v[166:169]
	ds_write_b128 v238, v[70:73] offset:16
	ds_write_b128 v238, v[162:165] offset:32
	ds_write_b128 v238, v[66:69] offset:48
	ds_write_b128 v239, v[102:105]
	ds_write_b128 v239, v[30:33] offset:16
	ds_write_b128 v239, v[98:101] offset:32
	ds_write_b128 v239, v[26:29] offset:48
	s_mov_b64 exec, s[4:5]
	ds_write_b128 v238, v[142:145] offset:1024
	ds_write_b128 v238, v[46:49] offset:1040
	ds_write_b128 v238, v[138:141] offset:1056
	ds_write_b128 v238, v[42:45] offset:1072
	ds_write_b128 v239, v[78:81] offset:1024
	ds_write_b128 v239, v[6:9] offset:1040
	ds_write_b128 v239, v[74:77] offset:1056
	ds_write_b128 v239, v[2:5] offset:1072
	s_mov_b64 exec, -1
	v_and_b32_e32 v250, 0xb80, v238
	v_lshlrev_b32_e32 v250, 3, v250
	v_bfe_u32 v251, v238, 6, 1
	v_lshl_add_u32 v250, v251, 3, v250
	v_lshl_add_u32 v250, v226, 4, v250
	v_add_u32_e32 v243, 0x20000, v250
	v_add_u32_e32 v244, 0xfffffff0, v243
	v_add_u32_e32 v250, 0xfffffc00, v238
	v_mov_b32_e32 v251, 0x27000
	v_cndmask_b32_e64 v245, v251, v250, s[74:75]
	v_add_u32_e32 v250, 0x800, v239
	v_cndmask_b32_e64 v246, v250, v251, s[74:75]
	s_waitcnt lgkmcnt(0)
	s_barrier
	s_cmp_lt_i32 s48, 1
	s_cbranch_scc1 .Lec_edge
	s_add_i32 s0, s48, 0x100
	s_cmp_ge_i32 s0, s93
	s_cbranch_scc1 .Lec_edge
	v_mbcnt_lo_u32_b32 v251, -1, 0
	v_mbcnt_hi_u32_b32 v251, -1, v251
	v_and_b32_e32 v220, 3, v251
	v_lshrrev_b32_e32 v251, 2, v251
	v_lshl_add_u32 v250, v220, 4, v251
	v_lshlrev_b32_e32 v250, 2, v250
	v_sub_u32_e32 v221, v227, v226
	v_add_u32_e32 v251, v221, v251
	v_and_b32_e32 v221, 0x60, v229
	v_lshl_add_u32 v221, v220, 3, v221
	v_lshl_or_b32 v221, s2, 7, v221
	v_lshlrev_b32_e32 v221, 1, v221
	s_add_i32 s0, s78, s48
	s_mulk_i32 s0, 0x1600
	v_add_u32_e32 v221, s0, v221
	v_mad_u32_u24 v247, v251, s29, v221
	v_add_u32_e32 v220, 0, v251
	v_cmp_le_i32_e64 s[12:13], s54, v220
	v_cmp_gt_i32_e32 vcc, s55, v220
	s_and_b64 s[12:13], s[12:13], vcc
	v_add_u32_e32 v220, 16, v251
	v_cmp_le_i32_e64 s[14:15], s54, v220
	v_cmp_gt_i32_e32 vcc, s55, v220
	s_and_b64 s[14:15], s[14:15], vcc
	v_add_u32_e32 v220, 32, v251
	v_cmp_le_i32_e64 s[16:17], s54, v220
	v_cmp_gt_i32_e32 vcc, s55, v220
	s_and_b64 s[16:17], s[16:17], vcc
	v_add_u32_e32 v220, 48, v251
	v_cmp_le_i32_e64 s[18:19], s54, v220
	v_cmp_gt_i32_e32 vcc, s55, v220
	s_and_b64 s[18:19], s[18:19], vcc
	v_add_u32_e32 v220, 128, v251
	v_cmp_le_i32_e64 s[20:21], s54, v220
	v_cmp_gt_i32_e32 vcc, s55, v220
	s_and_b64 s[20:21], s[20:21], vcc
	v_add_u32_e32 v220, 144, v251
	v_cmp_le_i32_e64 s[22:23], s54, v220
	v_cmp_gt_i32_e32 vcc, s55, v220
	s_and_b64 s[22:23], s[22:23], vcc
	v_add_u32_e32 v220, 160, v251
	v_cmp_le_i32_e64 s[24:25], s54, v220
	v_cmp_gt_i32_e32 vcc, s55, v220
	s_and_b64 s[24:25], s[24:25], vcc
	v_add_u32_e32 v220, 176, v251
	v_cmp_le_i32_e64 s[26:27], s54, v220
	v_cmp_gt_i32_e32 vcc, s55, v220
	s_and_b64 s[26:27], s[26:27], vcc
	ds_write_b64 v243, v[166:167]
	ds_write_b64 v243, v[158:159] offset:256
	ds_write_b64 v243, v[150:151] offset:512
	ds_write_b64 v243, v[142:143] offset:768
	ds_read_b64 v[170:171], v244
	ds_read_b64 v[178:179], v243 offset:16
	ds_read_b64 v[198:199], v245
	ds_read_b64 v[172:173], v244 offset:256
	ds_read_b64 v[180:181], v243 offset:272
	ds_read_b64 v[174:175], v244 offset:512
	ds_read_b64 v[194:195], v243 offset:528
	ds_read_b64 v[176:177], v244 offset:768
	ds_read_b64 v[196:197], v243 offset:784
	ds_read_b64 v[200:201], v238 offset:2048
	s_waitcnt vmcnt(0)
	ds_write_b64 v243, v[168:169]
	ds_write_b64 v243, v[160:161] offset:256
	ds_write_b64 v243, v[152:153] offset:512
	ds_write_b64 v243, v[144:145] offset:768
	s_waitcnt lgkmcnt(11)
	v_cndmask_b32_e64 v170, v170, v198, s[6:7]
	v_cndmask_b32_e64 v171, v171, v199, s[6:7]
	v_pk_fma_f32 v[202:203], v[106:107], v[170:171], v[118:119]
	v_pk_fma_f32 v[166:167], v[166:167], v[110:111], v[202:203]
	v_pk_fma_f32 v[166:167], v[114:115], v[178:179], v[166:167]
	ds_read_b64 v[170:171], v244
	ds_read_b64 v[178:179], v243 offset:16
	ds_read_b64 v[198:199], v245 offset:8
	s_waitcnt lgkmcnt(12)
	v_pk_fma_f32 v[202:203], v[106:107], v[172:173], v[118:119]
	v_pk_fma_f32 v[158:159], v[158:159], v[110:111], v[202:203]
	v_pk_fma_f32 v[158:159], v[114:115], v[180:181], v[158:159]
	ds_read_b64 v[172:173], v244 offset:256
	ds_read_b64 v[180:181], v243 offset:272
	s_waitcnt lgkmcnt(12)
	v_pk_fma_f32 v[202:203], v[106:107], v[174:175], v[118:119]
	v_pk_fma_f32 v[150:151], v[150:151], v[110:111], v[202:203]
	v_pk_fma_f32 v[150:151], v[114:115], v[194:195], v[150:151]
	ds_read_b64 v[174:175], v244 offset:512
	ds_read_b64 v[194:195], v243 offset:528
	s_waitcnt lgkmcnt(11)
; #define PG8_LAS __attribute__((address_space(3)))
; __device__ __forceinline__ float dpp_ror1(float v) { return __builtin_bit_cast(float, __builtin_amdgcn_update_dpp(0, __builtin_bit_cast(int, v), 0x121, 0xf, 0xf, false)); }
; __device__ __forceinline__ float dpp_ror15(float v) { return __builtin_bit_cast(float, __builtin_amdgcn_update_dpp(0, __builtin_bit_cast(int, v), 0x12F, 0xf, 0xf, false)); }
;     __device__ __forceinline__ void operator()(const f32x4 (&acc)[2][2][4][2], const Unit& u, int wr, int wc, int fr, int fq) const {
;     ...
;                 for (int m = 0; m < 4; ++m) { const int r = 128 * ai + 64 * wr + 16 * m + fr, t = tstart + r;
;                     const bool upok = t >= 1, dnok = (t + 1) < T, store_ok = (r >= vlo) && (r < vhi) && (t < T);
;                     f32x4 res[2];
; #pragma unroll
;                     for (int bj = 0; bj < 2; ++bj) { const f32x4 cur = acc[ai][bj][m][n];
;                         f32x4 su = cur, sd = cur;
;                         if (m > 0) { if (fr == 15) su = acc[ai][bj][m > 0 ? m - 1 : 0][n]; }
;                         if (m < 3) { if (fr == 0) sd = acc[ai][bj][m < 3 ? m + 1 : 3][n]; }
;                         f32x4 up, dn;
;                         up[0] = dpp_ror1(su[0]); up[1] = dpp_ror1(su[1]); up[2] = dpp_ror1(su[2]); up[3] = dpp_ror1(su[3]);
;                         dn[0] = dpp_ror15(sd[0]); dn[1] = dpp_ror15(sd[1]); dn[2] = dpp_ror15(sd[2]); dn[3] = dpp_ror15(sd[3]);
;                         if (m == 0) { f32x4 halo = zero4; if (blk > 0) halo = *(const PG8_LAS f32x4*)(xb + (((((blk - 1) * 2 + 1) * 4 + wc) * 4 + fq) * 16 + (bj * 2 + n) * 4)); if (fr == 0) up = halo; }
;                         if (m == 3) { f32x4 halo = zero4; if (blk < 3) halo = *(const PG8_LAS f32x4*)(xb + (((((blk + 1) * 2 + 0) * 4 + wc) * 4 + fq) * 16 + (bj * 2 + n) * 4)); if (fr == 15) dn = halo; }
;                         if (edge) { if (!upok) up = zero4; if (!dnok) dn = zero4; }
;                         res[bj] = bb[bj] + w0[bj] * up + w1[bj] * cur + w2[bj] * dn; }
	v_cndmask_b32_e64 v196, v196, v200, s[4:5]
	v_cndmask_b32_e64 v197, v197, v201, s[4:5]
	v_pk_fma_f32 v[202:203], v[106:107], v[176:177], v[118:119]
	v_pk_fma_f32 v[142:143], v[142:143], v[110:111], v[202:203]
	v_pk_fma_f32 v[142:143], v[114:115], v[196:197], v[142:143]
	ds_read_b64 v[176:177], v244 offset:768
	ds_read_b64 v[196:197], v243 offset:784
	ds_read_b64 v[200:201], v238 offset:2056
	ds_write_b64 v243, v[162:163]
	ds_write_b64 v243, v[154:155] offset:256
	ds_write_b64 v243, v[146:147] offset:512
	ds_write_b64 v243, v[138:139] offset:768
	s_waitcnt lgkmcnt(11)
	v_cndmask_b32_e64 v170, v170, v198, s[6:7]
	v_cndmask_b32_e64 v171, v171, v199, s[6:7]
	v_pk_fma_f32 v[202:203], v[108:109], v[170:171], v[120:121]
	v_pk_fma_f32 v[168:169], v[168:169], v[112:113], v[202:203]
	v_pk_fma_f32 v[168:169], v[116:117], v[178:179], v[168:169]
	ds_read_b64 v[170:171], v244
	ds_read_b64 v[178:179], v243 offset:16
	ds_read_b64 v[198:199], v245 offset:32
	s_waitcnt lgkmcnt(12)
	v_pk_fma_f32 v[202:203], v[108:109], v[172:173], v[120:121]
	v_pk_fma_f32 v[160:161], v[160:161], v[112:113], v[202:203]
	v_pk_fma_f32 v[160:161], v[116:117], v[180:181], v[160:161]
	ds_read_b64 v[172:173], v244 offset:256
	ds_read_b64 v[180:181], v243 offset:272
	s_waitcnt lgkmcnt(12)
	v_pk_fma_f32 v[202:203], v[108:109], v[174:175], v[120:121]
	v_pk_fma_f32 v[152:153], v[152:153], v[112:113], v[202:203]
	v_pk_fma_f32 v[152:153], v[116:117], v[194:195], v[152:153]
	ds_read_b64 v[174:175], v244 offset:512
	ds_read_b64 v[194:195], v243 offset:528
	s_waitcnt lgkmcnt(11)
	v_cndmask_b32_e64 v196, v196, v200, s[4:5]
	v_cndmask_b32_e64 v197, v197, v201, s[4:5]
	v_pk_fma_f32 v[202:203], v[108:109], v[176:177], v[120:121]
	v_pk_fma_f32 v[144:145], v[144:145], v[112:113], v[202:203]
	v_pk_fma_f32 v[144:145], v[116:117], v[196:197], v[144:145]
	ds_read_b64 v[176:177], v244 offset:768
	ds_read_b64 v[196:197], v243 offset:784
	ds_read_b64 v[200:201], v238 offset:2080
	ds_write_b64 v243, v[164:165]
	ds_write_b64 v243, v[156:157] offset:256
	ds_write_b64 v243, v[148:149] offset:512
	ds_write_b64 v243, v[140:141] offset:768
	s_waitcnt lgkmcnt(11)
	v_cndmask_b32_e64 v170, v170, v198, s[6:7]
	v_cndmask_b32_e64 v171, v171, v199, s[6:7]
	v_pk_fma_f32 v[202:203], v[122:123], v[170:171], v[134:135]
	v_pk_fma_f32 v[162:163], v[162:163], v[126:127], v[202:203]
	v_pk_fma_f32 v[162:163], v[130:131], v[178:179], v[162:163]
	ds_read_b64 v[170:171], v244
	ds_read_b64 v[178:179], v243 offset:16
	ds_read_b64 v[198:199], v245 offset:40
	s_waitcnt lgkmcnt(12)
	v_pk_fma_f32 v[202:203], v[122:123], v[172:173], v[134:135]
	v_pk_fma_f32 v[154:155], v[154:155], v[126:127], v[202:203]
	v_pk_fma_f32 v[154:155], v[130:131], v[180:181], v[154:155]
	ds_read_b64 v[172:173], v244 offset:256
	ds_read_b64 v[180:181], v243 offset:272
	s_waitcnt lgkmcnt(12)
	v_pk_fma_f32 v[202:203], v[122:123], v[174:175], v[134:135]
	v_pk_fma_f32 v[146:147], v[146:147], v[126:127], v[202:203]
	v_pk_fma_f32 v[146:147], v[130:131], v[194:195], v[146:147]
	ds_read_b64 v[174:175], v244 offset:512
	ds_read_b64 v[194:195], v243 offset:528
	s_waitcnt lgkmcnt(11)
	v_cndmask_b32_e64 v196, v196, v200, s[4:5]
	v_cndmask_b32_e64 v197, v197, v201, s[4:5]
	v_pk_fma_f32 v[202:203], v[122:123], v[176:177], v[134:135]
	v_pk_fma_f32 v[138:139], v[138:139], v[126:127], v[202:203]
	v_pk_fma_f32 v[138:139], v[130:131], v[196:197], v[138:139]
	ds_read_b64 v[176:177], v244 offset:768
	ds_read_b64 v[196:197], v243 offset:784
	ds_read_b64 v[200:201], v238 offset:2088
	ds_write_b64 v243, v[102:103]
	ds_write_b64 v243, v[94:95] offset:256
	ds_write_b64 v243, v[86:87] offset:512
	ds_write_b64 v243, v[78:79] offset:768
	s_waitcnt lgkmcnt(11)
	v_cndmask_b32_e64 v170, v170, v198, s[6:7]
	v_cndmask_b32_e64 v171, v171, v199, s[6:7]
	v_pk_fma_f32 v[202:203], v[124:125], v[170:171], v[136:137]
	v_pk_fma_f32 v[164:165], v[164:165], v[128:129], v[202:203]
	v_pk_fma_f32 v[164:165], v[132:133], v[178:179], v[164:165]
	ds_read_b64 v[170:171], v244
	ds_read_b64 v[178:179], v243 offset:16
	ds_read_b64 v[198:199], v238 offset:3072
	s_waitcnt lgkmcnt(12)
	v_pk_fma_f32 v[202:203], v[124:125], v[172:173], v[136:137]
	v_pk_fma_f32 v[156:157], v[156:157], v[128:129], v[202:203]
	v_pk_fma_f32 v[156:157], v[132:133], v[180:181], v[156:157]
	ds_read_b64 v[172:173], v244 offset:256
	ds_read_b64 v[180:181], v243 offset:272
	s_waitcnt lgkmcnt(12)
	v_pk_fma_f32 v[202:203], v[124:125], v[174:175], v[136:137]
	v_pk_fma_f32 v[148:149], v[148:149], v[128:129], v[202:203]
	v_pk_fma_f32 v[148:149], v[132:133], v[194:195], v[148:149]
	ds_read_b64 v[174:175], v244 offset:512
	ds_read_b64 v[194:195], v243 offset:528
	s_waitcnt lgkmcnt(11)
;     __device__ __forceinline__ void operator()(const f32x4 (&acc)[2][2][4][2], const Unit& u, int wr, int wc, int fr, int fq) const {
;     ...
;                 for (int bj = 0; bj < 2; ++bj) { const int col = bj * 2816 + ch0 + 4;
;                     w0[bj] = *(const f32x4*)(cw + col); w1[bj] = *(const f32x4*)(cw + 5632 + col); w2[bj] = *(const f32x4*)(cw + 11264 + col); bb[bj] = *(const f32x4*)(cb + col); } }
; #pragma unroll
;             for (int ai = 0; ai < 2; ++ai) { const int blk = ai * 2 + wr;
; #pragma unroll
;                 for (int m = 0; m < 4; ++m) { const int r = 128 * ai + 64 * wr + 16 * m + fr, t = tstart + r;
;                     const bool upok = t >= 1, dnok = (t + 1) < T, store_ok = (r >= vlo) && (r < vhi) && (t < T);
;                     f32x4 res[2];
; #pragma unroll
;                     for (int bj = 0; bj < 2; ++bj) { const f32x4 cur = acc[ai][bj][m][n];
;                         f32x4 su = cur, sd = cur;
;                         if (m > 0) { if (fr == 15) su = acc[ai][bj][m > 0 ? m - 1 : 0][n]; }
;                         if (m < 3) { if (fr == 0) sd = acc[ai][bj][m < 3 ? m + 1 : 3][n]; }
;                         f32x4 up, dn;
;                         up[0] = dpp_ror1(su[0]); up[1] = dpp_ror1(su[1]); up[2] = dpp_ror1(su[2]); up[3] = dpp_ror1(su[3]);
;                         dn[0] = dpp_ror15(sd[0]); dn[1] = dpp_ror15(sd[1]); dn[2] = dpp_ror15(sd[2]); dn[3] = dpp_ror15(sd[3]);
;                         if (m == 0) { f32x4 halo = zero4; if (blk > 0) halo = *(const PG8_LAS f32x4*)(xb + (((((blk - 1) * 2 + 1) * 4 + wc) * 4 + fq) * 16 + (bj * 2 + n) * 4)); if (fr == 0) up = halo; }
;                         if (m == 3) { f32x4 halo = zero4; if (blk < 3) halo = *(const PG8_LAS f32x4*)(xb + (((((blk + 1) * 2 + 0) * 4 + wc) * 4 + fq) * 16 + (bj * 2 + n) * 4)); if (fr == 15) dn = halo; }
;                         if (edge) { if (!upok) up = zero4; if (!dnok) dn = zero4; }
;                         res[bj] = bb[bj] + w0[bj] * up + w1[bj] * cur + w2[bj] * dn; }
;                     if (store_ok) {
;                         float o[4];
; #pragma unroll
;                         for (int j = 0; j < 4; ++j) { const float gg = res[1][j]; o[j] = gg * __builtin_amdgcn_rcpf(1.f + __expf(-gg)) * res[0][j]; }
;                         u32x2 w; w.x = cvt_pk_bf16(o[0], o[1]); w.y = cvt_pk_bf16(o[2], o[3]);
	v_cndmask_b32_e64 v196, v196, v200, s[4:5]
	v_cndmask_b32_e64 v197, v197, v201, s[4:5]
	v_pk_fma_f32 v[202:203], v[124:125], v[176:177], v[136:137]
	v_pk_fma_f32 v[140:141], v[140:141], v[128:129], v[202:203]
	v_pk_fma_f32 v[140:141], v[132:133], v[196:197], v[140:141]
	ds_read_b64 v[176:177], v244 offset:768
	ds_read_b64 v[196:197], v243 offset:784
	ds_read_b64 v[200:201], v246
	v_mul_f32_e32 v208, 0xbfb8aa3b, v162
	v_mul_f32_e32 v209, 0xbfb8aa3b, v163
	v_mul_f32_e32 v210, 0xbfb8aa3b, v164
	v_mul_f32_e32 v211, 0xbfb8aa3b, v165
	v_exp_f32_e32 v208, v208
	v_exp_f32_e32 v209, v209
	v_exp_f32_e32 v210, v210
	v_exp_f32_e32 v211, v211
	v_add_f32_e32 v208, 1.0, v208
	v_add_f32_e32 v209, 1.0, v209
	v_add_f32_e32 v210, 1.0, v210
	v_add_f32_e32 v211, 1.0, v211
	v_rcp_f32_e32 v208, v208
	v_rcp_f32_e32 v209, v209
	v_rcp_f32_e32 v210, v210
	v_rcp_f32_e32 v211, v211
	v_mul_f32_e32 v162, v162, v208
	v_mul_f32_e32 v163, v163, v209
	v_mul_f32_e32 v164, v164, v210
	v_mul_f32_e32 v165, v165, v211
	v_mul_f32_e32 v162, v166, v162
	v_mul_f32_e32 v163, v167, v163
	v_mul_f32_e32 v164, v168, v164
	v_mul_f32_e32 v165, v169, v165
	v_cvt_pk_bf16_f32 v38, v162, v163
	v_cvt_pk_bf16_f32 v39, v164, v165
	ds_bpermute_b32 v38, v250, v38
	ds_bpermute_b32 v39, v250, v39
	v_mul_f32_e32 v208, 0xbfb8aa3b, v154
	v_mul_f32_e32 v209, 0xbfb8aa3b, v155
	v_mul_f32_e32 v210, 0xbfb8aa3b, v156
	v_mul_f32_e32 v211, 0xbfb8aa3b, v157
	v_exp_f32_e32 v208, v208
	v_exp_f32_e32 v209, v209
	v_exp_f32_e32 v210, v210
	v_exp_f32_e32 v211, v211
	v_add_f32_e32 v208, 1.0, v208
	v_add_f32_e32 v209, 1.0, v209
	v_add_f32_e32 v210, 1.0, v210
	v_add_f32_e32 v211, 1.0, v211
	v_rcp_f32_e32 v208, v208
	v_rcp_f32_e32 v209, v209
	v_rcp_f32_e32 v210, v210
	v_rcp_f32_e32 v211, v211
	v_mul_f32_e32 v154, v154, v208
	v_mul_f32_e32 v155, v155, v209
	v_mul_f32_e32 v156, v156, v210
	v_mul_f32_e32 v157, v157, v211
	v_mul_f32_e32 v154, v158, v154
	v_mul_f32_e32 v155, v159, v155
	v_mul_f32_e32 v156, v160, v156
	v_mul_f32_e32 v157, v161, v157
	v_cvt_pk_bf16_f32 v40, v154, v155
	v_cvt_pk_bf16_f32 v41, v156, v157
	ds_bpermute_b32 v40, v250, v40
	ds_bpermute_b32 v41, v250, v41
	v_mul_f32_e32 v208, 0xbfb8aa3b, v146
	v_mul_f32_e32 v209, 0xbfb8aa3b, v147
	v_mul_f32_e32 v210, 0xbfb8aa3b, v148
	v_mul_f32_e32 v211, 0xbfb8aa3b, v149
	v_exp_f32_e32 v208, v208
	v_exp_f32_e32 v209, v209
	v_exp_f32_e32 v210, v210
	v_exp_f32_e32 v211, v211
	v_add_f32_e32 v208, 1.0, v208
	v_add_f32_e32 v209, 1.0, v209
	v_add_f32_e32 v210, 1.0, v210
	v_add_f32_e32 v211, 1.0, v211
	v_rcp_f32_e32 v208, v208
	v_rcp_f32_e32 v209, v209
	v_rcp_f32_e32 v210, v210
	v_rcp_f32_e32 v211, v211
	v_mul_f32_e32 v146, v146, v208
	v_mul_f32_e32 v147, v147, v209
	v_mul_f32_e32 v148, v148, v210
	v_mul_f32_e32 v149, v149, v211
	v_mul_f32_e32 v146, v150, v146
	v_mul_f32_e32 v147, v151, v147
	v_mul_f32_e32 v148, v152, v148
	v_mul_f32_e32 v149, v153, v149
	v_cvt_pk_bf16_f32 v212, v146, v147
	v_cvt_pk_bf16_f32 v213, v148, v149
	ds_bpermute_b32 v212, v250, v212
	ds_bpermute_b32 v213, v250, v213
	v_mul_f32_e32 v208, 0xbfb8aa3b, v138
	v_mul_f32_e32 v209, 0xbfb8aa3b, v139
	v_mul_f32_e32 v210, 0xbfb8aa3b, v140
	v_mul_f32_e32 v211, 0xbfb8aa3b, v141
	v_exp_f32_e32 v208, v208
	v_exp_f32_e32 v209, v209
	v_exp_f32_e32 v210, v210
	v_exp_f32_e32 v211, v211
	v_add_f32_e32 v208, 1.0, v208
	v_add_f32_e32 v209, 1.0, v209
	v_add_f32_e32 v210, 1.0, v210
	v_add_f32_e32 v211, 1.0, v211
	v_rcp_f32_e32 v208, v208
	v_rcp_f32_e32 v209, v209
	v_rcp_f32_e32 v210, v210
	v_rcp_f32_e32 v211, v211
	v_mul_f32_e32 v138, v138, v208
	v_mul_f32_e32 v139, v139, v209
	v_mul_f32_e32 v140, v140, v210
	v_mul_f32_e32 v141, v141, v211
	v_mul_f32_e32 v138, v142, v138
	v_mul_f32_e32 v139, v143, v139
	v_mul_f32_e32 v140, v144, v140
	v_mul_f32_e32 v141, v145, v141
	v_cvt_pk_bf16_f32 v218, v138, v139
	v_cvt_pk_bf16_f32 v219, v140, v141
	ds_bpermute_b32 v218, v250, v218
	ds_bpermute_b32 v219, v250, v219
	global_load_dwordx4 v[138:141], v248, s[62:63] offset:16
	global_load_dwordx4 v[142:145], v248, s[66:67] offset:16
	global_load_dwordx4 v[146:149], v248, s[68:69] offset:16
	global_load_dwordx4 v[150:153], v248, s[64:65] offset:16
	global_load_dwordx4 v[154:157], v249, s[62:63] offset:16
	global_load_dwordx4 v[158:161], v249, s[66:67] offset:16
	global_load_dwordx4 v[162:165], v249, s[68:69] offset:16
	global_load_dwordx4 v[166:169], v249, s[64:65] offset:16
	ds_write_b64 v243, v[104:105]
	ds_write_b64 v243, v[96:97] offset:256
	ds_write_b64 v243, v[88:89] offset:512
	ds_write_b64 v243, v[80:81] offset:768
	s_waitcnt lgkmcnt(15)
	v_cndmask_b32_e64 v170, v170, v198, s[6:7]
	v_cndmask_b32_e64 v171, v171, v199, s[6:7]
	v_pk_fma_f32 v[202:203], v[106:107], v[170:171], v[118:119]
	v_pk_fma_f32 v[102:103], v[102:103], v[110:111], v[202:203]
	v_pk_fma_f32 v[102:103], v[114:115], v[178:179], v[102:103]
	ds_read_b64 v[170:171], v244
	ds_read_b64 v[178:179], v243 offset:16
	ds_read_b64 v[198:199], v238 offset:3080
	v_pk_fma_f32 v[202:203], v[106:107], v[172:173], v[118:119]
	v_pk_fma_f32 v[94:95], v[94:95], v[110:111], v[202:203]
	v_pk_fma_f32 v[94:95], v[114:115], v[180:181], v[94:95]
	ds_read_b64 v[172:173], v244 offset:256
	ds_read_b64 v[180:181], v243 offset:272
	v_pk_fma_f32 v[202:203], v[106:107], v[174:175], v[118:119]
	v_pk_fma_f32 v[86:87], v[86:87], v[110:111], v[202:203]
	v_pk_fma_f32 v[86:87], v[114:115], v[194:195], v[86:87]
	ds_read_b64 v[174:175], v244 offset:512
	ds_read_b64 v[194:195], v243 offset:528
	s_waitcnt lgkmcnt(15)
; #define PG8_LAS __attribute__((address_space(3)))
; __device__ __forceinline__ float dpp_ror1(float v) { return __builtin_bit_cast(float, __builtin_amdgcn_update_dpp(0, __builtin_bit_cast(int, v), 0x121, 0xf, 0xf, false)); }
; __device__ __forceinline__ float dpp_ror15(float v) { return __builtin_bit_cast(float, __builtin_amdgcn_update_dpp(0, __builtin_bit_cast(int, v), 0x12F, 0xf, 0xf, false)); }
;     __device__ __forceinline__ void operator()(const f32x4 (&acc)[2][2][4][2], const Unit& u, int wr, int wc, int fr, int fq) const {
;     ...
;                 for (int m = 0; m < 4; ++m) { const int r = 128 * ai + 64 * wr + 16 * m + fr, t = tstart + r;
;                     const bool upok = t >= 1, dnok = (t + 1) < T, store_ok = (r >= vlo) && (r < vhi) && (t < T);
;                     f32x4 res[2];
; #pragma unroll
;                     for (int bj = 0; bj < 2; ++bj) { const f32x4 cur = acc[ai][bj][m][n];
;                         f32x4 su = cur, sd = cur;
;                         if (m > 0) { if (fr == 15) su = acc[ai][bj][m > 0 ? m - 1 : 0][n]; }
;                         if (m < 3) { if (fr == 0) sd = acc[ai][bj][m < 3 ? m + 1 : 3][n]; }
;                         f32x4 up, dn;
;                         up[0] = dpp_ror1(su[0]); up[1] = dpp_ror1(su[1]); up[2] = dpp_ror1(su[2]); up[3] = dpp_ror1(su[3]);
;                         dn[0] = dpp_ror15(sd[0]); dn[1] = dpp_ror15(sd[1]); dn[2] = dpp_ror15(sd[2]); dn[3] = dpp_ror15(sd[3]);
;                         if (m == 0) { f32x4 halo = zero4; if (blk > 0) halo = *(const PG8_LAS f32x4*)(xb + (((((blk - 1) * 2 + 1) * 4 + wc) * 4 + fq) * 16 + (bj * 2 + n) * 4)); if (fr == 0) up = halo; }
;                         if (m == 3) { f32x4 halo = zero4; if (blk < 3) halo = *(const PG8_LAS f32x4*)(xb + (((((blk + 1) * 2 + 0) * 4 + wc) * 4 + fq) * 16 + (bj * 2 + n) * 4)); if (fr == 15) dn = halo; }
;                         if (edge) { if (!upok) up = zero4; if (!dnok) dn = zero4; }
;                         res[bj] = bb[bj] + w0[bj] * up + w1[bj] * cur + w2[bj] * dn; }
	v_cndmask_b32_e64 v196, v196, v200, s[4:5]
	v_cndmask_b32_e64 v197, v197, v201, s[4:5]
	v_pk_fma_f32 v[202:203], v[106:107], v[176:177], v[118:119]
	v_pk_fma_f32 v[78:79], v[78:79], v[110:111], v[202:203]
	v_pk_fma_f32 v[78:79], v[114:115], v[196:197], v[78:79]
	ds_read_b64 v[176:177], v244 offset:768
	ds_read_b64 v[196:197], v243 offset:784
	ds_read_b64 v[200:201], v246 offset:8
	ds_write_b64 v243, v[98:99]
	ds_write_b64 v243, v[90:91] offset:256
	ds_write_b64 v243, v[82:83] offset:512
	ds_write_b64 v243, v[74:75] offset:768
	s_waitcnt lgkmcnt(11)
	v_cndmask_b32_e64 v170, v170, v198, s[6:7]
	v_cndmask_b32_e64 v171, v171, v199, s[6:7]
	v_pk_fma_f32 v[202:203], v[108:109], v[170:171], v[120:121]
	v_pk_fma_f32 v[104:105], v[104:105], v[112:113], v[202:203]
	v_pk_fma_f32 v[104:105], v[116:117], v[178:179], v[104:105]
	ds_read_b64 v[170:171], v244
	ds_read_b64 v[178:179], v243 offset:16
	ds_read_b64 v[198:199], v238 offset:3104
	s_waitcnt lgkmcnt(12)
	v_pk_fma_f32 v[202:203], v[108:109], v[172:173], v[120:121]
	v_pk_fma_f32 v[96:97], v[96:97], v[112:113], v[202:203]
	v_pk_fma_f32 v[96:97], v[116:117], v[180:181], v[96:97]
	ds_read_b64 v[172:173], v244 offset:256
	ds_read_b64 v[180:181], v243 offset:272
	s_waitcnt lgkmcnt(12)
	v_pk_fma_f32 v[202:203], v[108:109], v[174:175], v[120:121]
	v_pk_fma_f32 v[88:89], v[88:89], v[112:113], v[202:203]
	v_pk_fma_f32 v[88:89], v[116:117], v[194:195], v[88:89]
	ds_read_b64 v[174:175], v244 offset:512
	ds_read_b64 v[194:195], v243 offset:528
	s_waitcnt lgkmcnt(11)
	v_cndmask_b32_e64 v196, v196, v200, s[4:5]
	v_cndmask_b32_e64 v197, v197, v201, s[4:5]
	v_pk_fma_f32 v[202:203], v[108:109], v[176:177], v[120:121]
	v_pk_fma_f32 v[80:81], v[80:81], v[112:113], v[202:203]
	v_pk_fma_f32 v[80:81], v[116:117], v[196:197], v[80:81]
	ds_read_b64 v[176:177], v244 offset:768
	ds_read_b64 v[196:197], v243 offset:784
	ds_read_b64 v[200:201], v246 offset:32
	ds_write_b64 v243, v[100:101]
	ds_write_b64 v243, v[92:93] offset:256
	ds_write_b64 v243, v[84:85] offset:512
	ds_write_b64 v243, v[76:77] offset:768
	s_waitcnt lgkmcnt(11)
	v_cndmask_b32_e64 v170, v170, v198, s[6:7]
	v_cndmask_b32_e64 v171, v171, v199, s[6:7]
	v_pk_fma_f32 v[202:203], v[122:123], v[170:171], v[134:135]
	v_pk_fma_f32 v[98:99], v[98:99], v[126:127], v[202:203]
	v_pk_fma_f32 v[98:99], v[130:131], v[178:179], v[98:99]
	ds_read_b64 v[170:171], v244
	ds_read_b64 v[178:179], v243 offset:16
	ds_read_b64 v[198:199], v238 offset:3112
	s_waitcnt lgkmcnt(12)
	v_pk_fma_f32 v[202:203], v[122:123], v[172:173], v[134:135]
	v_pk_fma_f32 v[90:91], v[90:91], v[126:127], v[202:203]
	v_pk_fma_f32 v[90:91], v[130:131], v[180:181], v[90:91]
	ds_read_b64 v[172:173], v244 offset:256
	ds_read_b64 v[180:181], v243 offset:272
	s_waitcnt lgkmcnt(12)
	v_pk_fma_f32 v[202:203], v[122:123], v[174:175], v[134:135]
	v_pk_fma_f32 v[82:83], v[82:83], v[126:127], v[202:203]
	v_pk_fma_f32 v[82:83], v[130:131], v[194:195], v[82:83]
	ds_read_b64 v[174:175], v244 offset:512
	ds_read_b64 v[194:195], v243 offset:528
	s_waitcnt lgkmcnt(11)
	v_cndmask_b32_e64 v196, v196, v200, s[4:5]
	v_cndmask_b32_e64 v197, v197, v201, s[4:5]
	v_pk_fma_f32 v[202:203], v[122:123], v[176:177], v[134:135]
	v_pk_fma_f32 v[74:75], v[74:75], v[126:127], v[202:203]
	v_pk_fma_f32 v[74:75], v[130:131], v[196:197], v[74:75]
	ds_read_b64 v[176:177], v244 offset:768
	ds_read_b64 v[196:197], v243 offset:784
	ds_read_b64 v[200:201], v246 offset:40
	ds_write_b64 v243, v[70:71]
	ds_write_b64 v243, v[62:63] offset:256
	ds_write_b64 v243, v[54:55] offset:512
	ds_write_b64 v243, v[46:47] offset:768
	s_waitcnt lgkmcnt(11)
	v_cndmask_b32_e64 v170, v170, v198, s[6:7]
	v_cndmask_b32_e64 v171, v171, v199, s[6:7]
	v_pk_fma_f32 v[202:203], v[124:125], v[170:171], v[136:137]
	v_pk_fma_f32 v[100:101], v[100:101], v[128:129], v[202:203]
	v_pk_fma_f32 v[100:101], v[132:133], v[178:179], v[100:101]
	ds_read_b64 v[170:171], v244
	ds_read_b64 v[178:179], v243 offset:16
	ds_read_b64 v[198:199], v245 offset:16
	s_waitcnt lgkmcnt(12)
	v_pk_fma_f32 v[202:203], v[124:125], v[172:173], v[136:137]
	v_pk_fma_f32 v[92:93], v[92:93], v[128:129], v[202:203]
	v_pk_fma_f32 v[92:93], v[132:133], v[180:181], v[92:93]
	ds_read_b64 v[172:173], v244 offset:256
	ds_read_b64 v[180:181], v243 offset:272
	s_waitcnt lgkmcnt(12)
	v_pk_fma_f32 v[202:203], v[124:125], v[174:175], v[136:137]
	v_pk_fma_f32 v[84:85], v[84:85], v[128:129], v[202:203]
	v_pk_fma_f32 v[84:85], v[132:133], v[194:195], v[84:85]
	ds_read_b64 v[174:175], v244 offset:512
	ds_read_b64 v[194:195], v243 offset:528
	s_waitcnt lgkmcnt(11)
; __device__ __forceinline__ unsigned cvt_pk_bf16(float lo, float hi) { unsigned r; asm volatile("v_cvt_pk_bf16_f32 %0, %1, %2" : "=v"(r) : "v"(lo), "v"(hi)); return r; }
;     __device__ __forceinline__ void operator()(const f32x4 (&acc)[2][2][4][2], const Unit& u, int wr, int wc, int fr, int fq) const {
;     ...
;                 for (int bj = 0; bj < 2; ++bj) { const int col = bj * 2816 + ch0 + 4;
;                     w0[bj] = *(const f32x4*)(cw + col); w1[bj] = *(const f32x4*)(cw + 5632 + col); w2[bj] = *(const f32x4*)(cw + 11264 + col); bb[bj] = *(const f32x4*)(cb + col); } }
;     ...
;                         res[bj] = bb[bj] + w0[bj] * up + w1[bj] * cur + w2[bj] * dn; }
;                     if (store_ok) {
;                         float o[4];
; #pragma unroll
;                         for (int j = 0; j < 4; ++j) { const float gg = res[1][j]; o[j] = gg * __builtin_amdgcn_rcpf(1.f + __expf(-gg)) * res[0][j]; }
;                         u32x2 w; w.x = cvt_pk_bf16(o[0], o[1]); w.y = cvt_pk_bf16(o[2], o[3]);
;                         *(u32x2*)(ACT + (size_t)(seqrow + t) * 2816 + ch0 + 4 * n) = w; } } }
	v_cndmask_b32_e64 v196, v196, v200, s[4:5]
	v_cndmask_b32_e64 v197, v197, v201, s[4:5]
	v_pk_fma_f32 v[202:203], v[124:125], v[176:177], v[136:137]
	v_pk_fma_f32 v[76:77], v[76:77], v[128:129], v[202:203]
	v_pk_fma_f32 v[76:77], v[132:133], v[196:197], v[76:77]
	ds_read_b64 v[176:177], v244 offset:768
	ds_read_b64 v[196:197], v243 offset:784
	ds_read_b64 v[200:201], v238 offset:2064
	v_mul_f32_e32 v208, 0xbfb8aa3b, v98
	v_mul_f32_e32 v209, 0xbfb8aa3b, v99
	v_mul_f32_e32 v210, 0xbfb8aa3b, v100
	v_mul_f32_e32 v211, 0xbfb8aa3b, v101
	v_exp_f32_e32 v208, v208
	v_exp_f32_e32 v209, v209
	v_exp_f32_e32 v210, v210
	v_exp_f32_e32 v211, v211
	v_add_f32_e32 v208, 1.0, v208
	v_add_f32_e32 v209, 1.0, v209
	v_add_f32_e32 v210, 1.0, v210
	v_add_f32_e32 v211, 1.0, v211
	v_rcp_f32_e32 v208, v208
	v_rcp_f32_e32 v209, v209
	v_rcp_f32_e32 v210, v210
	v_rcp_f32_e32 v211, v211
	v_mul_f32_e32 v98, v98, v208
	v_mul_f32_e32 v99, v99, v209
	v_mul_f32_e32 v100, v100, v210
	v_mul_f32_e32 v101, v101, v211
	v_mul_f32_e32 v98, v102, v98
	v_mul_f32_e32 v99, v103, v99
	v_mul_f32_e32 v100, v104, v100
	v_mul_f32_e32 v101, v105, v101
	v_cvt_pk_bf16_f32 v98, v98, v99
	v_cvt_pk_bf16_f32 v99, v100, v101
	ds_bpermute_b32 v98, v250, v98
	ds_bpermute_b32 v99, v250, v99
	v_mul_f32_e32 v208, 0xbfb8aa3b, v90
	v_mul_f32_e32 v209, 0xbfb8aa3b, v91
	v_mul_f32_e32 v210, 0xbfb8aa3b, v92
	v_mul_f32_e32 v211, 0xbfb8aa3b, v93
	v_exp_f32_e32 v208, v208
	v_exp_f32_e32 v209, v209
	v_exp_f32_e32 v210, v210
	v_exp_f32_e32 v211, v211
	v_add_f32_e32 v208, 1.0, v208
	v_add_f32_e32 v209, 1.0, v209
	v_add_f32_e32 v210, 1.0, v210
	v_add_f32_e32 v211, 1.0, v211
	v_rcp_f32_e32 v208, v208
	v_rcp_f32_e32 v209, v209
	v_rcp_f32_e32 v210, v210
	v_rcp_f32_e32 v211, v211
	v_mul_f32_e32 v90, v90, v208
	v_mul_f32_e32 v91, v91, v209
	v_mul_f32_e32 v92, v92, v210
	v_mul_f32_e32 v93, v93, v211
	v_mul_f32_e32 v90, v94, v90
	v_mul_f32_e32 v91, v95, v91
	v_mul_f32_e32 v92, v96, v92
	v_mul_f32_e32 v93, v97, v93
	v_cvt_pk_bf16_f32 v90, v90, v91
	v_cvt_pk_bf16_f32 v91, v92, v93
	ds_bpermute_b32 v90, v250, v90
	ds_bpermute_b32 v91, v250, v91
	v_mul_f32_e32 v208, 0xbfb8aa3b, v82
	v_mul_f32_e32 v209, 0xbfb8aa3b, v83
	v_mul_f32_e32 v210, 0xbfb8aa3b, v84
	v_mul_f32_e32 v211, 0xbfb8aa3b, v85
	v_exp_f32_e32 v208, v208
	v_exp_f32_e32 v209, v209
	v_exp_f32_e32 v210, v210
	v_exp_f32_e32 v211, v211
	v_add_f32_e32 v208, 1.0, v208
	v_add_f32_e32 v209, 1.0, v209
	v_add_f32_e32 v210, 1.0, v210
	v_add_f32_e32 v211, 1.0, v211
	v_rcp_f32_e32 v208, v208
	v_rcp_f32_e32 v209, v209
	v_rcp_f32_e32 v210, v210
	v_rcp_f32_e32 v211, v211
	v_mul_f32_e32 v82, v82, v208
	v_mul_f32_e32 v83, v83, v209
	v_mul_f32_e32 v84, v84, v210
	v_mul_f32_e32 v85, v85, v211
	v_mul_f32_e32 v82, v86, v82
	v_mul_f32_e32 v83, v87, v83
	v_mul_f32_e32 v84, v88, v84
	v_mul_f32_e32 v85, v89, v85
	v_cvt_pk_bf16_f32 v82, v82, v83
	v_cvt_pk_bf16_f32 v83, v84, v85
	ds_bpermute_b32 v82, v250, v82
	ds_bpermute_b32 v83, v250, v83
	v_mul_f32_e32 v208, 0xbfb8aa3b, v74
	v_mul_f32_e32 v209, 0xbfb8aa3b, v75
	v_mul_f32_e32 v210, 0xbfb8aa3b, v76
	v_mul_f32_e32 v211, 0xbfb8aa3b, v77
	v_exp_f32_e32 v208, v208
	v_exp_f32_e32 v209, v209
	v_exp_f32_e32 v210, v210
	v_exp_f32_e32 v211, v211
	v_add_f32_e32 v208, 1.0, v208
	v_add_f32_e32 v209, 1.0, v209
	v_add_f32_e32 v210, 1.0, v210
	v_add_f32_e32 v211, 1.0, v211
	v_rcp_f32_e32 v208, v208
	v_rcp_f32_e32 v209, v209
	v_rcp_f32_e32 v210, v210
	v_rcp_f32_e32 v211, v211
	v_mul_f32_e32 v74, v74, v208
	v_mul_f32_e32 v75, v75, v209
	v_mul_f32_e32 v76, v76, v210
	v_mul_f32_e32 v77, v77, v211
	v_mul_f32_e32 v74, v78, v74
	v_mul_f32_e32 v75, v79, v75
	v_mul_f32_e32 v76, v80, v76
	v_mul_f32_e32 v77, v81, v77
	v_cvt_pk_bf16_f32 v74, v74, v75
	v_cvt_pk_bf16_f32 v75, v76, v77
	ds_bpermute_b32 v74, v250, v74
	ds_bpermute_b32 v75, v250, v75
	v_mov_b32_e32 v102, v38
	v_mov_b32_e32 v103, v39
	v_mov_b32_e32 v94, v40
	v_mov_b32_e32 v95, v41
	v_mov_b32_e32 v86, v212
	v_mov_b32_e32 v87, v213
	v_mov_b32_e32 v78, v218
	v_mov_b32_e32 v79, v219
	s_waitcnt vmcnt(0)
	ds_write_b64 v243, v[72:73]
	ds_write_b64 v243, v[64:65] offset:256
	ds_write_b64 v243, v[56:57] offset:512
	ds_write_b64 v243, v[48:49] offset:768
	s_waitcnt lgkmcnt(15)
	v_cndmask_b32_e64 v170, v170, v198, s[6:7]
	v_cndmask_b32_e64 v171, v171, v199, s[6:7]
	v_pk_fma_f32 v[202:203], v[138:139], v[170:171], v[150:151]
	v_pk_fma_f32 v[70:71], v[70:71], v[142:143], v[202:203]
	v_pk_fma_f32 v[70:71], v[146:147], v[178:179], v[70:71]
	ds_read_b64 v[170:171], v244
	ds_read_b64 v[178:179], v243 offset:16
	ds_read_b64 v[198:199], v245 offset:24
	v_pk_fma_f32 v[202:203], v[138:139], v[172:173], v[150:151]
	v_pk_fma_f32 v[62:63], v[62:63], v[142:143], v[202:203]
	v_pk_fma_f32 v[62:63], v[146:147], v[180:181], v[62:63]
	ds_read_b64 v[172:173], v244 offset:256
	ds_read_b64 v[180:181], v243 offset:272
	v_pk_fma_f32 v[202:203], v[138:139], v[174:175], v[150:151]
	v_pk_fma_f32 v[54:55], v[54:55], v[142:143], v[202:203]
	v_pk_fma_f32 v[54:55], v[146:147], v[194:195], v[54:55]
	ds_read_b64 v[174:175], v244 offset:512
	ds_read_b64 v[194:195], v243 offset:528
	s_waitcnt lgkmcnt(15)
	v_cndmask_b32_e64 v196, v196, v200, s[4:5]
	v_cndmask_b32_e64 v197, v197, v201, s[4:5]
	v_pk_fma_f32 v[202:203], v[138:139], v[176:177], v[150:151]
	v_pk_fma_f32 v[46:47], v[46:47], v[142:143], v[202:203]
	v_pk_fma_f32 v[46:47], v[146:147], v[196:197], v[46:47]
	ds_read_b64 v[176:177], v244 offset:768
	ds_read_b64 v[196:197], v243 offset:784
	ds_read_b64 v[200:201], v238 offset:2072
	ds_write_b64 v243, v[66:67]
	ds_write_b64 v243, v[58:59] offset:256
	ds_write_b64 v243, v[50:51] offset:512
	ds_write_b64 v243, v[42:43] offset:768
	s_waitcnt lgkmcnt(11)
; #define PG8_LAS __attribute__((address_space(3)))
; __device__ __forceinline__ unsigned cvt_pk_bf16(float lo, float hi) { unsigned r; asm volatile("v_cvt_pk_bf16_f32 %0, %1, %2" : "=v"(r) : "v"(lo), "v"(hi)); return r; }
;     __device__ __forceinline__ void operator()(const f32x4 (&acc)[2][2][4][2], const Unit& u, int wr, int wc, int fr, int fq) const {
;     ...
;                 for (int m = 0; m < 4; ++m) { const int r = 128 * ai + 64 * wr + 16 * m + fr, t = tstart + r;
;                     const bool upok = t >= 1, dnok = (t + 1) < T, store_ok = (r >= vlo) && (r < vhi) && (t < T);
;                     f32x4 res[2];
; #pragma unroll
;                     for (int bj = 0; bj < 2; ++bj) { const f32x4 cur = acc[ai][bj][m][n];
;                         f32x4 su = cur, sd = cur;
;                         if (m > 0) { if (fr == 15) su = acc[ai][bj][m > 0 ? m - 1 : 0][n]; }
;                         if (m < 3) { if (fr == 0) sd = acc[ai][bj][m < 3 ? m + 1 : 3][n]; }
;                         f32x4 up, dn;
;                         up[0] = dpp_ror1(su[0]); up[1] = dpp_ror1(su[1]); up[2] = dpp_ror1(su[2]); up[3] = dpp_ror1(su[3]);
;                         dn[0] = dpp_ror15(sd[0]); dn[1] = dpp_ror15(sd[1]); dn[2] = dpp_ror15(sd[2]); dn[3] = dpp_ror15(sd[3]);
;                         if (m == 0) { f32x4 halo = zero4; if (blk > 0) halo = *(const PG8_LAS f32x4*)(xb + (((((blk - 1) * 2 + 1) * 4 + wc) * 4 + fq) * 16 + (bj * 2 + n) * 4)); if (fr == 0) up = halo; }
;                         if (m == 3) { f32x4 halo = zero4; if (blk < 3) halo = *(const PG8_LAS f32x4*)(xb + (((((blk + 1) * 2 + 0) * 4 + wc) * 4 + fq) * 16 + (bj * 2 + n) * 4)); if (fr == 15) dn = halo; }
;                         if (edge) { if (!upok) up = zero4; if (!dnok) dn = zero4; }
;                         res[bj] = bb[bj] + w0[bj] * up + w1[bj] * cur + w2[bj] * dn; }
;                     if (store_ok) {
;                         float o[4];
; #pragma unroll
;                         for (int j = 0; j < 4; ++j) { const float gg = res[1][j]; o[j] = gg * __builtin_amdgcn_rcpf(1.f + __expf(-gg)) * res[0][j]; }
;                         u32x2 w; w.x = cvt_pk_bf16(o[0], o[1]); w.y = cvt_pk_bf16(o[2], o[3]);
;                         *(u32x2*)(ACT + (size_t)(seqrow + t) * 2816 + ch0 + 4 * n) = w; } } }
	v_cndmask_b32_e64 v170, v170, v198, s[6:7]
	v_cndmask_b32_e64 v171, v171, v199, s[6:7]
	v_pk_fma_f32 v[202:203], v[140:141], v[170:171], v[152:153]
	v_pk_fma_f32 v[72:73], v[72:73], v[144:145], v[202:203]
	v_pk_fma_f32 v[72:73], v[148:149], v[178:179], v[72:73]
	ds_read_b64 v[170:171], v244
	ds_read_b64 v[178:179], v243 offset:16
	ds_read_b64 v[198:199], v245 offset:48
	s_waitcnt lgkmcnt(12)
	v_pk_fma_f32 v[202:203], v[140:141], v[172:173], v[152:153]
	v_pk_fma_f32 v[64:65], v[64:65], v[144:145], v[202:203]
	v_pk_fma_f32 v[64:65], v[148:149], v[180:181], v[64:65]
	ds_read_b64 v[172:173], v244 offset:256
	ds_read_b64 v[180:181], v243 offset:272
	s_waitcnt lgkmcnt(12)
	v_pk_fma_f32 v[202:203], v[140:141], v[174:175], v[152:153]
	v_pk_fma_f32 v[56:57], v[56:57], v[144:145], v[202:203]
	v_pk_fma_f32 v[56:57], v[148:149], v[194:195], v[56:57]
	ds_read_b64 v[174:175], v244 offset:512
	ds_read_b64 v[194:195], v243 offset:528
	s_waitcnt lgkmcnt(11)
	v_cndmask_b32_e64 v196, v196, v200, s[4:5]
	v_cndmask_b32_e64 v197, v197, v201, s[4:5]
	v_pk_fma_f32 v[202:203], v[140:141], v[176:177], v[152:153]
	v_pk_fma_f32 v[48:49], v[48:49], v[144:145], v[202:203]
	v_pk_fma_f32 v[48:49], v[148:149], v[196:197], v[48:49]
	ds_read_b64 v[176:177], v244 offset:768
	ds_read_b64 v[196:197], v243 offset:784
	ds_read_b64 v[200:201], v238 offset:2096
	ds_write_b64 v243, v[68:69]
	ds_write_b64 v243, v[60:61] offset:256
	ds_write_b64 v243, v[52:53] offset:512
	ds_write_b64 v243, v[44:45] offset:768
	s_waitcnt lgkmcnt(11)
	v_cndmask_b32_e64 v170, v170, v198, s[6:7]
	v_cndmask_b32_e64 v171, v171, v199, s[6:7]
	v_pk_fma_f32 v[202:203], v[154:155], v[170:171], v[166:167]
	v_pk_fma_f32 v[66:67], v[66:67], v[158:159], v[202:203]
	v_pk_fma_f32 v[66:67], v[162:163], v[178:179], v[66:67]
	ds_read_b64 v[170:171], v244
	ds_read_b64 v[178:179], v243 offset:16
	ds_read_b64 v[198:199], v245 offset:56
	s_waitcnt lgkmcnt(12)
	v_pk_fma_f32 v[202:203], v[154:155], v[172:173], v[166:167]
	v_pk_fma_f32 v[58:59], v[58:59], v[158:159], v[202:203]
	v_pk_fma_f32 v[58:59], v[162:163], v[180:181], v[58:59]
	ds_read_b64 v[172:173], v244 offset:256
	ds_read_b64 v[180:181], v243 offset:272
	s_waitcnt lgkmcnt(12)
	v_pk_fma_f32 v[202:203], v[154:155], v[174:175], v[166:167]
	v_pk_fma_f32 v[50:51], v[50:51], v[158:159], v[202:203]
	v_pk_fma_f32 v[50:51], v[162:163], v[194:195], v[50:51]
	ds_read_b64 v[174:175], v244 offset:512
	ds_read_b64 v[194:195], v243 offset:528
	s_waitcnt lgkmcnt(11)
	v_cndmask_b32_e64 v196, v196, v200, s[4:5]
	v_cndmask_b32_e64 v197, v197, v201, s[4:5]
	v_pk_fma_f32 v[202:203], v[154:155], v[176:177], v[166:167]
	v_pk_fma_f32 v[42:43], v[42:43], v[158:159], v[202:203]
	v_pk_fma_f32 v[42:43], v[162:163], v[196:197], v[42:43]
	ds_read_b64 v[176:177], v244 offset:768
	ds_read_b64 v[196:197], v243 offset:784
	ds_read_b64 v[200:201], v238 offset:2104
	ds_write_b64 v243, v[30:31]
	ds_write_b64 v243, v[22:23] offset:256
	ds_write_b64 v243, v[14:15] offset:512
	ds_write_b64 v243, v[6:7] offset:768
	s_waitcnt lgkmcnt(11)
	v_cndmask_b32_e64 v170, v170, v198, s[6:7]
	v_cndmask_b32_e64 v171, v171, v199, s[6:7]
	v_pk_fma_f32 v[202:203], v[156:157], v[170:171], v[168:169]
	v_pk_fma_f32 v[68:69], v[68:69], v[160:161], v[202:203]
	v_pk_fma_f32 v[68:69], v[164:165], v[178:179], v[68:69]
	ds_read_b64 v[170:171], v244
	ds_read_b64 v[178:179], v243 offset:16
	ds_read_b64 v[198:199], v238 offset:3088
	s_waitcnt lgkmcnt(12)
	v_pk_fma_f32 v[202:203], v[156:157], v[172:173], v[168:169]
	v_pk_fma_f32 v[60:61], v[60:61], v[160:161], v[202:203]
	v_pk_fma_f32 v[60:61], v[164:165], v[180:181], v[60:61]
	ds_read_b64 v[172:173], v244 offset:256
	ds_read_b64 v[180:181], v243 offset:272
	s_waitcnt lgkmcnt(12)
	v_pk_fma_f32 v[202:203], v[156:157], v[174:175], v[168:169]
	v_pk_fma_f32 v[52:53], v[52:53], v[160:161], v[202:203]
	v_pk_fma_f32 v[52:53], v[164:165], v[194:195], v[52:53]
	ds_read_b64 v[174:175], v244 offset:512
	ds_read_b64 v[194:195], v243 offset:528
	s_waitcnt lgkmcnt(11)
	v_cndmask_b32_e64 v196, v196, v200, s[4:5]
	v_cndmask_b32_e64 v197, v197, v201, s[4:5]
	v_pk_fma_f32 v[202:203], v[156:157], v[176:177], v[168:169]
	v_pk_fma_f32 v[44:45], v[44:45], v[160:161], v[202:203]
	v_pk_fma_f32 v[44:45], v[164:165], v[196:197], v[44:45]
	ds_read_b64 v[176:177], v244 offset:768
	ds_read_b64 v[196:197], v243 offset:784
	ds_read_b64 v[200:201], v246 offset:16
	v_mul_f32_e32 v208, 0xbfb8aa3b, v66
	v_mul_f32_e32 v209, 0xbfb8aa3b, v67
	v_mul_f32_e32 v210, 0xbfb8aa3b, v68
	v_mul_f32_e32 v211, 0xbfb8aa3b, v69
	v_exp_f32_e32 v208, v208
	v_exp_f32_e32 v209, v209
	v_exp_f32_e32 v210, v210
	v_exp_f32_e32 v211, v211
	v_add_f32_e32 v208, 1.0, v208
	v_add_f32_e32 v209, 1.0, v209
	v_add_f32_e32 v210, 1.0, v210
	v_add_f32_e32 v211, 1.0, v211
	v_rcp_f32_e32 v208, v208
	v_rcp_f32_e32 v209, v209
	v_rcp_f32_e32 v210, v210
	v_rcp_f32_e32 v211, v211
	v_mul_f32_e32 v66, v66, v208
	v_mul_f32_e32 v67, v67, v209
	v_mul_f32_e32 v68, v68, v210
	v_mul_f32_e32 v69, v69, v211
	v_mul_f32_e32 v66, v70, v66
	v_mul_f32_e32 v67, v71, v67
	v_mul_f32_e32 v68, v72, v68
	v_mul_f32_e32 v69, v73, v69
	v_cvt_pk_bf16_f32 v66, v66, v67
	v_cvt_pk_bf16_f32 v67, v68, v69
	ds_bpermute_b32 v104, v250, v66
	ds_bpermute_b32 v105, v250, v67
	v_mul_f32_e32 v208, 0xbfb8aa3b, v58
	v_mul_f32_e32 v209, 0xbfb8aa3b, v59
	v_mul_f32_e32 v210, 0xbfb8aa3b, v60
	v_mul_f32_e32 v211, 0xbfb8aa3b, v61
	v_exp_f32_e32 v208, v208
	v_exp_f32_e32 v209, v209
	v_exp_f32_e32 v210, v210
	v_exp_f32_e32 v211, v211
	v_add_f32_e32 v208, 1.0, v208
	v_add_f32_e32 v209, 1.0, v209
	v_add_f32_e32 v210, 1.0, v210
	v_add_f32_e32 v211, 1.0, v211
	v_rcp_f32_e32 v208, v208
	v_rcp_f32_e32 v209, v209
; __device__ __forceinline__ unsigned cvt_pk_bf16(float lo, float hi) { unsigned r; asm volatile("v_cvt_pk_bf16_f32 %0, %1, %2" : "=v"(r) : "v"(lo), "v"(hi)); return r; }
;     __device__ __forceinline__ void operator()(const f32x4 (&acc)[2][2][4][2], const Unit& u, int wr, int wc, int fr, int fq) const {
;     ...
;                         res[bj] = bb[bj] + w0[bj] * up + w1[bj] * cur + w2[bj] * dn; }
;                     if (store_ok) {
;                         float o[4];
; #pragma unroll
;                         for (int j = 0; j < 4; ++j) { const float gg = res[1][j]; o[j] = gg * __builtin_amdgcn_rcpf(1.f + __expf(-gg)) * res[0][j]; }
;                         u32x2 w; w.x = cvt_pk_bf16(o[0], o[1]); w.y = cvt_pk_bf16(o[2], o[3]);
;                         *(u32x2*)(ACT + (size_t)(seqrow + t) * 2816 + ch0 + 4 * n) = w; } } }
	v_rcp_f32_e32 v210, v210
	v_rcp_f32_e32 v211, v211
	v_mul_f32_e32 v58, v58, v208
	v_mul_f32_e32 v59, v59, v209
	v_mul_f32_e32 v60, v60, v210
	v_mul_f32_e32 v61, v61, v211
	v_mul_f32_e32 v58, v62, v58
	v_mul_f32_e32 v59, v63, v59
	v_mul_f32_e32 v60, v64, v60
	v_mul_f32_e32 v61, v65, v61
	v_cvt_pk_bf16_f32 v58, v58, v59
	v_cvt_pk_bf16_f32 v59, v60, v61
	ds_bpermute_b32 v96, v250, v58
	ds_bpermute_b32 v97, v250, v59
	v_mul_f32_e32 v208, 0xbfb8aa3b, v50
	v_mul_f32_e32 v209, 0xbfb8aa3b, v51
	v_mul_f32_e32 v210, 0xbfb8aa3b, v52
	v_mul_f32_e32 v211, 0xbfb8aa3b, v53
	v_exp_f32_e32 v208, v208
	v_exp_f32_e32 v209, v209
	v_exp_f32_e32 v210, v210
	v_exp_f32_e32 v211, v211
	v_add_f32_e32 v208, 1.0, v208
	v_add_f32_e32 v209, 1.0, v209
	v_add_f32_e32 v210, 1.0, v210
	v_add_f32_e32 v211, 1.0, v211
	v_rcp_f32_e32 v208, v208
	v_rcp_f32_e32 v209, v209
	v_rcp_f32_e32 v210, v210
	v_rcp_f32_e32 v211, v211
	v_mul_f32_e32 v50, v50, v208
	v_mul_f32_e32 v51, v51, v209
	v_mul_f32_e32 v52, v52, v210
	v_mul_f32_e32 v53, v53, v211
	v_mul_f32_e32 v50, v54, v50
	v_mul_f32_e32 v51, v55, v51
	v_mul_f32_e32 v52, v56, v52
	v_mul_f32_e32 v53, v57, v53
	v_cvt_pk_bf16_f32 v50, v50, v51
	v_cvt_pk_bf16_f32 v51, v52, v53
	ds_bpermute_b32 v88, v250, v50
	ds_bpermute_b32 v89, v250, v51
	v_mul_f32_e32 v208, 0xbfb8aa3b, v42
	v_mul_f32_e32 v209, 0xbfb8aa3b, v43
	v_mul_f32_e32 v210, 0xbfb8aa3b, v44
	v_mul_f32_e32 v211, 0xbfb8aa3b, v45
	v_exp_f32_e32 v208, v208
	v_exp_f32_e32 v209, v209
	v_exp_f32_e32 v210, v210
	v_exp_f32_e32 v211, v211
	v_add_f32_e32 v208, 1.0, v208
	v_add_f32_e32 v209, 1.0, v209
	v_add_f32_e32 v210, 1.0, v210
	v_add_f32_e32 v211, 1.0, v211
	v_rcp_f32_e32 v208, v208
	v_rcp_f32_e32 v209, v209
	v_rcp_f32_e32 v210, v210
	v_rcp_f32_e32 v211, v211
	v_mul_f32_e32 v42, v42, v208
	v_mul_f32_e32 v43, v43, v209
	v_mul_f32_e32 v44, v44, v210
	v_mul_f32_e32 v45, v45, v211
	v_mul_f32_e32 v42, v46, v42
	v_mul_f32_e32 v43, v47, v43
	v_mul_f32_e32 v44, v48, v44
	v_mul_f32_e32 v45, v49, v45
	v_cvt_pk_bf16_f32 v42, v42, v43
	v_cvt_pk_bf16_f32 v43, v44, v45
	ds_bpermute_b32 v80, v250, v42
	ds_bpermute_b32 v81, v250, v43
	s_waitcnt lgkmcnt(6)
	v_add_u32_e32 v221, 0x0, v247
	s_and_saveexec_b64 s[30:31], s[12:13]
	global_store_dwordx4 v221, v[102:105], s[10:11]
	s_mov_b64 exec, s[30:31]
	s_waitcnt lgkmcnt(4)
	v_add_u32_e32 v251, 0x16000, v247
	s_and_saveexec_b64 s[30:31], s[14:15]
	global_store_dwordx4 v251, v[94:97], s[10:11]
	s_mov_b64 exec, s[30:31]
	s_waitcnt lgkmcnt(2)
	v_add_u32_e32 v221, 0x2c000, v247
	s_and_saveexec_b64 s[30:31], s[16:17]
	global_store_dwordx4 v221, v[86:89], s[10:11]
	s_mov_b64 exec, s[30:31]
	s_waitcnt lgkmcnt(0)
	v_add_u32_e32 v251, 0x42000, v247
	s_and_saveexec_b64 s[30:31], s[18:19]
	global_store_dwordx4 v251, v[78:81], s[10:11]
	s_mov_b64 exec, s[30:31]
	ds_write_b64 v243, v[32:33]
	ds_write_b64 v243, v[24:25] offset:256
	ds_write_b64 v243, v[16:17] offset:512
	ds_write_b64 v243, v[8:9] offset:768
	v_cndmask_b32_e64 v170, v170, v198, s[6:7]
	v_cndmask_b32_e64 v171, v171, v199, s[6:7]
	v_pk_fma_f32 v[202:203], v[138:139], v[170:171], v[150:151]
	v_pk_fma_f32 v[30:31], v[30:31], v[142:143], v[202:203]
	v_pk_fma_f32 v[30:31], v[146:147], v[178:179], v[30:31]
	ds_read_b64 v[170:171], v244
	ds_read_b64 v[178:179], v243 offset:16
	ds_read_b64 v[198:199], v238 offset:3096
	v_pk_fma_f32 v[202:203], v[138:139], v[172:173], v[150:151]
	v_pk_fma_f32 v[22:23], v[22:23], v[142:143], v[202:203]
	v_pk_fma_f32 v[22:23], v[146:147], v[180:181], v[22:23]
	ds_read_b64 v[172:173], v244 offset:256
	ds_read_b64 v[180:181], v243 offset:272
	v_pk_fma_f32 v[202:203], v[138:139], v[174:175], v[150:151]
	v_pk_fma_f32 v[14:15], v[14:15], v[142:143], v[202:203]
	v_pk_fma_f32 v[14:15], v[146:147], v[194:195], v[14:15]
	ds_read_b64 v[174:175], v244 offset:512
	ds_read_b64 v[194:195], v243 offset:528
	v_cndmask_b32_e64 v196, v196, v200, s[4:5]
	v_cndmask_b32_e64 v197, v197, v201, s[4:5]
	v_pk_fma_f32 v[202:203], v[138:139], v[176:177], v[150:151]
	v_pk_fma_f32 v[6:7], v[6:7], v[142:143], v[202:203]
	v_pk_fma_f32 v[6:7], v[146:147], v[196:197], v[6:7]
	ds_read_b64 v[176:177], v244 offset:768
	ds_read_b64 v[196:197], v243 offset:784
	ds_read_b64 v[200:201], v246 offset:24
	ds_write_b64 v243, v[26:27]
	ds_write_b64 v243, v[18:19] offset:256
	ds_write_b64 v243, v[10:11] offset:512
	ds_write_b64 v243, v[2:3] offset:768
	s_waitcnt lgkmcnt(11)
	v_cndmask_b32_e64 v170, v170, v198, s[6:7]
	v_cndmask_b32_e64 v171, v171, v199, s[6:7]
	v_pk_fma_f32 v[202:203], v[140:141], v[170:171], v[152:153]
	v_pk_fma_f32 v[32:33], v[32:33], v[144:145], v[202:203]
	v_pk_fma_f32 v[32:33], v[148:149], v[178:179], v[32:33]
	ds_read_b64 v[170:171], v244
	ds_read_b64 v[178:179], v243 offset:16
	ds_read_b64 v[198:199], v238 offset:3120
	s_waitcnt lgkmcnt(12)
	v_pk_fma_f32 v[202:203], v[140:141], v[172:173], v[152:153]
	v_pk_fma_f32 v[24:25], v[24:25], v[144:145], v[202:203]
	v_pk_fma_f32 v[24:25], v[148:149], v[180:181], v[24:25]
	ds_read_b64 v[172:173], v244 offset:256
	ds_read_b64 v[180:181], v243 offset:272
	s_waitcnt lgkmcnt(12)
	v_pk_fma_f32 v[202:203], v[140:141], v[174:175], v[152:153]
	v_pk_fma_f32 v[16:17], v[16:17], v[144:145], v[202:203]
	v_pk_fma_f32 v[16:17], v[148:149], v[194:195], v[16:17]
	ds_read_b64 v[174:175], v244 offset:512
	ds_read_b64 v[194:195], v243 offset:528
	s_waitcnt lgkmcnt(11)
	v_cndmask_b32_e64 v196, v196, v200, s[4:5]
	v_cndmask_b32_e64 v197, v197, v201, s[4:5]
	v_pk_fma_f32 v[202:203], v[140:141], v[176:177], v[152:153]
	v_pk_fma_f32 v[8:9], v[8:9], v[144:145], v[202:203]
	v_pk_fma_f32 v[8:9], v[148:149], v[196:197], v[8:9]
	ds_read_b64 v[176:177], v244 offset:768
	ds_read_b64 v[196:197], v243 offset:784
	ds_read_b64 v[200:201], v246 offset:48
	ds_write_b64 v243, v[28:29]
	ds_write_b64 v243, v[20:21] offset:256
	ds_write_b64 v243, v[12:13] offset:512
	ds_write_b64 v243, v[4:5] offset:768
	s_waitcnt lgkmcnt(11)
; #define PG8_LAS __attribute__((address_space(3)))
; __device__ __forceinline__ unsigned cvt_pk_bf16(float lo, float hi) { unsigned r; asm volatile("v_cvt_pk_bf16_f32 %0, %1, %2" : "=v"(r) : "v"(lo), "v"(hi)); return r; }
;     __device__ __forceinline__ void operator()(const f32x4 (&acc)[2][2][4][2], const Unit& u, int wr, int wc, int fr, int fq) const {
;     ...
;                 for (int m = 0; m < 4; ++m) { const int r = 128 * ai + 64 * wr + 16 * m + fr, t = tstart + r;
;                     const bool upok = t >= 1, dnok = (t + 1) < T, store_ok = (r >= vlo) && (r < vhi) && (t < T);
;                     f32x4 res[2];
; #pragma unroll
;                     for (int bj = 0; bj < 2; ++bj) { const f32x4 cur = acc[ai][bj][m][n];
;                         f32x4 su = cur, sd = cur;
;                         if (m > 0) { if (fr == 15) su = acc[ai][bj][m > 0 ? m - 1 : 0][n]; }
;                         if (m < 3) { if (fr == 0) sd = acc[ai][bj][m < 3 ? m + 1 : 3][n]; }
;                         f32x4 up, dn;
;                         up[0] = dpp_ror1(su[0]); up[1] = dpp_ror1(su[1]); up[2] = dpp_ror1(su[2]); up[3] = dpp_ror1(su[3]);
;                         dn[0] = dpp_ror15(sd[0]); dn[1] = dpp_ror15(sd[1]); dn[2] = dpp_ror15(sd[2]); dn[3] = dpp_ror15(sd[3]);
;                         if (m == 0) { f32x4 halo = zero4; if (blk > 0) halo = *(const PG8_LAS f32x4*)(xb + (((((blk - 1) * 2 + 1) * 4 + wc) * 4 + fq) * 16 + (bj * 2 + n) * 4)); if (fr == 0) up = halo; }
;                         if (m == 3) { f32x4 halo = zero4; if (blk < 3) halo = *(const PG8_LAS f32x4*)(xb + (((((blk + 1) * 2 + 0) * 4 + wc) * 4 + fq) * 16 + (bj * 2 + n) * 4)); if (fr == 15) dn = halo; }
;                         if (edge) { if (!upok) up = zero4; if (!dnok) dn = zero4; }
;                         res[bj] = bb[bj] + w0[bj] * up + w1[bj] * cur + w2[bj] * dn; }
;                     if (store_ok) {
;                         float o[4];
; #pragma unroll
;                         for (int j = 0; j < 4; ++j) { const float gg = res[1][j]; o[j] = gg * __builtin_amdgcn_rcpf(1.f + __expf(-gg)) * res[0][j]; }
;                         u32x2 w; w.x = cvt_pk_bf16(o[0], o[1]); w.y = cvt_pk_bf16(o[2], o[3]);
;                         *(u32x2*)(ACT + (size_t)(seqrow + t) * 2816 + ch0 + 4 * n) = w; } } }
	v_cndmask_b32_e64 v170, v170, v198, s[6:7]
	v_cndmask_b32_e64 v171, v171, v199, s[6:7]
	v_pk_fma_f32 v[202:203], v[154:155], v[170:171], v[166:167]
	v_pk_fma_f32 v[26:27], v[26:27], v[158:159], v[202:203]
	v_pk_fma_f32 v[26:27], v[162:163], v[178:179], v[26:27]
	ds_read_b64 v[170:171], v244
	ds_read_b64 v[178:179], v243 offset:16
	ds_read_b64 v[198:199], v238 offset:3128
	s_waitcnt lgkmcnt(12)
	v_pk_fma_f32 v[202:203], v[154:155], v[172:173], v[166:167]
	v_pk_fma_f32 v[18:19], v[18:19], v[158:159], v[202:203]
	v_pk_fma_f32 v[18:19], v[162:163], v[180:181], v[18:19]
	ds_read_b64 v[172:173], v244 offset:256
	ds_read_b64 v[180:181], v243 offset:272
	s_waitcnt lgkmcnt(12)
	v_pk_fma_f32 v[202:203], v[154:155], v[174:175], v[166:167]
	v_pk_fma_f32 v[10:11], v[10:11], v[158:159], v[202:203]
	v_pk_fma_f32 v[10:11], v[162:163], v[194:195], v[10:11]
	ds_read_b64 v[174:175], v244 offset:512
	ds_read_b64 v[194:195], v243 offset:528
	s_waitcnt lgkmcnt(11)
	v_cndmask_b32_e64 v196, v196, v200, s[4:5]
	v_cndmask_b32_e64 v197, v197, v201, s[4:5]
	v_pk_fma_f32 v[202:203], v[154:155], v[176:177], v[166:167]
	v_pk_fma_f32 v[2:3], v[2:3], v[158:159], v[202:203]
	v_pk_fma_f32 v[2:3], v[162:163], v[196:197], v[2:3]
	ds_read_b64 v[176:177], v244 offset:768
	ds_read_b64 v[196:197], v243 offset:784
	ds_read_b64 v[200:201], v246 offset:56
	s_waitcnt lgkmcnt(7)
	v_cndmask_b32_e64 v170, v170, v198, s[6:7]
	v_cndmask_b32_e64 v171, v171, v199, s[6:7]
	v_pk_fma_f32 v[202:203], v[156:157], v[170:171], v[168:169]
	v_pk_fma_f32 v[28:29], v[28:29], v[160:161], v[202:203]
	v_pk_fma_f32 v[28:29], v[164:165], v[178:179], v[28:29]
	s_waitcnt lgkmcnt(5)
	v_pk_fma_f32 v[202:203], v[156:157], v[172:173], v[168:169]
	v_pk_fma_f32 v[20:21], v[20:21], v[160:161], v[202:203]
	v_pk_fma_f32 v[20:21], v[164:165], v[180:181], v[20:21]
	s_waitcnt lgkmcnt(3)
	v_pk_fma_f32 v[202:203], v[156:157], v[174:175], v[168:169]
	v_pk_fma_f32 v[12:13], v[12:13], v[160:161], v[202:203]
	v_pk_fma_f32 v[12:13], v[164:165], v[194:195], v[12:13]
	s_waitcnt lgkmcnt(0)
	v_cndmask_b32_e64 v196, v196, v200, s[4:5]
	v_cndmask_b32_e64 v197, v197, v201, s[4:5]
	v_pk_fma_f32 v[202:203], v[156:157], v[176:177], v[168:169]
	v_pk_fma_f32 v[4:5], v[4:5], v[160:161], v[202:203]
	v_pk_fma_f32 v[4:5], v[164:165], v[196:197], v[4:5]
	v_mul_f32_e32 v208, 0xbfb8aa3b, v26
	v_mul_f32_e32 v209, 0xbfb8aa3b, v27
	v_mul_f32_e32 v210, 0xbfb8aa3b, v28
	v_mul_f32_e32 v211, 0xbfb8aa3b, v29
	v_exp_f32_e32 v208, v208
	v_exp_f32_e32 v209, v209
	v_exp_f32_e32 v210, v210
	v_exp_f32_e32 v211, v211
	v_add_f32_e32 v208, 1.0, v208
	v_add_f32_e32 v209, 1.0, v209
	v_add_f32_e32 v210, 1.0, v210
	v_add_f32_e32 v211, 1.0, v211
	v_rcp_f32_e32 v208, v208
	v_rcp_f32_e32 v209, v209
	v_rcp_f32_e32 v210, v210
	v_rcp_f32_e32 v211, v211
	v_mul_f32_e32 v26, v26, v208
	v_mul_f32_e32 v27, v27, v209
	v_mul_f32_e32 v28, v28, v210
	v_mul_f32_e32 v29, v29, v211
	v_mul_f32_e32 v26, v30, v26
	v_mul_f32_e32 v27, v31, v27
	v_mul_f32_e32 v28, v32, v28
	v_mul_f32_e32 v29, v33, v29
	v_cvt_pk_bf16_f32 v26, v26, v27
	v_cvt_pk_bf16_f32 v27, v28, v29
	ds_bpermute_b32 v100, v250, v26
	ds_bpermute_b32 v101, v250, v27
	v_mul_f32_e32 v208, 0xbfb8aa3b, v18
	v_mul_f32_e32 v209, 0xbfb8aa3b, v19
	v_mul_f32_e32 v210, 0xbfb8aa3b, v20
	v_mul_f32_e32 v211, 0xbfb8aa3b, v21
	v_exp_f32_e32 v208, v208
	v_exp_f32_e32 v209, v209
	v_exp_f32_e32 v210, v210
	v_exp_f32_e32 v211, v211
	v_add_f32_e32 v208, 1.0, v208
	v_add_f32_e32 v209, 1.0, v209
	v_add_f32_e32 v210, 1.0, v210
	v_add_f32_e32 v211, 1.0, v211
	v_rcp_f32_e32 v208, v208
	v_rcp_f32_e32 v209, v209
	v_rcp_f32_e32 v210, v210
	v_rcp_f32_e32 v211, v211
	v_mul_f32_e32 v18, v18, v208
	v_mul_f32_e32 v19, v19, v209
	v_mul_f32_e32 v20, v20, v210
	v_mul_f32_e32 v21, v21, v211
	v_mul_f32_e32 v18, v22, v18
	v_mul_f32_e32 v19, v23, v19
	v_mul_f32_e32 v20, v24, v20
	v_mul_f32_e32 v21, v25, v21
	v_cvt_pk_bf16_f32 v18, v18, v19
	v_cvt_pk_bf16_f32 v19, v20, v21
	ds_bpermute_b32 v92, v250, v18
	ds_bpermute_b32 v93, v250, v19
	v_mul_f32_e32 v208, 0xbfb8aa3b, v10
	v_mul_f32_e32 v209, 0xbfb8aa3b, v11
	v_mul_f32_e32 v210, 0xbfb8aa3b, v12
	v_mul_f32_e32 v211, 0xbfb8aa3b, v13
	v_exp_f32_e32 v208, v208
	v_exp_f32_e32 v209, v209
	v_exp_f32_e32 v210, v210
	v_exp_f32_e32 v211, v211
	v_add_f32_e32 v208, 1.0, v208
	v_add_f32_e32 v209, 1.0, v209
	v_add_f32_e32 v210, 1.0, v210
	v_add_f32_e32 v211, 1.0, v211
	v_rcp_f32_e32 v208, v208
	v_rcp_f32_e32 v209, v209
	v_rcp_f32_e32 v210, v210
	v_rcp_f32_e32 v211, v211
	v_mul_f32_e32 v10, v10, v208
	v_mul_f32_e32 v11, v11, v209
	v_mul_f32_e32 v12, v12, v210
	v_mul_f32_e32 v13, v13, v211
	v_mul_f32_e32 v10, v14, v10
	v_mul_f32_e32 v11, v15, v11
	v_mul_f32_e32 v12, v16, v12
	v_mul_f32_e32 v13, v17, v13
	v_cvt_pk_bf16_f32 v10, v10, v11
	v_cvt_pk_bf16_f32 v11, v12, v13
	ds_bpermute_b32 v84, v250, v10
	ds_bpermute_b32 v85, v250, v11
	v_mul_f32_e32 v208, 0xbfb8aa3b, v2
	v_mul_f32_e32 v209, 0xbfb8aa3b, v3
	v_mul_f32_e32 v210, 0xbfb8aa3b, v4
	v_mul_f32_e32 v211, 0xbfb8aa3b, v5
	v_exp_f32_e32 v208, v208
	v_exp_f32_e32 v209, v209
	v_exp_f32_e32 v210, v210
	v_exp_f32_e32 v211, v211
	v_add_f32_e32 v208, 1.0, v208
	v_add_f32_e32 v209, 1.0, v209
	v_add_f32_e32 v210, 1.0, v210
	v_add_f32_e32 v211, 1.0, v211
	v_rcp_f32_e32 v208, v208
	v_rcp_f32_e32 v209, v209
	v_rcp_f32_e32 v210, v210
	v_rcp_f32_e32 v211, v211
	v_mul_f32_e32 v2, v2, v208
	v_mul_f32_e32 v3, v3, v209
	v_mul_f32_e32 v4, v4, v210
	v_mul_f32_e32 v5, v5, v211
	v_mul_f32_e32 v2, v6, v2
	v_mul_f32_e32 v3, v7, v3
	v_mul_f32_e32 v4, v8, v4
	v_mul_f32_e32 v5, v9, v5
	v_cvt_pk_bf16_f32 v2, v2, v3
	v_cvt_pk_bf16_f32 v3, v4, v5
	ds_bpermute_b32 v76, v250, v2
	ds_bpermute_b32 v77, v250, v3
	s_waitcnt lgkmcnt(6)
	v_add_u32_e32 v221, 0xb0000, v247
	s_and_saveexec_b64 s[30:31], s[20:21]
	global_store_dwordx4 v221, v[98:101], s[10:11]
	s_mov_b64 exec, s[30:31]
	s_waitcnt lgkmcnt(4)
	v_add_u32_e32 v251, 0xc6000, v247
	s_and_saveexec_b64 s[30:31], s[22:23]
	global_store_dwordx4 v251, v[90:93], s[10:11]
	s_mov_b64 exec, s[30:31]
	s_waitcnt lgkmcnt(2)
	v_add_u32_e32 v221, 0xdc000, v247
	s_and_saveexec_b64 s[30:31], s[24:25]
	global_store_dwordx4 v221, v[82:85], s[10:11]
	s_mov_b64 exec, s[30:31]
	s_waitcnt lgkmcnt(0)
	v_add_u32_e32 v251, 0xf2000, v247
	s_and_saveexec_b64 s[30:31], s[26:27]
	global_store_dwordx4 v251, v[74:77], s[10:11]
	s_mov_b64 exec, s[30:31]
	s_branch .Lec_done
; #define PG8_LAS __attribute__((address_space(3)))
; __device__ __forceinline__ float dpp_ror1(float v) { return __builtin_bit_cast(float, __builtin_amdgcn_update_dpp(0, __builtin_bit_cast(int, v), 0x121, 0xf, 0xf, false)); }
; __device__ __forceinline__ float dpp_ror15(float v) { return __builtin_bit_cast(float, __builtin_amdgcn_update_dpp(0, __builtin_bit_cast(int, v), 0x12F, 0xf, 0xf, false)); }
;     __device__ __forceinline__ void operator()(const f32x4 (&acc)[2][2][4][2], const Unit& u, int wr, int wc, int fr, int fq) const {
;     ...
;                 for (int m = 0; m < 4; ++m) { const int r = 128 * ai + 64 * wr + 16 * m + fr, t = tstart + r;
;                     const bool upok = t >= 1, dnok = (t + 1) < T, store_ok = (r >= vlo) && (r < vhi) && (t < T);
;                     f32x4 res[2];
; #pragma unroll
;                     for (int bj = 0; bj < 2; ++bj) { const f32x4 cur = acc[ai][bj][m][n];
;                         f32x4 su = cur, sd = cur;
;                         if (m > 0) { if (fr == 15) su = acc[ai][bj][m > 0 ? m - 1 : 0][n]; }
;                         if (m < 3) { if (fr == 0) sd = acc[ai][bj][m < 3 ? m + 1 : 3][n]; }
;                         f32x4 up, dn;
;                         up[0] = dpp_ror1(su[0]); up[1] = dpp_ror1(su[1]); up[2] = dpp_ror1(su[2]); up[3] = dpp_ror1(su[3]);
;                         dn[0] = dpp_ror15(sd[0]); dn[1] = dpp_ror15(sd[1]); dn[2] = dpp_ror15(sd[2]); dn[3] = dpp_ror15(sd[3]);
;                         if (m == 0) { f32x4 halo = zero4; if (blk > 0) halo = *(const PG8_LAS f32x4*)(xb + (((((blk - 1) * 2 + 1) * 4 + wc) * 4 + fq) * 16 + (bj * 2 + n) * 4)); if (fr == 0) up = halo; }
;                         if (m == 3) { f32x4 halo = zero4; if (blk < 3) halo = *(const PG8_LAS f32x4*)(xb + (((((blk + 1) * 2 + 0) * 4 + wc) * 4 + fq) * 16 + (bj * 2 + n) * 4)); if (fr == 15) dn = halo; }
;                         if (edge) { if (!upok) up = zero4; if (!dnok) dn = zero4; }
;                         res[bj] = bb[bj] + w0[bj] * up + w1[bj] * cur + w2[bj] * dn; }
.Lec_edge:
	v_mbcnt_lo_u32_b32 v251, -1, 0
	v_mbcnt_hi_u32_b32 v251, -1, v251
	v_and_b32_e32 v220, 3, v251
	v_lshrrev_b32_e32 v251, 2, v251
	v_lshl_add_u32 v250, v220, 4, v251
	v_lshlrev_b32_e32 v250, 2, v250
	v_sub_u32_e32 v221, v227, v226
	v_add_u32_e32 v251, v221, v251
	v_and_b32_e32 v221, 0x60, v229
	v_lshl_add_u32 v221, v220, 3, v221
	v_lshl_or_b32 v221, s2, 7, v221
	v_lshlrev_b32_e32 v221, 1, v221
	s_add_i32 s0, s78, s48
	s_mulk_i32 s0, 0x1600
	v_add_u32_e32 v221, s0, v221
	v_mad_u32_u24 v247, v251, s29, v221
	v_add_u32_e32 v220, 0, v251
	v_cmp_le_i32_e64 s[12:13], s54, v220
	v_cmp_gt_i32_e32 vcc, s55, v220
	s_and_b64 s[12:13], s[12:13], vcc
	v_add_u32_e32 v220, s48, v220
	v_cmp_gt_i32_e32 vcc, s93, v220
	s_and_b64 s[12:13], s[12:13], vcc
	v_add_u32_e32 v220, 16, v251
	v_cmp_le_i32_e64 s[14:15], s54, v220
	v_cmp_gt_i32_e32 vcc, s55, v220
	s_and_b64 s[14:15], s[14:15], vcc
	v_add_u32_e32 v220, s48, v220
	v_cmp_gt_i32_e32 vcc, s93, v220
	s_and_b64 s[14:15], s[14:15], vcc
	v_add_u32_e32 v220, 32, v251
	v_cmp_le_i32_e64 s[16:17], s54, v220
	v_cmp_gt_i32_e32 vcc, s55, v220
	s_and_b64 s[16:17], s[16:17], vcc
	v_add_u32_e32 v220, s48, v220
	v_cmp_gt_i32_e32 vcc, s93, v220
	s_and_b64 s[16:17], s[16:17], vcc
	v_add_u32_e32 v220, 48, v251
	v_cmp_le_i32_e64 s[18:19], s54, v220
	v_cmp_gt_i32_e32 vcc, s55, v220
	s_and_b64 s[18:19], s[18:19], vcc
	v_add_u32_e32 v220, s48, v220
	v_cmp_gt_i32_e32 vcc, s93, v220
	s_and_b64 s[18:19], s[18:19], vcc
	v_add_u32_e32 v220, 128, v251
	v_cmp_le_i32_e64 s[20:21], s54, v220
	v_cmp_gt_i32_e32 vcc, s55, v220
	s_and_b64 s[20:21], s[20:21], vcc
	v_add_u32_e32 v220, s48, v220
	v_cmp_gt_i32_e32 vcc, s93, v220
	s_and_b64 s[20:21], s[20:21], vcc
	v_add_u32_e32 v220, 144, v251
	v_cmp_le_i32_e64 s[22:23], s54, v220
	v_cmp_gt_i32_e32 vcc, s55, v220
	s_and_b64 s[22:23], s[22:23], vcc
	v_add_u32_e32 v220, s48, v220
	v_cmp_gt_i32_e32 vcc, s93, v220
	s_and_b64 s[22:23], s[22:23], vcc
	v_add_u32_e32 v220, 160, v251
	v_cmp_le_i32_e64 s[24:25], s54, v220
	v_cmp_gt_i32_e32 vcc, s55, v220
	s_and_b64 s[24:25], s[24:25], vcc
	v_add_u32_e32 v220, s48, v220
	v_cmp_gt_i32_e32 vcc, s93, v220
	s_and_b64 s[24:25], s[24:25], vcc
	v_add_u32_e32 v220, 176, v251
	v_cmp_le_i32_e64 s[26:27], s54, v220
	v_cmp_gt_i32_e32 vcc, s55, v220
	s_and_b64 s[26:27], s[26:27], vcc
	v_add_u32_e32 v220, s48, v220
	v_cmp_gt_i32_e32 vcc, s93, v220
	s_and_b64 s[26:27], s[26:27], vcc
	ds_write_b64 v243, v[166:167]
	ds_write_b64 v243, v[158:159] offset:256
	ds_write_b64 v243, v[150:151] offset:512
	ds_write_b64 v243, v[142:143] offset:768
	ds_read_b64 v[170:171], v244
	ds_read_b64 v[178:179], v243 offset:16
	ds_read_b64 v[198:199], v245
	ds_read_b64 v[172:173], v244 offset:256
	ds_read_b64 v[180:181], v243 offset:272
	ds_read_b64 v[174:175], v244 offset:512
	ds_read_b64 v[194:195], v243 offset:528
	ds_read_b64 v[176:177], v244 offset:768
	ds_read_b64 v[196:197], v243 offset:784
	ds_read_b64 v[200:201], v238 offset:2048
	s_waitcnt vmcnt(0)
	ds_write_b64 v243, v[168:169]
	ds_write_b64 v243, v[160:161] offset:256
	ds_write_b64 v243, v[152:153] offset:512
	ds_write_b64 v243, v[144:145] offset:768
	s_waitcnt lgkmcnt(11)
	v_cndmask_b32_e64 v170, v170, v198, s[6:7]
	v_cndmask_b32_e64 v171, v171, v199, s[6:7]
	v_add_u32_e32 v220, s48, v227
	v_cmp_lt_i32_e32 vcc, 0, v220
	s_nop 1
	v_cndmask_b32_e32 v170, 0, v170, vcc
	v_cndmask_b32_e32 v171, 0, v171, vcc
	v_cmp_gt_i32_e32 vcc, s28, v220
	s_nop 1
	v_cndmask_b32_e32 v178, 0, v178, vcc
	v_cndmask_b32_e32 v179, 0, v179, vcc
	v_pk_fma_f32 v[202:203], v[106:107], v[170:171], v[118:119]
	v_pk_fma_f32 v[166:167], v[166:167], v[110:111], v[202:203]
	v_pk_fma_f32 v[166:167], v[114:115], v[178:179], v[166:167]
	ds_read_b64 v[170:171], v244
	ds_read_b64 v[178:179], v243 offset:16
	ds_read_b64 v[198:199], v245 offset:8
	s_waitcnt lgkmcnt(12)
	v_add_u32_e32 v220, s48, v231
	v_cmp_lt_i32_e32 vcc, 0, v220
	s_nop 1
	v_cndmask_b32_e32 v172, 0, v172, vcc
	v_cndmask_b32_e32 v173, 0, v173, vcc
	v_cmp_gt_i32_e32 vcc, s28, v220
	s_nop 1
	v_cndmask_b32_e32 v180, 0, v180, vcc
	v_cndmask_b32_e32 v181, 0, v181, vcc
	v_pk_fma_f32 v[202:203], v[106:107], v[172:173], v[118:119]
	v_pk_fma_f32 v[158:159], v[158:159], v[110:111], v[202:203]
	v_pk_fma_f32 v[158:159], v[114:115], v[180:181], v[158:159]
	ds_read_b64 v[172:173], v244 offset:256
	ds_read_b64 v[180:181], v243 offset:272
	s_waitcnt lgkmcnt(12)
	v_add_u32_e32 v220, s48, v232
	v_cmp_lt_i32_e32 vcc, 0, v220
	s_nop 1
	v_cndmask_b32_e32 v174, 0, v174, vcc
	v_cndmask_b32_e32 v175, 0, v175, vcc
	v_cmp_gt_i32_e32 vcc, s28, v220
	s_nop 1
	v_cndmask_b32_e32 v194, 0, v194, vcc
	v_cndmask_b32_e32 v195, 0, v195, vcc
	v_pk_fma_f32 v[202:203], v[106:107], v[174:175], v[118:119]
	v_pk_fma_f32 v[150:151], v[150:151], v[110:111], v[202:203]
	v_pk_fma_f32 v[150:151], v[114:115], v[194:195], v[150:151]
	ds_read_b64 v[174:175], v244 offset:512
	ds_read_b64 v[194:195], v243 offset:528
	s_waitcnt lgkmcnt(11)
	v_cndmask_b32_e64 v196, v196, v200, s[4:5]
	v_cndmask_b32_e64 v197, v197, v201, s[4:5]
	v_add_u32_e32 v220, s48, v233
	v_cmp_lt_i32_e32 vcc, 0, v220
	s_nop 1
	v_cndmask_b32_e32 v176, 0, v176, vcc
	v_cndmask_b32_e32 v177, 0, v177, vcc
	v_cmp_gt_i32_e32 vcc, s28, v220
	s_nop 1
	v_cndmask_b32_e32 v196, 0, v196, vcc
	v_cndmask_b32_e32 v197, 0, v197, vcc
	v_pk_fma_f32 v[202:203], v[106:107], v[176:177], v[118:119]
	v_pk_fma_f32 v[142:143], v[142:143], v[110:111], v[202:203]
	v_pk_fma_f32 v[142:143], v[114:115], v[196:197], v[142:143]
	ds_read_b64 v[176:177], v244 offset:768
	ds_read_b64 v[196:197], v243 offset:784
	ds_read_b64 v[200:201], v238 offset:2056
	ds_write_b64 v243, v[162:163]
	ds_write_b64 v243, v[154:155] offset:256
	ds_write_b64 v243, v[146:147] offset:512
	ds_write_b64 v243, v[138:139] offset:768
	s_waitcnt lgkmcnt(11)
; #define PG8_LAS __attribute__((address_space(3)))
; __device__ __forceinline__ float dpp_ror1(float v) { return __builtin_bit_cast(float, __builtin_amdgcn_update_dpp(0, __builtin_bit_cast(int, v), 0x121, 0xf, 0xf, false)); }
; __device__ __forceinline__ float dpp_ror15(float v) { return __builtin_bit_cast(float, __builtin_amdgcn_update_dpp(0, __builtin_bit_cast(int, v), 0x12F, 0xf, 0xf, false)); }
;     __device__ __forceinline__ void operator()(const f32x4 (&acc)[2][2][4][2], const Unit& u, int wr, int wc, int fr, int fq) const {
;     ...
;                 for (int m = 0; m < 4; ++m) { const int r = 128 * ai + 64 * wr + 16 * m + fr, t = tstart + r;
;                     const bool upok = t >= 1, dnok = (t + 1) < T, store_ok = (r >= vlo) && (r < vhi) && (t < T);
;                     f32x4 res[2];
; #pragma unroll
;                     for (int bj = 0; bj < 2; ++bj) { const f32x4 cur = acc[ai][bj][m][n];
;                         f32x4 su = cur, sd = cur;
;                         if (m > 0) { if (fr == 15) su = acc[ai][bj][m > 0 ? m - 1 : 0][n]; }
;                         if (m < 3) { if (fr == 0) sd = acc[ai][bj][m < 3 ? m + 1 : 3][n]; }
;                         f32x4 up, dn;
;                         up[0] = dpp_ror1(su[0]); up[1] = dpp_ror1(su[1]); up[2] = dpp_ror1(su[2]); up[3] = dpp_ror1(su[3]);
;                         dn[0] = dpp_ror15(sd[0]); dn[1] = dpp_ror15(sd[1]); dn[2] = dpp_ror15(sd[2]); dn[3] = dpp_ror15(sd[3]);
;                         if (m == 0) { f32x4 halo = zero4; if (blk > 0) halo = *(const PG8_LAS f32x4*)(xb + (((((blk - 1) * 2 + 1) * 4 + wc) * 4 + fq) * 16 + (bj * 2 + n) * 4)); if (fr == 0) up = halo; }
;                         if (m == 3) { f32x4 halo = zero4; if (blk < 3) halo = *(const PG8_LAS f32x4*)(xb + (((((blk + 1) * 2 + 0) * 4 + wc) * 4 + fq) * 16 + (bj * 2 + n) * 4)); if (fr == 15) dn = halo; }
;                         if (edge) { if (!upok) up = zero4; if (!dnok) dn = zero4; }
;                         res[bj] = bb[bj] + w0[bj] * up + w1[bj] * cur + w2[bj] * dn; }
	v_cndmask_b32_e64 v170, v170, v198, s[6:7]
	v_cndmask_b32_e64 v171, v171, v199, s[6:7]
	v_add_u32_e32 v220, s48, v227
	v_cmp_lt_i32_e32 vcc, 0, v220
	s_nop 1
	v_cndmask_b32_e32 v170, 0, v170, vcc
	v_cndmask_b32_e32 v171, 0, v171, vcc
	v_cmp_gt_i32_e32 vcc, s28, v220
	s_nop 1
	v_cndmask_b32_e32 v178, 0, v178, vcc
	v_cndmask_b32_e32 v179, 0, v179, vcc
	v_pk_fma_f32 v[202:203], v[108:109], v[170:171], v[120:121]
	v_pk_fma_f32 v[168:169], v[168:169], v[112:113], v[202:203]
	v_pk_fma_f32 v[168:169], v[116:117], v[178:179], v[168:169]
	ds_read_b64 v[170:171], v244
	ds_read_b64 v[178:179], v243 offset:16
	ds_read_b64 v[198:199], v245 offset:32
	s_waitcnt lgkmcnt(12)
	v_add_u32_e32 v220, s48, v231
	v_cmp_lt_i32_e32 vcc, 0, v220
	s_nop 1
	v_cndmask_b32_e32 v172, 0, v172, vcc
	v_cndmask_b32_e32 v173, 0, v173, vcc
	v_cmp_gt_i32_e32 vcc, s28, v220
	s_nop 1
	v_cndmask_b32_e32 v180, 0, v180, vcc
	v_cndmask_b32_e32 v181, 0, v181, vcc
	v_pk_fma_f32 v[202:203], v[108:109], v[172:173], v[120:121]
	v_pk_fma_f32 v[160:161], v[160:161], v[112:113], v[202:203]
	v_pk_fma_f32 v[160:161], v[116:117], v[180:181], v[160:161]
	ds_read_b64 v[172:173], v244 offset:256
	ds_read_b64 v[180:181], v243 offset:272
	s_waitcnt lgkmcnt(12)
	v_add_u32_e32 v220, s48, v232
	v_cmp_lt_i32_e32 vcc, 0, v220
	s_nop 1
	v_cndmask_b32_e32 v174, 0, v174, vcc
	v_cndmask_b32_e32 v175, 0, v175, vcc
	v_cmp_gt_i32_e32 vcc, s28, v220
	s_nop 1
	v_cndmask_b32_e32 v194, 0, v194, vcc
	v_cndmask_b32_e32 v195, 0, v195, vcc
	v_pk_fma_f32 v[202:203], v[108:109], v[174:175], v[120:121]
	v_pk_fma_f32 v[152:153], v[152:153], v[112:113], v[202:203]
	v_pk_fma_f32 v[152:153], v[116:117], v[194:195], v[152:153]
	ds_read_b64 v[174:175], v244 offset:512
	ds_read_b64 v[194:195], v243 offset:528
	s_waitcnt lgkmcnt(11)
	v_cndmask_b32_e64 v196, v196, v200, s[4:5]
	v_cndmask_b32_e64 v197, v197, v201, s[4:5]
	v_add_u32_e32 v220, s48, v233
	v_cmp_lt_i32_e32 vcc, 0, v220
	s_nop 1
	v_cndmask_b32_e32 v176, 0, v176, vcc
	v_cndmask_b32_e32 v177, 0, v177, vcc
	v_cmp_gt_i32_e32 vcc, s28, v220
	s_nop 1
	v_cndmask_b32_e32 v196, 0, v196, vcc
	v_cndmask_b32_e32 v197, 0, v197, vcc
	v_pk_fma_f32 v[202:203], v[108:109], v[176:177], v[120:121]
	v_pk_fma_f32 v[144:145], v[144:145], v[112:113], v[202:203]
	v_pk_fma_f32 v[144:145], v[116:117], v[196:197], v[144:145]
	ds_read_b64 v[176:177], v244 offset:768
	ds_read_b64 v[196:197], v243 offset:784
	ds_read_b64 v[200:201], v238 offset:2080
	ds_write_b64 v243, v[164:165]
	ds_write_b64 v243, v[156:157] offset:256
	ds_write_b64 v243, v[148:149] offset:512
	ds_write_b64 v243, v[140:141] offset:768
	s_waitcnt lgkmcnt(11)
	v_cndmask_b32_e64 v170, v170, v198, s[6:7]
	v_cndmask_b32_e64 v171, v171, v199, s[6:7]
	v_add_u32_e32 v220, s48, v227
	v_cmp_lt_i32_e32 vcc, 0, v220
	s_nop 1
	v_cndmask_b32_e32 v170, 0, v170, vcc
	v_cndmask_b32_e32 v171, 0, v171, vcc
	v_cmp_gt_i32_e32 vcc, s28, v220
	s_nop 1
	v_cndmask_b32_e32 v178, 0, v178, vcc
	v_cndmask_b32_e32 v179, 0, v179, vcc
	v_pk_fma_f32 v[202:203], v[122:123], v[170:171], v[134:135]
	v_pk_fma_f32 v[162:163], v[162:163], v[126:127], v[202:203]
	v_pk_fma_f32 v[162:163], v[130:131], v[178:179], v[162:163]
	ds_read_b64 v[170:171], v244
	ds_read_b64 v[178:179], v243 offset:16
	ds_read_b64 v[198:199], v245 offset:40
	s_waitcnt lgkmcnt(12)
	v_add_u32_e32 v220, s48, v231
	v_cmp_lt_i32_e32 vcc, 0, v220
	s_nop 1
	v_cndmask_b32_e32 v172, 0, v172, vcc
	v_cndmask_b32_e32 v173, 0, v173, vcc
	v_cmp_gt_i32_e32 vcc, s28, v220
	s_nop 1
	v_cndmask_b32_e32 v180, 0, v180, vcc
	v_cndmask_b32_e32 v181, 0, v181, vcc
	v_pk_fma_f32 v[202:203], v[122:123], v[172:173], v[134:135]
	v_pk_fma_f32 v[154:155], v[154:155], v[126:127], v[202:203]
	v_pk_fma_f32 v[154:155], v[130:131], v[180:181], v[154:155]
	ds_read_b64 v[172:173], v244 offset:256
	ds_read_b64 v[180:181], v243 offset:272
	s_waitcnt lgkmcnt(12)
	v_add_u32_e32 v220, s48, v232
	v_cmp_lt_i32_e32 vcc, 0, v220
	s_nop 1
	v_cndmask_b32_e32 v174, 0, v174, vcc
	v_cndmask_b32_e32 v175, 0, v175, vcc
	v_cmp_gt_i32_e32 vcc, s28, v220
	s_nop 1
	v_cndmask_b32_e32 v194, 0, v194, vcc
	v_cndmask_b32_e32 v195, 0, v195, vcc
	v_pk_fma_f32 v[202:203], v[122:123], v[174:175], v[134:135]
	v_pk_fma_f32 v[146:147], v[146:147], v[126:127], v[202:203]
	v_pk_fma_f32 v[146:147], v[130:131], v[194:195], v[146:147]
	ds_read_b64 v[174:175], v244 offset:512
	ds_read_b64 v[194:195], v243 offset:528
	s_waitcnt lgkmcnt(11)
	v_cndmask_b32_e64 v196, v196, v200, s[4:5]
	v_cndmask_b32_e64 v197, v197, v201, s[4:5]
	v_add_u32_e32 v220, s48, v233
	v_cmp_lt_i32_e32 vcc, 0, v220
	s_nop 1
	v_cndmask_b32_e32 v176, 0, v176, vcc
	v_cndmask_b32_e32 v177, 0, v177, vcc
	v_cmp_gt_i32_e32 vcc, s28, v220
	s_nop 1
	v_cndmask_b32_e32 v196, 0, v196, vcc
	v_cndmask_b32_e32 v197, 0, v197, vcc
	v_pk_fma_f32 v[202:203], v[122:123], v[176:177], v[134:135]
	v_pk_fma_f32 v[138:139], v[138:139], v[126:127], v[202:203]
	v_pk_fma_f32 v[138:139], v[130:131], v[196:197], v[138:139]
	ds_read_b64 v[176:177], v244 offset:768
	ds_read_b64 v[196:197], v243 offset:784
	ds_read_b64 v[200:201], v238 offset:2088
	ds_write_b64 v243, v[102:103]
	ds_write_b64 v243, v[94:95] offset:256
	ds_write_b64 v243, v[86:87] offset:512
	ds_write_b64 v243, v[78:79] offset:768
	s_waitcnt lgkmcnt(11)
	v_cndmask_b32_e64 v170, v170, v198, s[6:7]
	v_cndmask_b32_e64 v171, v171, v199, s[6:7]
	v_add_u32_e32 v220, s48, v227
	v_cmp_lt_i32_e32 vcc, 0, v220
	s_nop 1
	v_cndmask_b32_e32 v170, 0, v170, vcc
	v_cndmask_b32_e32 v171, 0, v171, vcc
	v_cmp_gt_i32_e32 vcc, s28, v220
	s_nop 1
	v_cndmask_b32_e32 v178, 0, v178, vcc
	v_cndmask_b32_e32 v179, 0, v179, vcc
	v_pk_fma_f32 v[202:203], v[124:125], v[170:171], v[136:137]
	v_pk_fma_f32 v[164:165], v[164:165], v[128:129], v[202:203]
	v_pk_fma_f32 v[164:165], v[132:133], v[178:179], v[164:165]
	ds_read_b64 v[170:171], v244
	ds_read_b64 v[178:179], v243 offset:16
	ds_read_b64 v[198:199], v238 offset:3072
	s_waitcnt lgkmcnt(12)
; #define PG8_LAS __attribute__((address_space(3)))
; __device__ __forceinline__ unsigned cvt_pk_bf16(float lo, float hi) { unsigned r; asm volatile("v_cvt_pk_bf16_f32 %0, %1, %2" : "=v"(r) : "v"(lo), "v"(hi)); return r; }
; __device__ __forceinline__ float dpp_ror1(float v) { return __builtin_bit_cast(float, __builtin_amdgcn_update_dpp(0, __builtin_bit_cast(int, v), 0x121, 0xf, 0xf, false)); }
; __device__ __forceinline__ float dpp_ror15(float v) { return __builtin_bit_cast(float, __builtin_amdgcn_update_dpp(0, __builtin_bit_cast(int, v), 0x12F, 0xf, 0xf, false)); }
;     __device__ __forceinline__ void operator()(const f32x4 (&acc)[2][2][4][2], const Unit& u, int wr, int wc, int fr, int fq) const {
;     ...
;                     for (int bj = 0; bj < 2; ++bj) { const f32x4 cur = acc[ai][bj][m][n];
;                         f32x4 su = cur, sd = cur;
;                         if (m > 0) { if (fr == 15) su = acc[ai][bj][m > 0 ? m - 1 : 0][n]; }
;                         if (m < 3) { if (fr == 0) sd = acc[ai][bj][m < 3 ? m + 1 : 3][n]; }
;                         f32x4 up, dn;
;                         up[0] = dpp_ror1(su[0]); up[1] = dpp_ror1(su[1]); up[2] = dpp_ror1(su[2]); up[3] = dpp_ror1(su[3]);
;                         dn[0] = dpp_ror15(sd[0]); dn[1] = dpp_ror15(sd[1]); dn[2] = dpp_ror15(sd[2]); dn[3] = dpp_ror15(sd[3]);
;                         if (m == 0) { f32x4 halo = zero4; if (blk > 0) halo = *(const PG8_LAS f32x4*)(xb + (((((blk - 1) * 2 + 1) * 4 + wc) * 4 + fq) * 16 + (bj * 2 + n) * 4)); if (fr == 0) up = halo; }
;                         if (m == 3) { f32x4 halo = zero4; if (blk < 3) halo = *(const PG8_LAS f32x4*)(xb + (((((blk + 1) * 2 + 0) * 4 + wc) * 4 + fq) * 16 + (bj * 2 + n) * 4)); if (fr == 15) dn = halo; }
;                         if (edge) { if (!upok) up = zero4; if (!dnok) dn = zero4; }
;                         res[bj] = bb[bj] + w0[bj] * up + w1[bj] * cur + w2[bj] * dn; }
;                     if (store_ok) {
;                         float o[4];
; #pragma unroll
;                         for (int j = 0; j < 4; ++j) { const float gg = res[1][j]; o[j] = gg * __builtin_amdgcn_rcpf(1.f + __expf(-gg)) * res[0][j]; }
;                         u32x2 w; w.x = cvt_pk_bf16(o[0], o[1]); w.y = cvt_pk_bf16(o[2], o[3]);
;                         *(u32x2*)(ACT + (size_t)(seqrow + t) * 2816 + ch0 + 4 * n) = w; } } }
	v_add_u32_e32 v220, s48, v231
	v_cmp_lt_i32_e32 vcc, 0, v220
	s_nop 1
	v_cndmask_b32_e32 v172, 0, v172, vcc
	v_cndmask_b32_e32 v173, 0, v173, vcc
	v_cmp_gt_i32_e32 vcc, s28, v220
	s_nop 1
	v_cndmask_b32_e32 v180, 0, v180, vcc
	v_cndmask_b32_e32 v181, 0, v181, vcc
	v_pk_fma_f32 v[202:203], v[124:125], v[172:173], v[136:137]
	v_pk_fma_f32 v[156:157], v[156:157], v[128:129], v[202:203]
	v_pk_fma_f32 v[156:157], v[132:133], v[180:181], v[156:157]
	ds_read_b64 v[172:173], v244 offset:256
	ds_read_b64 v[180:181], v243 offset:272
	s_waitcnt lgkmcnt(12)
	v_add_u32_e32 v220, s48, v232
	v_cmp_lt_i32_e32 vcc, 0, v220
	s_nop 1
	v_cndmask_b32_e32 v174, 0, v174, vcc
	v_cndmask_b32_e32 v175, 0, v175, vcc
	v_cmp_gt_i32_e32 vcc, s28, v220
	s_nop 1
	v_cndmask_b32_e32 v194, 0, v194, vcc
	v_cndmask_b32_e32 v195, 0, v195, vcc
	v_pk_fma_f32 v[202:203], v[124:125], v[174:175], v[136:137]
	v_pk_fma_f32 v[148:149], v[148:149], v[128:129], v[202:203]
	v_pk_fma_f32 v[148:149], v[132:133], v[194:195], v[148:149]
	ds_read_b64 v[174:175], v244 offset:512
	ds_read_b64 v[194:195], v243 offset:528
	s_waitcnt lgkmcnt(11)
	v_cndmask_b32_e64 v196, v196, v200, s[4:5]
	v_cndmask_b32_e64 v197, v197, v201, s[4:5]
	v_add_u32_e32 v220, s48, v233
	v_cmp_lt_i32_e32 vcc, 0, v220
	s_nop 1
	v_cndmask_b32_e32 v176, 0, v176, vcc
	v_cndmask_b32_e32 v177, 0, v177, vcc
	v_cmp_gt_i32_e32 vcc, s28, v220
	s_nop 1
	v_cndmask_b32_e32 v196, 0, v196, vcc
	v_cndmask_b32_e32 v197, 0, v197, vcc
	v_pk_fma_f32 v[202:203], v[124:125], v[176:177], v[136:137]
	v_pk_fma_f32 v[140:141], v[140:141], v[128:129], v[202:203]
	v_pk_fma_f32 v[140:141], v[132:133], v[196:197], v[140:141]
	ds_read_b64 v[176:177], v244 offset:768
	ds_read_b64 v[196:197], v243 offset:784
	ds_read_b64 v[200:201], v246
	v_mul_f32_e32 v208, 0xbfb8aa3b, v162
	v_mul_f32_e32 v209, 0xbfb8aa3b, v163
	v_mul_f32_e32 v210, 0xbfb8aa3b, v164
	v_mul_f32_e32 v211, 0xbfb8aa3b, v165
	v_exp_f32_e32 v208, v208
	v_exp_f32_e32 v209, v209
	v_exp_f32_e32 v210, v210
	v_exp_f32_e32 v211, v211
	v_add_f32_e32 v208, 1.0, v208
	v_add_f32_e32 v209, 1.0, v209
	v_add_f32_e32 v210, 1.0, v210
	v_add_f32_e32 v211, 1.0, v211
	v_rcp_f32_e32 v208, v208
	v_rcp_f32_e32 v209, v209
	v_rcp_f32_e32 v210, v210
	v_rcp_f32_e32 v211, v211
	v_mul_f32_e32 v162, v162, v208
	v_mul_f32_e32 v163, v163, v209
	v_mul_f32_e32 v164, v164, v210
	v_mul_f32_e32 v165, v165, v211
	v_mul_f32_e32 v162, v166, v162
	v_mul_f32_e32 v163, v167, v163
	v_mul_f32_e32 v164, v168, v164
	v_mul_f32_e32 v165, v169, v165
	v_cvt_pk_bf16_f32 v38, v162, v163
	v_cvt_pk_bf16_f32 v39, v164, v165
	ds_bpermute_b32 v38, v250, v38
	ds_bpermute_b32 v39, v250, v39
	v_mul_f32_e32 v208, 0xbfb8aa3b, v154
	v_mul_f32_e32 v209, 0xbfb8aa3b, v155
	v_mul_f32_e32 v210, 0xbfb8aa3b, v156
	v_mul_f32_e32 v211, 0xbfb8aa3b, v157
	v_exp_f32_e32 v208, v208
	v_exp_f32_e32 v209, v209
	v_exp_f32_e32 v210, v210
	v_exp_f32_e32 v211, v211
	v_add_f32_e32 v208, 1.0, v208
	v_add_f32_e32 v209, 1.0, v209
	v_add_f32_e32 v210, 1.0, v210
	v_add_f32_e32 v211, 1.0, v211
	v_rcp_f32_e32 v208, v208
	v_rcp_f32_e32 v209, v209
	v_rcp_f32_e32 v210, v210
	v_rcp_f32_e32 v211, v211
	v_mul_f32_e32 v154, v154, v208
	v_mul_f32_e32 v155, v155, v209
	v_mul_f32_e32 v156, v156, v210
	v_mul_f32_e32 v157, v157, v211
	v_mul_f32_e32 v154, v158, v154
	v_mul_f32_e32 v155, v159, v155
	v_mul_f32_e32 v156, v160, v156
	v_mul_f32_e32 v157, v161, v157
	v_cvt_pk_bf16_f32 v40, v154, v155
	v_cvt_pk_bf16_f32 v41, v156, v157
	ds_bpermute_b32 v40, v250, v40
	ds_bpermute_b32 v41, v250, v41
	v_mul_f32_e32 v208, 0xbfb8aa3b, v146
	v_mul_f32_e32 v209, 0xbfb8aa3b, v147
	v_mul_f32_e32 v210, 0xbfb8aa3b, v148
	v_mul_f32_e32 v211, 0xbfb8aa3b, v149
	v_exp_f32_e32 v208, v208
	v_exp_f32_e32 v209, v209
	v_exp_f32_e32 v210, v210
	v_exp_f32_e32 v211, v211
	v_add_f32_e32 v208, 1.0, v208
	v_add_f32_e32 v209, 1.0, v209
	v_add_f32_e32 v210, 1.0, v210
	v_add_f32_e32 v211, 1.0, v211
	v_rcp_f32_e32 v208, v208
	v_rcp_f32_e32 v209, v209
	v_rcp_f32_e32 v210, v210
	v_rcp_f32_e32 v211, v211
	v_mul_f32_e32 v146, v146, v208
	v_mul_f32_e32 v147, v147, v209
	v_mul_f32_e32 v148, v148, v210
	v_mul_f32_e32 v149, v149, v211
	v_mul_f32_e32 v146, v150, v146
	v_mul_f32_e32 v147, v151, v147
	v_mul_f32_e32 v148, v152, v148
	v_mul_f32_e32 v149, v153, v149
	v_cvt_pk_bf16_f32 v212, v146, v147
	v_cvt_pk_bf16_f32 v213, v148, v149
	ds_bpermute_b32 v212, v250, v212
	ds_bpermute_b32 v213, v250, v213
	v_mul_f32_e32 v208, 0xbfb8aa3b, v138
	v_mul_f32_e32 v209, 0xbfb8aa3b, v139
	v_mul_f32_e32 v210, 0xbfb8aa3b, v140
	v_mul_f32_e32 v211, 0xbfb8aa3b, v141
	v_exp_f32_e32 v208, v208
	v_exp_f32_e32 v209, v209
	v_exp_f32_e32 v210, v210
	v_exp_f32_e32 v211, v211
	v_add_f32_e32 v208, 1.0, v208
	v_add_f32_e32 v209, 1.0, v209
	v_add_f32_e32 v210, 1.0, v210
	v_add_f32_e32 v211, 1.0, v211
	v_rcp_f32_e32 v208, v208
	v_rcp_f32_e32 v209, v209
	v_rcp_f32_e32 v210, v210
	v_rcp_f32_e32 v211, v211
	v_mul_f32_e32 v138, v138, v208
	v_mul_f32_e32 v139, v139, v209
	v_mul_f32_e32 v140, v140, v210
	v_mul_f32_e32 v141, v141, v211
	v_mul_f32_e32 v138, v142, v138
	v_mul_f32_e32 v139, v143, v139
	v_mul_f32_e32 v140, v144, v140
	v_mul_f32_e32 v141, v145, v141
	v_cvt_pk_bf16_f32 v218, v138, v139
	v_cvt_pk_bf16_f32 v219, v140, v141
	ds_bpermute_b32 v218, v250, v218
	ds_bpermute_b32 v219, v250, v219
	global_load_dwordx4 v[138:141], v248, s[62:63] offset:16
	global_load_dwordx4 v[142:145], v248, s[66:67] offset:16
	global_load_dwordx4 v[146:149], v248, s[68:69] offset:16
	global_load_dwordx4 v[150:153], v248, s[64:65] offset:16
	global_load_dwordx4 v[154:157], v249, s[62:63] offset:16
	global_load_dwordx4 v[158:161], v249, s[66:67] offset:16
	global_load_dwordx4 v[162:165], v249, s[68:69] offset:16
	global_load_dwordx4 v[166:169], v249, s[64:65] offset:16
	ds_write_b64 v243, v[104:105]
	ds_write_b64 v243, v[96:97] offset:256
	ds_write_b64 v243, v[88:89] offset:512
	ds_write_b64 v243, v[80:81] offset:768
	s_waitcnt lgkmcnt(15)
; #define PG8_LAS __attribute__((address_space(3)))
; __device__ __forceinline__ float dpp_ror1(float v) { return __builtin_bit_cast(float, __builtin_amdgcn_update_dpp(0, __builtin_bit_cast(int, v), 0x121, 0xf, 0xf, false)); }
; __device__ __forceinline__ float dpp_ror15(float v) { return __builtin_bit_cast(float, __builtin_amdgcn_update_dpp(0, __builtin_bit_cast(int, v), 0x12F, 0xf, 0xf, false)); }
;     __device__ __forceinline__ void operator()(const f32x4 (&acc)[2][2][4][2], const Unit& u, int wr, int wc, int fr, int fq) const {
;     ...
;                 for (int m = 0; m < 4; ++m) { const int r = 128 * ai + 64 * wr + 16 * m + fr, t = tstart + r;
;                     const bool upok = t >= 1, dnok = (t + 1) < T, store_ok = (r >= vlo) && (r < vhi) && (t < T);
;                     f32x4 res[2];
; #pragma unroll
;                     for (int bj = 0; bj < 2; ++bj) { const f32x4 cur = acc[ai][bj][m][n];
;                         f32x4 su = cur, sd = cur;
;                         if (m > 0) { if (fr == 15) su = acc[ai][bj][m > 0 ? m - 1 : 0][n]; }
;                         if (m < 3) { if (fr == 0) sd = acc[ai][bj][m < 3 ? m + 1 : 3][n]; }
;                         f32x4 up, dn;
;                         up[0] = dpp_ror1(su[0]); up[1] = dpp_ror1(su[1]); up[2] = dpp_ror1(su[2]); up[3] = dpp_ror1(su[3]);
;                         dn[0] = dpp_ror15(sd[0]); dn[1] = dpp_ror15(sd[1]); dn[2] = dpp_ror15(sd[2]); dn[3] = dpp_ror15(sd[3]);
;                         if (m == 0) { f32x4 halo = zero4; if (blk > 0) halo = *(const PG8_LAS f32x4*)(xb + (((((blk - 1) * 2 + 1) * 4 + wc) * 4 + fq) * 16 + (bj * 2 + n) * 4)); if (fr == 0) up = halo; }
;                         if (m == 3) { f32x4 halo = zero4; if (blk < 3) halo = *(const PG8_LAS f32x4*)(xb + (((((blk + 1) * 2 + 0) * 4 + wc) * 4 + fq) * 16 + (bj * 2 + n) * 4)); if (fr == 15) dn = halo; }
;                         if (edge) { if (!upok) up = zero4; if (!dnok) dn = zero4; }
;                         res[bj] = bb[bj] + w0[bj] * up + w1[bj] * cur + w2[bj] * dn; }
	v_cndmask_b32_e64 v170, v170, v198, s[6:7]
	v_cndmask_b32_e64 v171, v171, v199, s[6:7]
	v_add_u32_e32 v220, s48, v234
	v_cmp_lt_i32_e32 vcc, 0, v220
	s_nop 1
	v_cndmask_b32_e32 v170, 0, v170, vcc
	v_cndmask_b32_e32 v171, 0, v171, vcc
	v_cmp_gt_i32_e32 vcc, s28, v220
	s_nop 1
	v_cndmask_b32_e32 v178, 0, v178, vcc
	v_cndmask_b32_e32 v179, 0, v179, vcc
	v_pk_fma_f32 v[202:203], v[106:107], v[170:171], v[118:119]
	v_pk_fma_f32 v[102:103], v[102:103], v[110:111], v[202:203]
	v_pk_fma_f32 v[102:103], v[114:115], v[178:179], v[102:103]
	ds_read_b64 v[170:171], v244
	ds_read_b64 v[178:179], v243 offset:16
	ds_read_b64 v[198:199], v238 offset:3080
	v_add_u32_e32 v220, s48, v235
	v_cmp_lt_i32_e32 vcc, 0, v220
	s_nop 1
	v_cndmask_b32_e32 v172, 0, v172, vcc
	v_cndmask_b32_e32 v173, 0, v173, vcc
	v_cmp_gt_i32_e32 vcc, s28, v220
	s_nop 1
	v_cndmask_b32_e32 v180, 0, v180, vcc
	v_cndmask_b32_e32 v181, 0, v181, vcc
	v_pk_fma_f32 v[202:203], v[106:107], v[172:173], v[118:119]
	v_pk_fma_f32 v[94:95], v[94:95], v[110:111], v[202:203]
	v_pk_fma_f32 v[94:95], v[114:115], v[180:181], v[94:95]
	ds_read_b64 v[172:173], v244 offset:256
	ds_read_b64 v[180:181], v243 offset:272
	v_add_u32_e32 v220, s48, v236
	v_cmp_lt_i32_e32 vcc, 0, v220
	s_nop 1
	v_cndmask_b32_e32 v174, 0, v174, vcc
	v_cndmask_b32_e32 v175, 0, v175, vcc
	v_cmp_gt_i32_e32 vcc, s28, v220
	s_nop 1
	v_cndmask_b32_e32 v194, 0, v194, vcc
	v_cndmask_b32_e32 v195, 0, v195, vcc
	v_pk_fma_f32 v[202:203], v[106:107], v[174:175], v[118:119]
	v_pk_fma_f32 v[86:87], v[86:87], v[110:111], v[202:203]
	v_pk_fma_f32 v[86:87], v[114:115], v[194:195], v[86:87]
	ds_read_b64 v[174:175], v244 offset:512
	ds_read_b64 v[194:195], v243 offset:528
	s_waitcnt lgkmcnt(15)
	v_cndmask_b32_e64 v196, v196, v200, s[4:5]
	v_cndmask_b32_e64 v197, v197, v201, s[4:5]
	v_add_u32_e32 v220, s48, v237
	v_cmp_lt_i32_e32 vcc, 0, v220
	s_nop 1
	v_cndmask_b32_e32 v176, 0, v176, vcc
	v_cndmask_b32_e32 v177, 0, v177, vcc
	v_cmp_gt_i32_e32 vcc, s28, v220
	s_nop 1
	v_cndmask_b32_e32 v196, 0, v196, vcc
	v_cndmask_b32_e32 v197, 0, v197, vcc
	v_pk_fma_f32 v[202:203], v[106:107], v[176:177], v[118:119]
	v_pk_fma_f32 v[78:79], v[78:79], v[110:111], v[202:203]
	v_pk_fma_f32 v[78:79], v[114:115], v[196:197], v[78:79]
	ds_read_b64 v[176:177], v244 offset:768
	ds_read_b64 v[196:197], v243 offset:784
	ds_read_b64 v[200:201], v246 offset:8
	ds_write_b64 v243, v[98:99]
	ds_write_b64 v243, v[90:91] offset:256
	ds_write_b64 v243, v[82:83] offset:512
	ds_write_b64 v243, v[74:75] offset:768
	s_waitcnt lgkmcnt(11)
	v_cndmask_b32_e64 v170, v170, v198, s[6:7]
	v_cndmask_b32_e64 v171, v171, v199, s[6:7]
	v_add_u32_e32 v220, s48, v234
	v_cmp_lt_i32_e32 vcc, 0, v220
	s_nop 1
	v_cndmask_b32_e32 v170, 0, v170, vcc
	v_cndmask_b32_e32 v171, 0, v171, vcc
	v_cmp_gt_i32_e32 vcc, s28, v220
	s_nop 1
	v_cndmask_b32_e32 v178, 0, v178, vcc
	v_cndmask_b32_e32 v179, 0, v179, vcc
	v_pk_fma_f32 v[202:203], v[108:109], v[170:171], v[120:121]
	v_pk_fma_f32 v[104:105], v[104:105], v[112:113], v[202:203]
	v_pk_fma_f32 v[104:105], v[116:117], v[178:179], v[104:105]
	ds_read_b64 v[170:171], v244
	ds_read_b64 v[178:179], v243 offset:16
	ds_read_b64 v[198:199], v238 offset:3104
	s_waitcnt lgkmcnt(12)
	v_add_u32_e32 v220, s48, v235
	v_cmp_lt_i32_e32 vcc, 0, v220
	s_nop 1
	v_cndmask_b32_e32 v172, 0, v172, vcc
	v_cndmask_b32_e32 v173, 0, v173, vcc
	v_cmp_gt_i32_e32 vcc, s28, v220
	s_nop 1
	v_cndmask_b32_e32 v180, 0, v180, vcc
	v_cndmask_b32_e32 v181, 0, v181, vcc
	v_pk_fma_f32 v[202:203], v[108:109], v[172:173], v[120:121]
	v_pk_fma_f32 v[96:97], v[96:97], v[112:113], v[202:203]
	v_pk_fma_f32 v[96:97], v[116:117], v[180:181], v[96:97]
	ds_read_b64 v[172:173], v244 offset:256
	ds_read_b64 v[180:181], v243 offset:272
	s_waitcnt lgkmcnt(12)
	v_add_u32_e32 v220, s48, v236
	v_cmp_lt_i32_e32 vcc, 0, v220
	s_nop 1
	v_cndmask_b32_e32 v174, 0, v174, vcc
	v_cndmask_b32_e32 v175, 0, v175, vcc
	v_cmp_gt_i32_e32 vcc, s28, v220
	s_nop 1
	v_cndmask_b32_e32 v194, 0, v194, vcc
	v_cndmask_b32_e32 v195, 0, v195, vcc
	v_pk_fma_f32 v[202:203], v[108:109], v[174:175], v[120:121]
	v_pk_fma_f32 v[88:89], v[88:89], v[112:113], v[202:203]
	v_pk_fma_f32 v[88:89], v[116:117], v[194:195], v[88:89]
	ds_read_b64 v[174:175], v244 offset:512
	ds_read_b64 v[194:195], v243 offset:528
	s_waitcnt lgkmcnt(11)
	v_cndmask_b32_e64 v196, v196, v200, s[4:5]
	v_cndmask_b32_e64 v197, v197, v201, s[4:5]
	v_add_u32_e32 v220, s48, v237
	v_cmp_lt_i32_e32 vcc, 0, v220
	s_nop 1
	v_cndmask_b32_e32 v176, 0, v176, vcc
	v_cndmask_b32_e32 v177, 0, v177, vcc
	v_cmp_gt_i32_e32 vcc, s28, v220
	s_nop 1
	v_cndmask_b32_e32 v196, 0, v196, vcc
	v_cndmask_b32_e32 v197, 0, v197, vcc
	v_pk_fma_f32 v[202:203], v[108:109], v[176:177], v[120:121]
	v_pk_fma_f32 v[80:81], v[80:81], v[112:113], v[202:203]
	v_pk_fma_f32 v[80:81], v[116:117], v[196:197], v[80:81]
	ds_read_b64 v[176:177], v244 offset:768
	ds_read_b64 v[196:197], v243 offset:784
	ds_read_b64 v[200:201], v246 offset:32
	ds_write_b64 v243, v[100:101]
	ds_write_b64 v243, v[92:93] offset:256
	ds_write_b64 v243, v[84:85] offset:512
	ds_write_b64 v243, v[76:77] offset:768
	s_waitcnt lgkmcnt(11)
	v_cndmask_b32_e64 v170, v170, v198, s[6:7]
	v_cndmask_b32_e64 v171, v171, v199, s[6:7]
	v_add_u32_e32 v220, s48, v234
	v_cmp_lt_i32_e32 vcc, 0, v220
	s_nop 1
	v_cndmask_b32_e32 v170, 0, v170, vcc
	v_cndmask_b32_e32 v171, 0, v171, vcc
	v_cmp_gt_i32_e32 vcc, s28, v220
	s_nop 1
	v_cndmask_b32_e32 v178, 0, v178, vcc
	v_cndmask_b32_e32 v179, 0, v179, vcc
	v_pk_fma_f32 v[202:203], v[122:123], v[170:171], v[134:135]
	v_pk_fma_f32 v[98:99], v[98:99], v[126:127], v[202:203]
	v_pk_fma_f32 v[98:99], v[130:131], v[178:179], v[98:99]
	ds_read_b64 v[170:171], v244
	ds_read_b64 v[178:179], v243 offset:16
	ds_read_b64 v[198:199], v238 offset:3112
	s_waitcnt lgkmcnt(12)
; #define PG8_LAS __attribute__((address_space(3)))
; __device__ __forceinline__ unsigned cvt_pk_bf16(float lo, float hi) { unsigned r; asm volatile("v_cvt_pk_bf16_f32 %0, %1, %2" : "=v"(r) : "v"(lo), "v"(hi)); return r; }
;     __device__ __forceinline__ void operator()(const f32x4 (&acc)[2][2][4][2], const Unit& u, int wr, int wc, int fr, int fq) const {
;     ...
;                 for (int m = 0; m < 4; ++m) { const int r = 128 * ai + 64 * wr + 16 * m + fr, t = tstart + r;
;                     const bool upok = t >= 1, dnok = (t + 1) < T, store_ok = (r >= vlo) && (r < vhi) && (t < T);
;                     f32x4 res[2];
; #pragma unroll
;                     for (int bj = 0; bj < 2; ++bj) { const f32x4 cur = acc[ai][bj][m][n];
;                         f32x4 su = cur, sd = cur;
;                         if (m > 0) { if (fr == 15) su = acc[ai][bj][m > 0 ? m - 1 : 0][n]; }
;                         if (m < 3) { if (fr == 0) sd = acc[ai][bj][m < 3 ? m + 1 : 3][n]; }
;                         f32x4 up, dn;
;                         up[0] = dpp_ror1(su[0]); up[1] = dpp_ror1(su[1]); up[2] = dpp_ror1(su[2]); up[3] = dpp_ror1(su[3]);
;                         dn[0] = dpp_ror15(sd[0]); dn[1] = dpp_ror15(sd[1]); dn[2] = dpp_ror15(sd[2]); dn[3] = dpp_ror15(sd[3]);
;                         if (m == 0) { f32x4 halo = zero4; if (blk > 0) halo = *(const PG8_LAS f32x4*)(xb + (((((blk - 1) * 2 + 1) * 4 + wc) * 4 + fq) * 16 + (bj * 2 + n) * 4)); if (fr == 0) up = halo; }
;                         if (m == 3) { f32x4 halo = zero4; if (blk < 3) halo = *(const PG8_LAS f32x4*)(xb + (((((blk + 1) * 2 + 0) * 4 + wc) * 4 + fq) * 16 + (bj * 2 + n) * 4)); if (fr == 15) dn = halo; }
;                         if (edge) { if (!upok) up = zero4; if (!dnok) dn = zero4; }
;                         res[bj] = bb[bj] + w0[bj] * up + w1[bj] * cur + w2[bj] * dn; }
;                     if (store_ok) {
;                         float o[4];
; #pragma unroll
;                         for (int j = 0; j < 4; ++j) { const float gg = res[1][j]; o[j] = gg * __builtin_amdgcn_rcpf(1.f + __expf(-gg)) * res[0][j]; }
;                         u32x2 w; w.x = cvt_pk_bf16(o[0], o[1]); w.y = cvt_pk_bf16(o[2], o[3]);
;                         *(u32x2*)(ACT + (size_t)(seqrow + t) * 2816 + ch0 + 4 * n) = w; } } }
	v_add_u32_e32 v220, s48, v235
	v_cmp_lt_i32_e32 vcc, 0, v220
	s_nop 1
	v_cndmask_b32_e32 v172, 0, v172, vcc
	v_cndmask_b32_e32 v173, 0, v173, vcc
	v_cmp_gt_i32_e32 vcc, s28, v220
	s_nop 1
	v_cndmask_b32_e32 v180, 0, v180, vcc
	v_cndmask_b32_e32 v181, 0, v181, vcc
	v_pk_fma_f32 v[202:203], v[122:123], v[172:173], v[134:135]
	v_pk_fma_f32 v[90:91], v[90:91], v[126:127], v[202:203]
	v_pk_fma_f32 v[90:91], v[130:131], v[180:181], v[90:91]
	ds_read_b64 v[172:173], v244 offset:256
	ds_read_b64 v[180:181], v243 offset:272
	s_waitcnt lgkmcnt(12)
	v_add_u32_e32 v220, s48, v236
	v_cmp_lt_i32_e32 vcc, 0, v220
	s_nop 1
	v_cndmask_b32_e32 v174, 0, v174, vcc
	v_cndmask_b32_e32 v175, 0, v175, vcc
	v_cmp_gt_i32_e32 vcc, s28, v220
	s_nop 1
	v_cndmask_b32_e32 v194, 0, v194, vcc
	v_cndmask_b32_e32 v195, 0, v195, vcc
	v_pk_fma_f32 v[202:203], v[122:123], v[174:175], v[134:135]
	v_pk_fma_f32 v[82:83], v[82:83], v[126:127], v[202:203]
	v_pk_fma_f32 v[82:83], v[130:131], v[194:195], v[82:83]
	ds_read_b64 v[174:175], v244 offset:512
	ds_read_b64 v[194:195], v243 offset:528
	s_waitcnt lgkmcnt(11)
	v_cndmask_b32_e64 v196, v196, v200, s[4:5]
	v_cndmask_b32_e64 v197, v197, v201, s[4:5]
	v_add_u32_e32 v220, s48, v237
	v_cmp_lt_i32_e32 vcc, 0, v220
	s_nop 1
	v_cndmask_b32_e32 v176, 0, v176, vcc
	v_cndmask_b32_e32 v177, 0, v177, vcc
	v_cmp_gt_i32_e32 vcc, s28, v220
	s_nop 1
	v_cndmask_b32_e32 v196, 0, v196, vcc
	v_cndmask_b32_e32 v197, 0, v197, vcc
	v_pk_fma_f32 v[202:203], v[122:123], v[176:177], v[134:135]
	v_pk_fma_f32 v[74:75], v[74:75], v[126:127], v[202:203]
	v_pk_fma_f32 v[74:75], v[130:131], v[196:197], v[74:75]
	ds_read_b64 v[176:177], v244 offset:768
	ds_read_b64 v[196:197], v243 offset:784
	ds_read_b64 v[200:201], v246 offset:40
	ds_write_b64 v243, v[70:71]
	ds_write_b64 v243, v[62:63] offset:256
	ds_write_b64 v243, v[54:55] offset:512
	ds_write_b64 v243, v[46:47] offset:768
	s_waitcnt lgkmcnt(11)
	v_cndmask_b32_e64 v170, v170, v198, s[6:7]
	v_cndmask_b32_e64 v171, v171, v199, s[6:7]
	v_add_u32_e32 v220, s48, v234
	v_cmp_lt_i32_e32 vcc, 0, v220
	s_nop 1
	v_cndmask_b32_e32 v170, 0, v170, vcc
	v_cndmask_b32_e32 v171, 0, v171, vcc
	v_cmp_gt_i32_e32 vcc, s28, v220
	s_nop 1
	v_cndmask_b32_e32 v178, 0, v178, vcc
	v_cndmask_b32_e32 v179, 0, v179, vcc
	v_pk_fma_f32 v[202:203], v[124:125], v[170:171], v[136:137]
	v_pk_fma_f32 v[100:101], v[100:101], v[128:129], v[202:203]
	v_pk_fma_f32 v[100:101], v[132:133], v[178:179], v[100:101]
	ds_read_b64 v[170:171], v244
	ds_read_b64 v[178:179], v243 offset:16
	ds_read_b64 v[198:199], v245 offset:16
	s_waitcnt lgkmcnt(12)
	v_add_u32_e32 v220, s48, v235
	v_cmp_lt_i32_e32 vcc, 0, v220
	s_nop 1
	v_cndmask_b32_e32 v172, 0, v172, vcc
	v_cndmask_b32_e32 v173, 0, v173, vcc
	v_cmp_gt_i32_e32 vcc, s28, v220
	s_nop 1
	v_cndmask_b32_e32 v180, 0, v180, vcc
	v_cndmask_b32_e32 v181, 0, v181, vcc
	v_pk_fma_f32 v[202:203], v[124:125], v[172:173], v[136:137]
	v_pk_fma_f32 v[92:93], v[92:93], v[128:129], v[202:203]
	v_pk_fma_f32 v[92:93], v[132:133], v[180:181], v[92:93]
	ds_read_b64 v[172:173], v244 offset:256
	ds_read_b64 v[180:181], v243 offset:272
	s_waitcnt lgkmcnt(12)
	v_add_u32_e32 v220, s48, v236
	v_cmp_lt_i32_e32 vcc, 0, v220
	s_nop 1
	v_cndmask_b32_e32 v174, 0, v174, vcc
	v_cndmask_b32_e32 v175, 0, v175, vcc
	v_cmp_gt_i32_e32 vcc, s28, v220
	s_nop 1
	v_cndmask_b32_e32 v194, 0, v194, vcc
	v_cndmask_b32_e32 v195, 0, v195, vcc
	v_pk_fma_f32 v[202:203], v[124:125], v[174:175], v[136:137]
	v_pk_fma_f32 v[84:85], v[84:85], v[128:129], v[202:203]
	v_pk_fma_f32 v[84:85], v[132:133], v[194:195], v[84:85]
	ds_read_b64 v[174:175], v244 offset:512
	ds_read_b64 v[194:195], v243 offset:528
	s_waitcnt lgkmcnt(11)
	v_cndmask_b32_e64 v196, v196, v200, s[4:5]
	v_cndmask_b32_e64 v197, v197, v201, s[4:5]
	v_add_u32_e32 v220, s48, v237
	v_cmp_lt_i32_e32 vcc, 0, v220
	s_nop 1
	v_cndmask_b32_e32 v176, 0, v176, vcc
	v_cndmask_b32_e32 v177, 0, v177, vcc
	v_cmp_gt_i32_e32 vcc, s28, v220
	s_nop 1
	v_cndmask_b32_e32 v196, 0, v196, vcc
	v_cndmask_b32_e32 v197, 0, v197, vcc
	v_pk_fma_f32 v[202:203], v[124:125], v[176:177], v[136:137]
	v_pk_fma_f32 v[76:77], v[76:77], v[128:129], v[202:203]
	v_pk_fma_f32 v[76:77], v[132:133], v[196:197], v[76:77]
	ds_read_b64 v[176:177], v244 offset:768
	ds_read_b64 v[196:197], v243 offset:784
	ds_read_b64 v[200:201], v238 offset:2064
	v_mul_f32_e32 v208, 0xbfb8aa3b, v98
	v_mul_f32_e32 v209, 0xbfb8aa3b, v99
	v_mul_f32_e32 v210, 0xbfb8aa3b, v100
	v_mul_f32_e32 v211, 0xbfb8aa3b, v101
	v_exp_f32_e32 v208, v208
	v_exp_f32_e32 v209, v209
	v_exp_f32_e32 v210, v210
	v_exp_f32_e32 v211, v211
	v_add_f32_e32 v208, 1.0, v208
	v_add_f32_e32 v209, 1.0, v209
	v_add_f32_e32 v210, 1.0, v210
	v_add_f32_e32 v211, 1.0, v211
	v_rcp_f32_e32 v208, v208
	v_rcp_f32_e32 v209, v209
	v_rcp_f32_e32 v210, v210
	v_rcp_f32_e32 v211, v211
	v_mul_f32_e32 v98, v98, v208
	v_mul_f32_e32 v99, v99, v209
	v_mul_f32_e32 v100, v100, v210
	v_mul_f32_e32 v101, v101, v211
	v_mul_f32_e32 v98, v102, v98
	v_mul_f32_e32 v99, v103, v99
	v_mul_f32_e32 v100, v104, v100
	v_mul_f32_e32 v101, v105, v101
	v_cvt_pk_bf16_f32 v98, v98, v99
	v_cvt_pk_bf16_f32 v99, v100, v101
	ds_bpermute_b32 v98, v250, v98
	ds_bpermute_b32 v99, v250, v99
	v_mul_f32_e32 v208, 0xbfb8aa3b, v90
	v_mul_f32_e32 v209, 0xbfb8aa3b, v91
	v_mul_f32_e32 v210, 0xbfb8aa3b, v92
	v_mul_f32_e32 v211, 0xbfb8aa3b, v93
	v_exp_f32_e32 v208, v208
	v_exp_f32_e32 v209, v209
	v_exp_f32_e32 v210, v210
	v_exp_f32_e32 v211, v211
	v_add_f32_e32 v208, 1.0, v208
	v_add_f32_e32 v209, 1.0, v209
	v_add_f32_e32 v210, 1.0, v210
	v_add_f32_e32 v211, 1.0, v211
	v_rcp_f32_e32 v208, v208
	v_rcp_f32_e32 v209, v209
	v_rcp_f32_e32 v210, v210
; #define PG8_LAS __attribute__((address_space(3)))
; __device__ __forceinline__ unsigned cvt_pk_bf16(float lo, float hi) { unsigned r; asm volatile("v_cvt_pk_bf16_f32 %0, %1, %2" : "=v"(r) : "v"(lo), "v"(hi)); return r; }
;     __device__ __forceinline__ void operator()(const f32x4 (&acc)[2][2][4][2], const Unit& u, int wr, int wc, int fr, int fq) const {
;     ...
;                 for (int m = 0; m < 4; ++m) { const int r = 128 * ai + 64 * wr + 16 * m + fr, t = tstart + r;
;                     const bool upok = t >= 1, dnok = (t + 1) < T, store_ok = (r >= vlo) && (r < vhi) && (t < T);
;                     f32x4 res[2];
; #pragma unroll
;                     for (int bj = 0; bj < 2; ++bj) { const f32x4 cur = acc[ai][bj][m][n];
;                         f32x4 su = cur, sd = cur;
;                         if (m > 0) { if (fr == 15) su = acc[ai][bj][m > 0 ? m - 1 : 0][n]; }
;                         if (m < 3) { if (fr == 0) sd = acc[ai][bj][m < 3 ? m + 1 : 3][n]; }
;                         f32x4 up, dn;
;                         up[0] = dpp_ror1(su[0]); up[1] = dpp_ror1(su[1]); up[2] = dpp_ror1(su[2]); up[3] = dpp_ror1(su[3]);
;                         dn[0] = dpp_ror15(sd[0]); dn[1] = dpp_ror15(sd[1]); dn[2] = dpp_ror15(sd[2]); dn[3] = dpp_ror15(sd[3]);
;                         if (m == 0) { f32x4 halo = zero4; if (blk > 0) halo = *(const PG8_LAS f32x4*)(xb + (((((blk - 1) * 2 + 1) * 4 + wc) * 4 + fq) * 16 + (bj * 2 + n) * 4)); if (fr == 0) up = halo; }
;                         if (m == 3) { f32x4 halo = zero4; if (blk < 3) halo = *(const PG8_LAS f32x4*)(xb + (((((blk + 1) * 2 + 0) * 4 + wc) * 4 + fq) * 16 + (bj * 2 + n) * 4)); if (fr == 15) dn = halo; }
;                         if (edge) { if (!upok) up = zero4; if (!dnok) dn = zero4; }
;                         res[bj] = bb[bj] + w0[bj] * up + w1[bj] * cur + w2[bj] * dn; }
;                     if (store_ok) {
;                         float o[4];
; #pragma unroll
;                         for (int j = 0; j < 4; ++j) { const float gg = res[1][j]; o[j] = gg * __builtin_amdgcn_rcpf(1.f + __expf(-gg)) * res[0][j]; }
;                         u32x2 w; w.x = cvt_pk_bf16(o[0], o[1]); w.y = cvt_pk_bf16(o[2], o[3]);
;                         *(u32x2*)(ACT + (size_t)(seqrow + t) * 2816 + ch0 + 4 * n) = w; } } }
	v_rcp_f32_e32 v211, v211
	v_mul_f32_e32 v90, v90, v208
	v_mul_f32_e32 v91, v91, v209
	v_mul_f32_e32 v92, v92, v210
	v_mul_f32_e32 v93, v93, v211
	v_mul_f32_e32 v90, v94, v90
	v_mul_f32_e32 v91, v95, v91
	v_mul_f32_e32 v92, v96, v92
	v_mul_f32_e32 v93, v97, v93
	v_cvt_pk_bf16_f32 v90, v90, v91
	v_cvt_pk_bf16_f32 v91, v92, v93
	ds_bpermute_b32 v90, v250, v90
	ds_bpermute_b32 v91, v250, v91
	v_mul_f32_e32 v208, 0xbfb8aa3b, v82
	v_mul_f32_e32 v209, 0xbfb8aa3b, v83
	v_mul_f32_e32 v210, 0xbfb8aa3b, v84
	v_mul_f32_e32 v211, 0xbfb8aa3b, v85
	v_exp_f32_e32 v208, v208
	v_exp_f32_e32 v209, v209
	v_exp_f32_e32 v210, v210
	v_exp_f32_e32 v211, v211
	v_add_f32_e32 v208, 1.0, v208
	v_add_f32_e32 v209, 1.0, v209
	v_add_f32_e32 v210, 1.0, v210
	v_add_f32_e32 v211, 1.0, v211
	v_rcp_f32_e32 v208, v208
	v_rcp_f32_e32 v209, v209
	v_rcp_f32_e32 v210, v210
	v_rcp_f32_e32 v211, v211
	v_mul_f32_e32 v82, v82, v208
	v_mul_f32_e32 v83, v83, v209
	v_mul_f32_e32 v84, v84, v210
	v_mul_f32_e32 v85, v85, v211
	v_mul_f32_e32 v82, v86, v82
	v_mul_f32_e32 v83, v87, v83
	v_mul_f32_e32 v84, v88, v84
	v_mul_f32_e32 v85, v89, v85
	v_cvt_pk_bf16_f32 v82, v82, v83
	v_cvt_pk_bf16_f32 v83, v84, v85
	ds_bpermute_b32 v82, v250, v82
	ds_bpermute_b32 v83, v250, v83
	v_mul_f32_e32 v208, 0xbfb8aa3b, v74
	v_mul_f32_e32 v209, 0xbfb8aa3b, v75
	v_mul_f32_e32 v210, 0xbfb8aa3b, v76
	v_mul_f32_e32 v211, 0xbfb8aa3b, v77
	v_exp_f32_e32 v208, v208
	v_exp_f32_e32 v209, v209
	v_exp_f32_e32 v210, v210
	v_exp_f32_e32 v211, v211
	v_add_f32_e32 v208, 1.0, v208
	v_add_f32_e32 v209, 1.0, v209
	v_add_f32_e32 v210, 1.0, v210
	v_add_f32_e32 v211, 1.0, v211
	v_rcp_f32_e32 v208, v208
	v_rcp_f32_e32 v209, v209
	v_rcp_f32_e32 v210, v210
	v_rcp_f32_e32 v211, v211
	v_mul_f32_e32 v74, v74, v208
	v_mul_f32_e32 v75, v75, v209
	v_mul_f32_e32 v76, v76, v210
	v_mul_f32_e32 v77, v77, v211
	v_mul_f32_e32 v74, v78, v74
	v_mul_f32_e32 v75, v79, v75
	v_mul_f32_e32 v76, v80, v76
	v_mul_f32_e32 v77, v81, v77
	v_cvt_pk_bf16_f32 v74, v74, v75
	v_cvt_pk_bf16_f32 v75, v76, v77
	ds_bpermute_b32 v74, v250, v74
	ds_bpermute_b32 v75, v250, v75
	v_mov_b32_e32 v102, v38
	v_mov_b32_e32 v103, v39
	v_mov_b32_e32 v94, v40
	v_mov_b32_e32 v95, v41
	v_mov_b32_e32 v86, v212
	v_mov_b32_e32 v87, v213
	v_mov_b32_e32 v78, v218
	v_mov_b32_e32 v79, v219
	s_waitcnt vmcnt(0)
	ds_write_b64 v243, v[72:73]
	ds_write_b64 v243, v[64:65] offset:256
	ds_write_b64 v243, v[56:57] offset:512
	ds_write_b64 v243, v[48:49] offset:768
	s_waitcnt lgkmcnt(15)
	v_cndmask_b32_e64 v170, v170, v198, s[6:7]
	v_cndmask_b32_e64 v171, v171, v199, s[6:7]
	v_add_u32_e32 v220, s48, v227
	v_cmp_lt_i32_e32 vcc, 0, v220
	s_nop 1
	v_cndmask_b32_e32 v170, 0, v170, vcc
	v_cndmask_b32_e32 v171, 0, v171, vcc
	v_cmp_gt_i32_e32 vcc, s28, v220
	s_nop 1
	v_cndmask_b32_e32 v178, 0, v178, vcc
	v_cndmask_b32_e32 v179, 0, v179, vcc
	v_pk_fma_f32 v[202:203], v[138:139], v[170:171], v[150:151]
	v_pk_fma_f32 v[70:71], v[70:71], v[142:143], v[202:203]
	v_pk_fma_f32 v[70:71], v[146:147], v[178:179], v[70:71]
	ds_read_b64 v[170:171], v244
	ds_read_b64 v[178:179], v243 offset:16
	ds_read_b64 v[198:199], v245 offset:24
	v_add_u32_e32 v220, s48, v231
	v_cmp_lt_i32_e32 vcc, 0, v220
	s_nop 1
	v_cndmask_b32_e32 v172, 0, v172, vcc
	v_cndmask_b32_e32 v173, 0, v173, vcc
	v_cmp_gt_i32_e32 vcc, s28, v220
	s_nop 1
	v_cndmask_b32_e32 v180, 0, v180, vcc
	v_cndmask_b32_e32 v181, 0, v181, vcc
	v_pk_fma_f32 v[202:203], v[138:139], v[172:173], v[150:151]
	v_pk_fma_f32 v[62:63], v[62:63], v[142:143], v[202:203]
	v_pk_fma_f32 v[62:63], v[146:147], v[180:181], v[62:63]
	ds_read_b64 v[172:173], v244 offset:256
	ds_read_b64 v[180:181], v243 offset:272
	v_add_u32_e32 v220, s48, v232
	v_cmp_lt_i32_e32 vcc, 0, v220
	s_nop 1
	v_cndmask_b32_e32 v174, 0, v174, vcc
	v_cndmask_b32_e32 v175, 0, v175, vcc
	v_cmp_gt_i32_e32 vcc, s28, v220
	s_nop 1
	v_cndmask_b32_e32 v194, 0, v194, vcc
	v_cndmask_b32_e32 v195, 0, v195, vcc
	v_pk_fma_f32 v[202:203], v[138:139], v[174:175], v[150:151]
	v_pk_fma_f32 v[54:55], v[54:55], v[142:143], v[202:203]
	v_pk_fma_f32 v[54:55], v[146:147], v[194:195], v[54:55]
	ds_read_b64 v[174:175], v244 offset:512
	ds_read_b64 v[194:195], v243 offset:528
	s_waitcnt lgkmcnt(15)
	v_cndmask_b32_e64 v196, v196, v200, s[4:5]
	v_cndmask_b32_e64 v197, v197, v201, s[4:5]
	v_add_u32_e32 v220, s48, v233
	v_cmp_lt_i32_e32 vcc, 0, v220
	s_nop 1
	v_cndmask_b32_e32 v176, 0, v176, vcc
	v_cndmask_b32_e32 v177, 0, v177, vcc
	v_cmp_gt_i32_e32 vcc, s28, v220
	s_nop 1
	v_cndmask_b32_e32 v196, 0, v196, vcc
	v_cndmask_b32_e32 v197, 0, v197, vcc
	v_pk_fma_f32 v[202:203], v[138:139], v[176:177], v[150:151]
	v_pk_fma_f32 v[46:47], v[46:47], v[142:143], v[202:203]
	v_pk_fma_f32 v[46:47], v[146:147], v[196:197], v[46:47]
	ds_read_b64 v[176:177], v244 offset:768
	ds_read_b64 v[196:197], v243 offset:784
	ds_read_b64 v[200:201], v238 offset:2072
	ds_write_b64 v243, v[66:67]
	ds_write_b64 v243, v[58:59] offset:256
	ds_write_b64 v243, v[50:51] offset:512
	ds_write_b64 v243, v[42:43] offset:768
	s_waitcnt lgkmcnt(11)
	v_cndmask_b32_e64 v170, v170, v198, s[6:7]
	v_cndmask_b32_e64 v171, v171, v199, s[6:7]
	v_add_u32_e32 v220, s48, v227
	v_cmp_lt_i32_e32 vcc, 0, v220
	s_nop 1
	v_cndmask_b32_e32 v170, 0, v170, vcc
	v_cndmask_b32_e32 v171, 0, v171, vcc
	v_cmp_gt_i32_e32 vcc, s28, v220
	s_nop 1
	v_cndmask_b32_e32 v178, 0, v178, vcc
	v_cndmask_b32_e32 v179, 0, v179, vcc
	v_pk_fma_f32 v[202:203], v[140:141], v[170:171], v[152:153]
	v_pk_fma_f32 v[72:73], v[72:73], v[144:145], v[202:203]
	v_pk_fma_f32 v[72:73], v[148:149], v[178:179], v[72:73]
	ds_read_b64 v[170:171], v244
	ds_read_b64 v[178:179], v243 offset:16
	ds_read_b64 v[198:199], v245 offset:48
	s_waitcnt lgkmcnt(12)
; #define PG8_LAS __attribute__((address_space(3)))
; __device__ __forceinline__ float dpp_ror1(float v) { return __builtin_bit_cast(float, __builtin_amdgcn_update_dpp(0, __builtin_bit_cast(int, v), 0x121, 0xf, 0xf, false)); }
; __device__ __forceinline__ float dpp_ror15(float v) { return __builtin_bit_cast(float, __builtin_amdgcn_update_dpp(0, __builtin_bit_cast(int, v), 0x12F, 0xf, 0xf, false)); }
;     __device__ __forceinline__ void operator()(const f32x4 (&acc)[2][2][4][2], const Unit& u, int wr, int wc, int fr, int fq) const {
;     ...
;                 for (int m = 0; m < 4; ++m) { const int r = 128 * ai + 64 * wr + 16 * m + fr, t = tstart + r;
;                     const bool upok = t >= 1, dnok = (t + 1) < T, store_ok = (r >= vlo) && (r < vhi) && (t < T);
;                     f32x4 res[2];
; #pragma unroll
;                     for (int bj = 0; bj < 2; ++bj) { const f32x4 cur = acc[ai][bj][m][n];
;                         f32x4 su = cur, sd = cur;
;                         if (m > 0) { if (fr == 15) su = acc[ai][bj][m > 0 ? m - 1 : 0][n]; }
;                         if (m < 3) { if (fr == 0) sd = acc[ai][bj][m < 3 ? m + 1 : 3][n]; }
;                         f32x4 up, dn;
;                         up[0] = dpp_ror1(su[0]); up[1] = dpp_ror1(su[1]); up[2] = dpp_ror1(su[2]); up[3] = dpp_ror1(su[3]);
;                         dn[0] = dpp_ror15(sd[0]); dn[1] = dpp_ror15(sd[1]); dn[2] = dpp_ror15(sd[2]); dn[3] = dpp_ror15(sd[3]);
;                         if (m == 0) { f32x4 halo = zero4; if (blk > 0) halo = *(const PG8_LAS f32x4*)(xb + (((((blk - 1) * 2 + 1) * 4 + wc) * 4 + fq) * 16 + (bj * 2 + n) * 4)); if (fr == 0) up = halo; }
;                         if (m == 3) { f32x4 halo = zero4; if (blk < 3) halo = *(const PG8_LAS f32x4*)(xb + (((((blk + 1) * 2 + 0) * 4 + wc) * 4 + fq) * 16 + (bj * 2 + n) * 4)); if (fr == 15) dn = halo; }
;                         if (edge) { if (!upok) up = zero4; if (!dnok) dn = zero4; }
;                         res[bj] = bb[bj] + w0[bj] * up + w1[bj] * cur + w2[bj] * dn; }
	v_add_u32_e32 v220, s48, v231
	v_cmp_lt_i32_e32 vcc, 0, v220
	s_nop 1
	v_cndmask_b32_e32 v172, 0, v172, vcc
	v_cndmask_b32_e32 v173, 0, v173, vcc
	v_cmp_gt_i32_e32 vcc, s28, v220
	s_nop 1
	v_cndmask_b32_e32 v180, 0, v180, vcc
	v_cndmask_b32_e32 v181, 0, v181, vcc
	v_pk_fma_f32 v[202:203], v[140:141], v[172:173], v[152:153]
	v_pk_fma_f32 v[64:65], v[64:65], v[144:145], v[202:203]
	v_pk_fma_f32 v[64:65], v[148:149], v[180:181], v[64:65]
	ds_read_b64 v[172:173], v244 offset:256
	ds_read_b64 v[180:181], v243 offset:272
	s_waitcnt lgkmcnt(12)
	v_add_u32_e32 v220, s48, v232
	v_cmp_lt_i32_e32 vcc, 0, v220
	s_nop 1
	v_cndmask_b32_e32 v174, 0, v174, vcc
	v_cndmask_b32_e32 v175, 0, v175, vcc
	v_cmp_gt_i32_e32 vcc, s28, v220
	s_nop 1
	v_cndmask_b32_e32 v194, 0, v194, vcc
	v_cndmask_b32_e32 v195, 0, v195, vcc
	v_pk_fma_f32 v[202:203], v[140:141], v[174:175], v[152:153]
	v_pk_fma_f32 v[56:57], v[56:57], v[144:145], v[202:203]
	v_pk_fma_f32 v[56:57], v[148:149], v[194:195], v[56:57]
	ds_read_b64 v[174:175], v244 offset:512
	ds_read_b64 v[194:195], v243 offset:528
	s_waitcnt lgkmcnt(11)
	v_cndmask_b32_e64 v196, v196, v200, s[4:5]
	v_cndmask_b32_e64 v197, v197, v201, s[4:5]
	v_add_u32_e32 v220, s48, v233
	v_cmp_lt_i32_e32 vcc, 0, v220
	s_nop 1
	v_cndmask_b32_e32 v176, 0, v176, vcc
	v_cndmask_b32_e32 v177, 0, v177, vcc
	v_cmp_gt_i32_e32 vcc, s28, v220
	s_nop 1
	v_cndmask_b32_e32 v196, 0, v196, vcc
	v_cndmask_b32_e32 v197, 0, v197, vcc
	v_pk_fma_f32 v[202:203], v[140:141], v[176:177], v[152:153]
	v_pk_fma_f32 v[48:49], v[48:49], v[144:145], v[202:203]
	v_pk_fma_f32 v[48:49], v[148:149], v[196:197], v[48:49]
	ds_read_b64 v[176:177], v244 offset:768
	ds_read_b64 v[196:197], v243 offset:784
	ds_read_b64 v[200:201], v238 offset:2096
	ds_write_b64 v243, v[68:69]
	ds_write_b64 v243, v[60:61] offset:256
	ds_write_b64 v243, v[52:53] offset:512
	ds_write_b64 v243, v[44:45] offset:768
	s_waitcnt lgkmcnt(11)
	v_cndmask_b32_e64 v170, v170, v198, s[6:7]
	v_cndmask_b32_e64 v171, v171, v199, s[6:7]
	v_add_u32_e32 v220, s48, v227
	v_cmp_lt_i32_e32 vcc, 0, v220
	s_nop 1
	v_cndmask_b32_e32 v170, 0, v170, vcc
	v_cndmask_b32_e32 v171, 0, v171, vcc
	v_cmp_gt_i32_e32 vcc, s28, v220
	s_nop 1
	v_cndmask_b32_e32 v178, 0, v178, vcc
	v_cndmask_b32_e32 v179, 0, v179, vcc
	v_pk_fma_f32 v[202:203], v[154:155], v[170:171], v[166:167]
	v_pk_fma_f32 v[66:67], v[66:67], v[158:159], v[202:203]
	v_pk_fma_f32 v[66:67], v[162:163], v[178:179], v[66:67]
	ds_read_b64 v[170:171], v244
	ds_read_b64 v[178:179], v243 offset:16
	ds_read_b64 v[198:199], v245 offset:56
	s_waitcnt lgkmcnt(12)
	v_add_u32_e32 v220, s48, v231
	v_cmp_lt_i32_e32 vcc, 0, v220
	s_nop 1
	v_cndmask_b32_e32 v172, 0, v172, vcc
	v_cndmask_b32_e32 v173, 0, v173, vcc
	v_cmp_gt_i32_e32 vcc, s28, v220
	s_nop 1
	v_cndmask_b32_e32 v180, 0, v180, vcc
	v_cndmask_b32_e32 v181, 0, v181, vcc
	v_pk_fma_f32 v[202:203], v[154:155], v[172:173], v[166:167]
	v_pk_fma_f32 v[58:59], v[58:59], v[158:159], v[202:203]
	v_pk_fma_f32 v[58:59], v[162:163], v[180:181], v[58:59]
	ds_read_b64 v[172:173], v244 offset:256
	ds_read_b64 v[180:181], v243 offset:272
	s_waitcnt lgkmcnt(12)
	v_add_u32_e32 v220, s48, v232
	v_cmp_lt_i32_e32 vcc, 0, v220
	s_nop 1
	v_cndmask_b32_e32 v174, 0, v174, vcc
	v_cndmask_b32_e32 v175, 0, v175, vcc
	v_cmp_gt_i32_e32 vcc, s28, v220
	s_nop 1
	v_cndmask_b32_e32 v194, 0, v194, vcc
	v_cndmask_b32_e32 v195, 0, v195, vcc
	v_pk_fma_f32 v[202:203], v[154:155], v[174:175], v[166:167]
	v_pk_fma_f32 v[50:51], v[50:51], v[158:159], v[202:203]
	v_pk_fma_f32 v[50:51], v[162:163], v[194:195], v[50:51]
	ds_read_b64 v[174:175], v244 offset:512
	ds_read_b64 v[194:195], v243 offset:528
	s_waitcnt lgkmcnt(11)
	v_cndmask_b32_e64 v196, v196, v200, s[4:5]
	v_cndmask_b32_e64 v197, v197, v201, s[4:5]
	v_add_u32_e32 v220, s48, v233
	v_cmp_lt_i32_e32 vcc, 0, v220
	s_nop 1
	v_cndmask_b32_e32 v176, 0, v176, vcc
	v_cndmask_b32_e32 v177, 0, v177, vcc
	v_cmp_gt_i32_e32 vcc, s28, v220
	s_nop 1
	v_cndmask_b32_e32 v196, 0, v196, vcc
	v_cndmask_b32_e32 v197, 0, v197, vcc
	v_pk_fma_f32 v[202:203], v[154:155], v[176:177], v[166:167]
	v_pk_fma_f32 v[42:43], v[42:43], v[158:159], v[202:203]
	v_pk_fma_f32 v[42:43], v[162:163], v[196:197], v[42:43]
	ds_read_b64 v[176:177], v244 offset:768
	ds_read_b64 v[196:197], v243 offset:784
	ds_read_b64 v[200:201], v238 offset:2104
	ds_write_b64 v243, v[30:31]
	ds_write_b64 v243, v[22:23] offset:256
	ds_write_b64 v243, v[14:15] offset:512
	ds_write_b64 v243, v[6:7] offset:768
	s_waitcnt lgkmcnt(11)
	v_cndmask_b32_e64 v170, v170, v198, s[6:7]
	v_cndmask_b32_e64 v171, v171, v199, s[6:7]
	v_add_u32_e32 v220, s48, v227
	v_cmp_lt_i32_e32 vcc, 0, v220
	s_nop 1
	v_cndmask_b32_e32 v170, 0, v170, vcc
	v_cndmask_b32_e32 v171, 0, v171, vcc
	v_cmp_gt_i32_e32 vcc, s28, v220
	s_nop 1
	v_cndmask_b32_e32 v178, 0, v178, vcc
	v_cndmask_b32_e32 v179, 0, v179, vcc
	v_pk_fma_f32 v[202:203], v[156:157], v[170:171], v[168:169]
	v_pk_fma_f32 v[68:69], v[68:69], v[160:161], v[202:203]
	v_pk_fma_f32 v[68:69], v[164:165], v[178:179], v[68:69]
	ds_read_b64 v[170:171], v244
	ds_read_b64 v[178:179], v243 offset:16
	ds_read_b64 v[198:199], v238 offset:3088
	s_waitcnt lgkmcnt(12)
	v_add_u32_e32 v220, s48, v231
	v_cmp_lt_i32_e32 vcc, 0, v220
	s_nop 1
	v_cndmask_b32_e32 v172, 0, v172, vcc
	v_cndmask_b32_e32 v173, 0, v173, vcc
	v_cmp_gt_i32_e32 vcc, s28, v220
	s_nop 1
	v_cndmask_b32_e32 v180, 0, v180, vcc
	v_cndmask_b32_e32 v181, 0, v181, vcc
	v_pk_fma_f32 v[202:203], v[156:157], v[172:173], v[168:169]
	v_pk_fma_f32 v[60:61], v[60:61], v[160:161], v[202:203]
	v_pk_fma_f32 v[60:61], v[164:165], v[180:181], v[60:61]
	ds_read_b64 v[172:173], v244 offset:256
	ds_read_b64 v[180:181], v243 offset:272
	s_waitcnt lgkmcnt(12)
; #define PG8_LAS __attribute__((address_space(3)))
; __device__ __forceinline__ unsigned cvt_pk_bf16(float lo, float hi) { unsigned r; asm volatile("v_cvt_pk_bf16_f32 %0, %1, %2" : "=v"(r) : "v"(lo), "v"(hi)); return r; }
;     __device__ __forceinline__ void operator()(const f32x4 (&acc)[2][2][4][2], const Unit& u, int wr, int wc, int fr, int fq) const {
;     ...
;                 for (int m = 0; m < 4; ++m) { const int r = 128 * ai + 64 * wr + 16 * m + fr, t = tstart + r;
;                     const bool upok = t >= 1, dnok = (t + 1) < T, store_ok = (r >= vlo) && (r < vhi) && (t < T);
;                     f32x4 res[2];
; #pragma unroll
;                     for (int bj = 0; bj < 2; ++bj) { const f32x4 cur = acc[ai][bj][m][n];
;                         f32x4 su = cur, sd = cur;
;                         if (m > 0) { if (fr == 15) su = acc[ai][bj][m > 0 ? m - 1 : 0][n]; }
;                         if (m < 3) { if (fr == 0) sd = acc[ai][bj][m < 3 ? m + 1 : 3][n]; }
;                         f32x4 up, dn;
;                         up[0] = dpp_ror1(su[0]); up[1] = dpp_ror1(su[1]); up[2] = dpp_ror1(su[2]); up[3] = dpp_ror1(su[3]);
;                         dn[0] = dpp_ror15(sd[0]); dn[1] = dpp_ror15(sd[1]); dn[2] = dpp_ror15(sd[2]); dn[3] = dpp_ror15(sd[3]);
;                         if (m == 0) { f32x4 halo = zero4; if (blk > 0) halo = *(const PG8_LAS f32x4*)(xb + (((((blk - 1) * 2 + 1) * 4 + wc) * 4 + fq) * 16 + (bj * 2 + n) * 4)); if (fr == 0) up = halo; }
;                         if (m == 3) { f32x4 halo = zero4; if (blk < 3) halo = *(const PG8_LAS f32x4*)(xb + (((((blk + 1) * 2 + 0) * 4 + wc) * 4 + fq) * 16 + (bj * 2 + n) * 4)); if (fr == 15) dn = halo; }
;                         if (edge) { if (!upok) up = zero4; if (!dnok) dn = zero4; }
;                         res[bj] = bb[bj] + w0[bj] * up + w1[bj] * cur + w2[bj] * dn; }
;                     if (store_ok) {
;                         float o[4];
; #pragma unroll
;                         for (int j = 0; j < 4; ++j) { const float gg = res[1][j]; o[j] = gg * __builtin_amdgcn_rcpf(1.f + __expf(-gg)) * res[0][j]; }
;                         u32x2 w; w.x = cvt_pk_bf16(o[0], o[1]); w.y = cvt_pk_bf16(o[2], o[3]);
;                         *(u32x2*)(ACT + (size_t)(seqrow + t) * 2816 + ch0 + 4 * n) = w; } } }
	v_add_u32_e32 v220, s48, v232
	v_cmp_lt_i32_e32 vcc, 0, v220
	s_nop 1
	v_cndmask_b32_e32 v174, 0, v174, vcc
	v_cndmask_b32_e32 v175, 0, v175, vcc
	v_cmp_gt_i32_e32 vcc, s28, v220
	s_nop 1
	v_cndmask_b32_e32 v194, 0, v194, vcc
	v_cndmask_b32_e32 v195, 0, v195, vcc
	v_pk_fma_f32 v[202:203], v[156:157], v[174:175], v[168:169]
	v_pk_fma_f32 v[52:53], v[52:53], v[160:161], v[202:203]
	v_pk_fma_f32 v[52:53], v[164:165], v[194:195], v[52:53]
	ds_read_b64 v[174:175], v244 offset:512
	ds_read_b64 v[194:195], v243 offset:528
	s_waitcnt lgkmcnt(11)
	v_cndmask_b32_e64 v196, v196, v200, s[4:5]
	v_cndmask_b32_e64 v197, v197, v201, s[4:5]
	v_add_u32_e32 v220, s48, v233
	v_cmp_lt_i32_e32 vcc, 0, v220
	s_nop 1
	v_cndmask_b32_e32 v176, 0, v176, vcc
	v_cndmask_b32_e32 v177, 0, v177, vcc
	v_cmp_gt_i32_e32 vcc, s28, v220
	s_nop 1
	v_cndmask_b32_e32 v196, 0, v196, vcc
	v_cndmask_b32_e32 v197, 0, v197, vcc
	v_pk_fma_f32 v[202:203], v[156:157], v[176:177], v[168:169]
	v_pk_fma_f32 v[44:45], v[44:45], v[160:161], v[202:203]
	v_pk_fma_f32 v[44:45], v[164:165], v[196:197], v[44:45]
	ds_read_b64 v[176:177], v244 offset:768
	ds_read_b64 v[196:197], v243 offset:784
	ds_read_b64 v[200:201], v246 offset:16
	v_mul_f32_e32 v208, 0xbfb8aa3b, v66
	v_mul_f32_e32 v209, 0xbfb8aa3b, v67
	v_mul_f32_e32 v210, 0xbfb8aa3b, v68
	v_mul_f32_e32 v211, 0xbfb8aa3b, v69
	v_exp_f32_e32 v208, v208
	v_exp_f32_e32 v209, v209
	v_exp_f32_e32 v210, v210
	v_exp_f32_e32 v211, v211
	v_add_f32_e32 v208, 1.0, v208
	v_add_f32_e32 v209, 1.0, v209
	v_add_f32_e32 v210, 1.0, v210
	v_add_f32_e32 v211, 1.0, v211
	v_rcp_f32_e32 v208, v208
	v_rcp_f32_e32 v209, v209
	v_rcp_f32_e32 v210, v210
	v_rcp_f32_e32 v211, v211
	v_mul_f32_e32 v66, v66, v208
	v_mul_f32_e32 v67, v67, v209
	v_mul_f32_e32 v68, v68, v210
	v_mul_f32_e32 v69, v69, v211
	v_mul_f32_e32 v66, v70, v66
	v_mul_f32_e32 v67, v71, v67
	v_mul_f32_e32 v68, v72, v68
	v_mul_f32_e32 v69, v73, v69
	v_cvt_pk_bf16_f32 v66, v66, v67
	v_cvt_pk_bf16_f32 v67, v68, v69
	ds_bpermute_b32 v104, v250, v66
	ds_bpermute_b32 v105, v250, v67
	v_mul_f32_e32 v208, 0xbfb8aa3b, v58
	v_mul_f32_e32 v209, 0xbfb8aa3b, v59
	v_mul_f32_e32 v210, 0xbfb8aa3b, v60
	v_mul_f32_e32 v211, 0xbfb8aa3b, v61
	v_exp_f32_e32 v208, v208
	v_exp_f32_e32 v209, v209
	v_exp_f32_e32 v210, v210
	v_exp_f32_e32 v211, v211
	v_add_f32_e32 v208, 1.0, v208
	v_add_f32_e32 v209, 1.0, v209
	v_add_f32_e32 v210, 1.0, v210
	v_add_f32_e32 v211, 1.0, v211
	v_rcp_f32_e32 v208, v208
	v_rcp_f32_e32 v209, v209
	v_rcp_f32_e32 v210, v210
	v_rcp_f32_e32 v211, v211
	v_mul_f32_e32 v58, v58, v208
	v_mul_f32_e32 v59, v59, v209
	v_mul_f32_e32 v60, v60, v210
	v_mul_f32_e32 v61, v61, v211
	v_mul_f32_e32 v58, v62, v58
	v_mul_f32_e32 v59, v63, v59
	v_mul_f32_e32 v60, v64, v60
	v_mul_f32_e32 v61, v65, v61
	v_cvt_pk_bf16_f32 v58, v58, v59
	v_cvt_pk_bf16_f32 v59, v60, v61
	ds_bpermute_b32 v96, v250, v58
	ds_bpermute_b32 v97, v250, v59
	v_mul_f32_e32 v208, 0xbfb8aa3b, v50
	v_mul_f32_e32 v209, 0xbfb8aa3b, v51
	v_mul_f32_e32 v210, 0xbfb8aa3b, v52
	v_mul_f32_e32 v211, 0xbfb8aa3b, v53
	v_exp_f32_e32 v208, v208
	v_exp_f32_e32 v209, v209
	v_exp_f32_e32 v210, v210
	v_exp_f32_e32 v211, v211
	v_add_f32_e32 v208, 1.0, v208
	v_add_f32_e32 v209, 1.0, v209
	v_add_f32_e32 v210, 1.0, v210
	v_add_f32_e32 v211, 1.0, v211
	v_rcp_f32_e32 v208, v208
	v_rcp_f32_e32 v209, v209
	v_rcp_f32_e32 v210, v210
	v_rcp_f32_e32 v211, v211
	v_mul_f32_e32 v50, v50, v208
	v_mul_f32_e32 v51, v51, v209
	v_mul_f32_e32 v52, v52, v210
	v_mul_f32_e32 v53, v53, v211
	v_mul_f32_e32 v50, v54, v50
	v_mul_f32_e32 v51, v55, v51
	v_mul_f32_e32 v52, v56, v52
	v_mul_f32_e32 v53, v57, v53
	v_cvt_pk_bf16_f32 v50, v50, v51
	v_cvt_pk_bf16_f32 v51, v52, v53
	ds_bpermute_b32 v88, v250, v50
	ds_bpermute_b32 v89, v250, v51
	v_mul_f32_e32 v208, 0xbfb8aa3b, v42
	v_mul_f32_e32 v209, 0xbfb8aa3b, v43
	v_mul_f32_e32 v210, 0xbfb8aa3b, v44
	v_mul_f32_e32 v211, 0xbfb8aa3b, v45
	v_exp_f32_e32 v208, v208
	v_exp_f32_e32 v209, v209
	v_exp_f32_e32 v210, v210
	v_exp_f32_e32 v211, v211
	v_add_f32_e32 v208, 1.0, v208
	v_add_f32_e32 v209, 1.0, v209
	v_add_f32_e32 v210, 1.0, v210
	v_add_f32_e32 v211, 1.0, v211
	v_rcp_f32_e32 v208, v208
	v_rcp_f32_e32 v209, v209
	v_rcp_f32_e32 v210, v210
	v_rcp_f32_e32 v211, v211
	v_mul_f32_e32 v42, v42, v208
	v_mul_f32_e32 v43, v43, v209
	v_mul_f32_e32 v44, v44, v210
	v_mul_f32_e32 v45, v45, v211
	v_mul_f32_e32 v42, v46, v42
	v_mul_f32_e32 v43, v47, v43
	v_mul_f32_e32 v44, v48, v44
	v_mul_f32_e32 v45, v49, v45
	v_cvt_pk_bf16_f32 v42, v42, v43
	v_cvt_pk_bf16_f32 v43, v44, v45
	ds_bpermute_b32 v80, v250, v42
	ds_bpermute_b32 v81, v250, v43
	s_waitcnt lgkmcnt(6)
	v_add_u32_e32 v221, 0x0, v247
	s_and_saveexec_b64 s[30:31], s[12:13]
	global_store_dwordx4 v221, v[102:105], s[10:11]
	s_mov_b64 exec, s[30:31]
	s_waitcnt lgkmcnt(4)
	v_add_u32_e32 v251, 0x16000, v247
	s_and_saveexec_b64 s[30:31], s[14:15]
	global_store_dwordx4 v251, v[94:97], s[10:11]
	s_mov_b64 exec, s[30:31]
	s_waitcnt lgkmcnt(2)
	v_add_u32_e32 v221, 0x2c000, v247
	s_and_saveexec_b64 s[30:31], s[16:17]
	global_store_dwordx4 v221, v[86:89], s[10:11]
	s_mov_b64 exec, s[30:31]
	s_waitcnt lgkmcnt(0)
; #define PG8_LAS __attribute__((address_space(3)))
; __device__ __forceinline__ float dpp_ror1(float v) { return __builtin_bit_cast(float, __builtin_amdgcn_update_dpp(0, __builtin_bit_cast(int, v), 0x121, 0xf, 0xf, false)); }
; __device__ __forceinline__ float dpp_ror15(float v) { return __builtin_bit_cast(float, __builtin_amdgcn_update_dpp(0, __builtin_bit_cast(int, v), 0x12F, 0xf, 0xf, false)); }
;     __device__ __forceinline__ void operator()(const f32x4 (&acc)[2][2][4][2], const Unit& u, int wr, int wc, int fr, int fq) const {
;     ...
;                 for (int m = 0; m < 4; ++m) { const int r = 128 * ai + 64 * wr + 16 * m + fr, t = tstart + r;
;                     const bool upok = t >= 1, dnok = (t + 1) < T, store_ok = (r >= vlo) && (r < vhi) && (t < T);
;                     f32x4 res[2];
; #pragma unroll
;                     for (int bj = 0; bj < 2; ++bj) { const f32x4 cur = acc[ai][bj][m][n];
;                         f32x4 su = cur, sd = cur;
;                         if (m > 0) { if (fr == 15) su = acc[ai][bj][m > 0 ? m - 1 : 0][n]; }
;                         if (m < 3) { if (fr == 0) sd = acc[ai][bj][m < 3 ? m + 1 : 3][n]; }
;                         f32x4 up, dn;
;                         up[0] = dpp_ror1(su[0]); up[1] = dpp_ror1(su[1]); up[2] = dpp_ror1(su[2]); up[3] = dpp_ror1(su[3]);
;                         dn[0] = dpp_ror15(sd[0]); dn[1] = dpp_ror15(sd[1]); dn[2] = dpp_ror15(sd[2]); dn[3] = dpp_ror15(sd[3]);
;                         if (m == 0) { f32x4 halo = zero4; if (blk > 0) halo = *(const PG8_LAS f32x4*)(xb + (((((blk - 1) * 2 + 1) * 4 + wc) * 4 + fq) * 16 + (bj * 2 + n) * 4)); if (fr == 0) up = halo; }
;                         if (m == 3) { f32x4 halo = zero4; if (blk < 3) halo = *(const PG8_LAS f32x4*)(xb + (((((blk + 1) * 2 + 0) * 4 + wc) * 4 + fq) * 16 + (bj * 2 + n) * 4)); if (fr == 15) dn = halo; }
;                         if (edge) { if (!upok) up = zero4; if (!dnok) dn = zero4; }
;                         res[bj] = bb[bj] + w0[bj] * up + w1[bj] * cur + w2[bj] * dn; }
	v_add_u32_e32 v251, 0x42000, v247
	s_and_saveexec_b64 s[30:31], s[18:19]
	global_store_dwordx4 v251, v[78:81], s[10:11]
	s_mov_b64 exec, s[30:31]
	ds_write_b64 v243, v[32:33]
	ds_write_b64 v243, v[24:25] offset:256
	ds_write_b64 v243, v[16:17] offset:512
	ds_write_b64 v243, v[8:9] offset:768
	v_cndmask_b32_e64 v170, v170, v198, s[6:7]
	v_cndmask_b32_e64 v171, v171, v199, s[6:7]
	v_add_u32_e32 v220, s48, v234
	v_cmp_lt_i32_e32 vcc, 0, v220
	s_nop 1
	v_cndmask_b32_e32 v170, 0, v170, vcc
	v_cndmask_b32_e32 v171, 0, v171, vcc
	v_cmp_gt_i32_e32 vcc, s28, v220
	s_nop 1
	v_cndmask_b32_e32 v178, 0, v178, vcc
	v_cndmask_b32_e32 v179, 0, v179, vcc
	v_pk_fma_f32 v[202:203], v[138:139], v[170:171], v[150:151]
	v_pk_fma_f32 v[30:31], v[30:31], v[142:143], v[202:203]
	v_pk_fma_f32 v[30:31], v[146:147], v[178:179], v[30:31]
	ds_read_b64 v[170:171], v244
	ds_read_b64 v[178:179], v243 offset:16
	ds_read_b64 v[198:199], v238 offset:3096
	v_add_u32_e32 v220, s48, v235
	v_cmp_lt_i32_e32 vcc, 0, v220
	s_nop 1
	v_cndmask_b32_e32 v172, 0, v172, vcc
	v_cndmask_b32_e32 v173, 0, v173, vcc
	v_cmp_gt_i32_e32 vcc, s28, v220
	s_nop 1
	v_cndmask_b32_e32 v180, 0, v180, vcc
	v_cndmask_b32_e32 v181, 0, v181, vcc
	v_pk_fma_f32 v[202:203], v[138:139], v[172:173], v[150:151]
	v_pk_fma_f32 v[22:23], v[22:23], v[142:143], v[202:203]
	v_pk_fma_f32 v[22:23], v[146:147], v[180:181], v[22:23]
	ds_read_b64 v[172:173], v244 offset:256
	ds_read_b64 v[180:181], v243 offset:272
	v_add_u32_e32 v220, s48, v236
	v_cmp_lt_i32_e32 vcc, 0, v220
	s_nop 1
	v_cndmask_b32_e32 v174, 0, v174, vcc
	v_cndmask_b32_e32 v175, 0, v175, vcc
	v_cmp_gt_i32_e32 vcc, s28, v220
	s_nop 1
	v_cndmask_b32_e32 v194, 0, v194, vcc
	v_cndmask_b32_e32 v195, 0, v195, vcc
	v_pk_fma_f32 v[202:203], v[138:139], v[174:175], v[150:151]
	v_pk_fma_f32 v[14:15], v[14:15], v[142:143], v[202:203]
	v_pk_fma_f32 v[14:15], v[146:147], v[194:195], v[14:15]
	ds_read_b64 v[174:175], v244 offset:512
	ds_read_b64 v[194:195], v243 offset:528
	v_cndmask_b32_e64 v196, v196, v200, s[4:5]
	v_cndmask_b32_e64 v197, v197, v201, s[4:5]
	v_add_u32_e32 v220, s48, v237
	v_cmp_lt_i32_e32 vcc, 0, v220
	s_nop 1
	v_cndmask_b32_e32 v176, 0, v176, vcc
	v_cndmask_b32_e32 v177, 0, v177, vcc
	v_cmp_gt_i32_e32 vcc, s28, v220
	s_nop 1
	v_cndmask_b32_e32 v196, 0, v196, vcc
	v_cndmask_b32_e32 v197, 0, v197, vcc
	v_pk_fma_f32 v[202:203], v[138:139], v[176:177], v[150:151]
	v_pk_fma_f32 v[6:7], v[6:7], v[142:143], v[202:203]
	v_pk_fma_f32 v[6:7], v[146:147], v[196:197], v[6:7]
	ds_read_b64 v[176:177], v244 offset:768
	ds_read_b64 v[196:197], v243 offset:784
	ds_read_b64 v[200:201], v246 offset:24
	ds_write_b64 v243, v[26:27]
	ds_write_b64 v243, v[18:19] offset:256
	ds_write_b64 v243, v[10:11] offset:512
	ds_write_b64 v243, v[2:3] offset:768
	s_waitcnt lgkmcnt(11)
	v_cndmask_b32_e64 v170, v170, v198, s[6:7]
	v_cndmask_b32_e64 v171, v171, v199, s[6:7]
	v_add_u32_e32 v220, s48, v234
	v_cmp_lt_i32_e32 vcc, 0, v220
	s_nop 1
	v_cndmask_b32_e32 v170, 0, v170, vcc
	v_cndmask_b32_e32 v171, 0, v171, vcc
	v_cmp_gt_i32_e32 vcc, s28, v220
	s_nop 1
	v_cndmask_b32_e32 v178, 0, v178, vcc
	v_cndmask_b32_e32 v179, 0, v179, vcc
	v_pk_fma_f32 v[202:203], v[140:141], v[170:171], v[152:153]
	v_pk_fma_f32 v[32:33], v[32:33], v[144:145], v[202:203]
	v_pk_fma_f32 v[32:33], v[148:149], v[178:179], v[32:33]
	ds_read_b64 v[170:171], v244
	ds_read_b64 v[178:179], v243 offset:16
	ds_read_b64 v[198:199], v238 offset:3120
	s_waitcnt lgkmcnt(12)
	v_add_u32_e32 v220, s48, v235
	v_cmp_lt_i32_e32 vcc, 0, v220
	s_nop 1
	v_cndmask_b32_e32 v172, 0, v172, vcc
	v_cndmask_b32_e32 v173, 0, v173, vcc
	v_cmp_gt_i32_e32 vcc, s28, v220
	s_nop 1
	v_cndmask_b32_e32 v180, 0, v180, vcc
	v_cndmask_b32_e32 v181, 0, v181, vcc
	v_pk_fma_f32 v[202:203], v[140:141], v[172:173], v[152:153]
	v_pk_fma_f32 v[24:25], v[24:25], v[144:145], v[202:203]
	v_pk_fma_f32 v[24:25], v[148:149], v[180:181], v[24:25]
	ds_read_b64 v[172:173], v244 offset:256
	ds_read_b64 v[180:181], v243 offset:272
	s_waitcnt lgkmcnt(12)
	v_add_u32_e32 v220, s48, v236
	v_cmp_lt_i32_e32 vcc, 0, v220
	s_nop 1
	v_cndmask_b32_e32 v174, 0, v174, vcc
	v_cndmask_b32_e32 v175, 0, v175, vcc
	v_cmp_gt_i32_e32 vcc, s28, v220
	s_nop 1
	v_cndmask_b32_e32 v194, 0, v194, vcc
	v_cndmask_b32_e32 v195, 0, v195, vcc
	v_pk_fma_f32 v[202:203], v[140:141], v[174:175], v[152:153]
	v_pk_fma_f32 v[16:17], v[16:17], v[144:145], v[202:203]
	v_pk_fma_f32 v[16:17], v[148:149], v[194:195], v[16:17]
	ds_read_b64 v[174:175], v244 offset:512
	ds_read_b64 v[194:195], v243 offset:528
	s_waitcnt lgkmcnt(11)
	v_cndmask_b32_e64 v196, v196, v200, s[4:5]
	v_cndmask_b32_e64 v197, v197, v201, s[4:5]
	v_add_u32_e32 v220, s48, v237
	v_cmp_lt_i32_e32 vcc, 0, v220
	s_nop 1
	v_cndmask_b32_e32 v176, 0, v176, vcc
	v_cndmask_b32_e32 v177, 0, v177, vcc
	v_cmp_gt_i32_e32 vcc, s28, v220
	s_nop 1
	v_cndmask_b32_e32 v196, 0, v196, vcc
	v_cndmask_b32_e32 v197, 0, v197, vcc
	v_pk_fma_f32 v[202:203], v[140:141], v[176:177], v[152:153]
	v_pk_fma_f32 v[8:9], v[8:9], v[144:145], v[202:203]
	v_pk_fma_f32 v[8:9], v[148:149], v[196:197], v[8:9]
	ds_read_b64 v[176:177], v244 offset:768
	ds_read_b64 v[196:197], v243 offset:784
	ds_read_b64 v[200:201], v246 offset:48
	ds_write_b64 v243, v[28:29]
	ds_write_b64 v243, v[20:21] offset:256
	ds_write_b64 v243, v[12:13] offset:512
	ds_write_b64 v243, v[4:5] offset:768
	s_waitcnt lgkmcnt(11)
; #define PG8_LAS __attribute__((address_space(3)))
; __device__ __forceinline__ float dpp_ror1(float v) { return __builtin_bit_cast(float, __builtin_amdgcn_update_dpp(0, __builtin_bit_cast(int, v), 0x121, 0xf, 0xf, false)); }
; __device__ __forceinline__ float dpp_ror15(float v) { return __builtin_bit_cast(float, __builtin_amdgcn_update_dpp(0, __builtin_bit_cast(int, v), 0x12F, 0xf, 0xf, false)); }
;     __device__ __forceinline__ void operator()(const f32x4 (&acc)[2][2][4][2], const Unit& u, int wr, int wc, int fr, int fq) const {
;     ...
;                 for (int m = 0; m < 4; ++m) { const int r = 128 * ai + 64 * wr + 16 * m + fr, t = tstart + r;
;                     const bool upok = t >= 1, dnok = (t + 1) < T, store_ok = (r >= vlo) && (r < vhi) && (t < T);
;                     f32x4 res[2];
; #pragma unroll
;                     for (int bj = 0; bj < 2; ++bj) { const f32x4 cur = acc[ai][bj][m][n];
;                         f32x4 su = cur, sd = cur;
;                         if (m > 0) { if (fr == 15) su = acc[ai][bj][m > 0 ? m - 1 : 0][n]; }
;                         if (m < 3) { if (fr == 0) sd = acc[ai][bj][m < 3 ? m + 1 : 3][n]; }
;                         f32x4 up, dn;
;                         up[0] = dpp_ror1(su[0]); up[1] = dpp_ror1(su[1]); up[2] = dpp_ror1(su[2]); up[3] = dpp_ror1(su[3]);
;                         dn[0] = dpp_ror15(sd[0]); dn[1] = dpp_ror15(sd[1]); dn[2] = dpp_ror15(sd[2]); dn[3] = dpp_ror15(sd[3]);
;                         if (m == 0) { f32x4 halo = zero4; if (blk > 0) halo = *(const PG8_LAS f32x4*)(xb + (((((blk - 1) * 2 + 1) * 4 + wc) * 4 + fq) * 16 + (bj * 2 + n) * 4)); if (fr == 0) up = halo; }
;                         if (m == 3) { f32x4 halo = zero4; if (blk < 3) halo = *(const PG8_LAS f32x4*)(xb + (((((blk + 1) * 2 + 0) * 4 + wc) * 4 + fq) * 16 + (bj * 2 + n) * 4)); if (fr == 15) dn = halo; }
;                         if (edge) { if (!upok) up = zero4; if (!dnok) dn = zero4; }
;                         res[bj] = bb[bj] + w0[bj] * up + w1[bj] * cur + w2[bj] * dn; }
	v_cndmask_b32_e64 v170, v170, v198, s[6:7]
	v_cndmask_b32_e64 v171, v171, v199, s[6:7]
	v_add_u32_e32 v220, s48, v234
	v_cmp_lt_i32_e32 vcc, 0, v220
	s_nop 1
	v_cndmask_b32_e32 v170, 0, v170, vcc
	v_cndmask_b32_e32 v171, 0, v171, vcc
	v_cmp_gt_i32_e32 vcc, s28, v220
	s_nop 1
	v_cndmask_b32_e32 v178, 0, v178, vcc
	v_cndmask_b32_e32 v179, 0, v179, vcc
	v_pk_fma_f32 v[202:203], v[154:155], v[170:171], v[166:167]
	v_pk_fma_f32 v[26:27], v[26:27], v[158:159], v[202:203]
	v_pk_fma_f32 v[26:27], v[162:163], v[178:179], v[26:27]
	ds_read_b64 v[170:171], v244
	ds_read_b64 v[178:179], v243 offset:16
	ds_read_b64 v[198:199], v238 offset:3128
	s_waitcnt lgkmcnt(12)
	v_add_u32_e32 v220, s48, v235
	v_cmp_lt_i32_e32 vcc, 0, v220
	s_nop 1
	v_cndmask_b32_e32 v172, 0, v172, vcc
	v_cndmask_b32_e32 v173, 0, v173, vcc
	v_cmp_gt_i32_e32 vcc, s28, v220
	s_nop 1
	v_cndmask_b32_e32 v180, 0, v180, vcc
	v_cndmask_b32_e32 v181, 0, v181, vcc
	v_pk_fma_f32 v[202:203], v[154:155], v[172:173], v[166:167]
	v_pk_fma_f32 v[18:19], v[18:19], v[158:159], v[202:203]
	v_pk_fma_f32 v[18:19], v[162:163], v[180:181], v[18:19]
	ds_read_b64 v[172:173], v244 offset:256
	ds_read_b64 v[180:181], v243 offset:272
	s_waitcnt lgkmcnt(12)
	v_add_u32_e32 v220, s48, v236
	v_cmp_lt_i32_e32 vcc, 0, v220
	s_nop 1
	v_cndmask_b32_e32 v174, 0, v174, vcc
	v_cndmask_b32_e32 v175, 0, v175, vcc
	v_cmp_gt_i32_e32 vcc, s28, v220
	s_nop 1
	v_cndmask_b32_e32 v194, 0, v194, vcc
	v_cndmask_b32_e32 v195, 0, v195, vcc
	v_pk_fma_f32 v[202:203], v[154:155], v[174:175], v[166:167]
	v_pk_fma_f32 v[10:11], v[10:11], v[158:159], v[202:203]
	v_pk_fma_f32 v[10:11], v[162:163], v[194:195], v[10:11]
	ds_read_b64 v[174:175], v244 offset:512
	ds_read_b64 v[194:195], v243 offset:528
	s_waitcnt lgkmcnt(11)
	v_cndmask_b32_e64 v196, v196, v200, s[4:5]
	v_cndmask_b32_e64 v197, v197, v201, s[4:5]
	v_add_u32_e32 v220, s48, v237
	v_cmp_lt_i32_e32 vcc, 0, v220
	s_nop 1
	v_cndmask_b32_e32 v176, 0, v176, vcc
	v_cndmask_b32_e32 v177, 0, v177, vcc
	v_cmp_gt_i32_e32 vcc, s28, v220
	s_nop 1
	v_cndmask_b32_e32 v196, 0, v196, vcc
	v_cndmask_b32_e32 v197, 0, v197, vcc
	v_pk_fma_f32 v[202:203], v[154:155], v[176:177], v[166:167]
	v_pk_fma_f32 v[2:3], v[2:3], v[158:159], v[202:203]
	v_pk_fma_f32 v[2:3], v[162:163], v[196:197], v[2:3]
	ds_read_b64 v[176:177], v244 offset:768
	ds_read_b64 v[196:197], v243 offset:784
	ds_read_b64 v[200:201], v246 offset:56
	s_waitcnt lgkmcnt(7)
	v_cndmask_b32_e64 v170, v170, v198, s[6:7]
	v_cndmask_b32_e64 v171, v171, v199, s[6:7]
	v_add_u32_e32 v220, s48, v234
	v_cmp_lt_i32_e32 vcc, 0, v220
	s_nop 1
	v_cndmask_b32_e32 v170, 0, v170, vcc
	v_cndmask_b32_e32 v171, 0, v171, vcc
	v_cmp_gt_i32_e32 vcc, s28, v220
	s_nop 1
	v_cndmask_b32_e32 v178, 0, v178, vcc
	v_cndmask_b32_e32 v179, 0, v179, vcc
	v_pk_fma_f32 v[202:203], v[156:157], v[170:171], v[168:169]
	v_pk_fma_f32 v[28:29], v[28:29], v[160:161], v[202:203]
	v_pk_fma_f32 v[28:29], v[164:165], v[178:179], v[28:29]
	s_waitcnt lgkmcnt(5)
	v_add_u32_e32 v220, s48, v235
	v_cmp_lt_i32_e32 vcc, 0, v220
	s_nop 1
	v_cndmask_b32_e32 v172, 0, v172, vcc
	v_cndmask_b32_e32 v173, 0, v173, vcc
	v_cmp_gt_i32_e32 vcc, s28, v220
	s_nop 1
	v_cndmask_b32_e32 v180, 0, v180, vcc
	v_cndmask_b32_e32 v181, 0, v181, vcc
	v_pk_fma_f32 v[202:203], v[156:157], v[172:173], v[168:169]
	v_pk_fma_f32 v[20:21], v[20:21], v[160:161], v[202:203]
	v_pk_fma_f32 v[20:21], v[164:165], v[180:181], v[20:21]
	s_waitcnt lgkmcnt(3)
	v_add_u32_e32 v220, s48, v236
	v_cmp_lt_i32_e32 vcc, 0, v220
	s_nop 1
	v_cndmask_b32_e32 v174, 0, v174, vcc
	v_cndmask_b32_e32 v175, 0, v175, vcc
	v_cmp_gt_i32_e32 vcc, s28, v220
	s_nop 1
	v_cndmask_b32_e32 v194, 0, v194, vcc
	v_cndmask_b32_e32 v195, 0, v195, vcc
	v_pk_fma_f32 v[202:203], v[156:157], v[174:175], v[168:169]
	v_pk_fma_f32 v[12:13], v[12:13], v[160:161], v[202:203]
	v_pk_fma_f32 v[12:13], v[164:165], v[194:195], v[12:13]
	s_waitcnt lgkmcnt(0)
; #define PG8_LAS __attribute__((address_space(3)))
; __device__ __forceinline__ unsigned cvt_pk_bf16(float lo, float hi) { unsigned r; asm volatile("v_cvt_pk_bf16_f32 %0, %1, %2" : "=v"(r) : "v"(lo), "v"(hi)); return r; }
;     __device__ __forceinline__ void operator()(const f32x4 (&acc)[2][2][4][2], const Unit& u, int wr, int wc, int fr, int fq) const {
;     ...
;                 for (int m = 0; m < 4; ++m) { const int r = 128 * ai + 64 * wr + 16 * m + fr, t = tstart + r;
;                     const bool upok = t >= 1, dnok = (t + 1) < T, store_ok = (r >= vlo) && (r < vhi) && (t < T);
;                     f32x4 res[2];
; #pragma unroll
;                     for (int bj = 0; bj < 2; ++bj) { const f32x4 cur = acc[ai][bj][m][n];
;                         f32x4 su = cur, sd = cur;
;                         if (m > 0) { if (fr == 15) su = acc[ai][bj][m > 0 ? m - 1 : 0][n]; }
;                         if (m < 3) { if (fr == 0) sd = acc[ai][bj][m < 3 ? m + 1 : 3][n]; }
;                         f32x4 up, dn;
;                         up[0] = dpp_ror1(su[0]); up[1] = dpp_ror1(su[1]); up[2] = dpp_ror1(su[2]); up[3] = dpp_ror1(su[3]);
;                         dn[0] = dpp_ror15(sd[0]); dn[1] = dpp_ror15(sd[1]); dn[2] = dpp_ror15(sd[2]); dn[3] = dpp_ror15(sd[3]);
;                         if (m == 0) { f32x4 halo = zero4; if (blk > 0) halo = *(const PG8_LAS f32x4*)(xb + (((((blk - 1) * 2 + 1) * 4 + wc) * 4 + fq) * 16 + (bj * 2 + n) * 4)); if (fr == 0) up = halo; }
;                         if (m == 3) { f32x4 halo = zero4; if (blk < 3) halo = *(const PG8_LAS f32x4*)(xb + (((((blk + 1) * 2 + 0) * 4 + wc) * 4 + fq) * 16 + (bj * 2 + n) * 4)); if (fr == 15) dn = halo; }
;                         if (edge) { if (!upok) up = zero4; if (!dnok) dn = zero4; }
;                         res[bj] = bb[bj] + w0[bj] * up + w1[bj] * cur + w2[bj] * dn; }
;                     if (store_ok) {
;                         float o[4];
; #pragma unroll
;                         for (int j = 0; j < 4; ++j) { const float gg = res[1][j]; o[j] = gg * __builtin_amdgcn_rcpf(1.f + __expf(-gg)) * res[0][j]; }
;                         u32x2 w; w.x = cvt_pk_bf16(o[0], o[1]); w.y = cvt_pk_bf16(o[2], o[3]);
;                         *(u32x2*)(ACT + (size_t)(seqrow + t) * 2816 + ch0 + 4 * n) = w; } } }
	v_cndmask_b32_e64 v196, v196, v200, s[4:5]
	v_cndmask_b32_e64 v197, v197, v201, s[4:5]
	v_add_u32_e32 v220, s48, v237
	v_cmp_lt_i32_e32 vcc, 0, v220
	s_nop 1
	v_cndmask_b32_e32 v176, 0, v176, vcc
	v_cndmask_b32_e32 v177, 0, v177, vcc
	v_cmp_gt_i32_e32 vcc, s28, v220
	s_nop 1
	v_cndmask_b32_e32 v196, 0, v196, vcc
	v_cndmask_b32_e32 v197, 0, v197, vcc
	v_pk_fma_f32 v[202:203], v[156:157], v[176:177], v[168:169]
	v_pk_fma_f32 v[4:5], v[4:5], v[160:161], v[202:203]
	v_pk_fma_f32 v[4:5], v[164:165], v[196:197], v[4:5]
	v_mul_f32_e32 v208, 0xbfb8aa3b, v26
	v_mul_f32_e32 v209, 0xbfb8aa3b, v27
	v_mul_f32_e32 v210, 0xbfb8aa3b, v28
	v_mul_f32_e32 v211, 0xbfb8aa3b, v29
	v_exp_f32_e32 v208, v208
	v_exp_f32_e32 v209, v209
	v_exp_f32_e32 v210, v210
	v_exp_f32_e32 v211, v211
	v_add_f32_e32 v208, 1.0, v208
	v_add_f32_e32 v209, 1.0, v209
	v_add_f32_e32 v210, 1.0, v210
	v_add_f32_e32 v211, 1.0, v211
	v_rcp_f32_e32 v208, v208
	v_rcp_f32_e32 v209, v209
	v_rcp_f32_e32 v210, v210
	v_rcp_f32_e32 v211, v211
	v_mul_f32_e32 v26, v26, v208
	v_mul_f32_e32 v27, v27, v209
	v_mul_f32_e32 v28, v28, v210
	v_mul_f32_e32 v29, v29, v211
	v_mul_f32_e32 v26, v30, v26
	v_mul_f32_e32 v27, v31, v27
	v_mul_f32_e32 v28, v32, v28
	v_mul_f32_e32 v29, v33, v29
	v_cvt_pk_bf16_f32 v26, v26, v27
	v_cvt_pk_bf16_f32 v27, v28, v29
	ds_bpermute_b32 v100, v250, v26
	ds_bpermute_b32 v101, v250, v27
	v_mul_f32_e32 v208, 0xbfb8aa3b, v18
	v_mul_f32_e32 v209, 0xbfb8aa3b, v19
	v_mul_f32_e32 v210, 0xbfb8aa3b, v20
	v_mul_f32_e32 v211, 0xbfb8aa3b, v21
	v_exp_f32_e32 v208, v208
	v_exp_f32_e32 v209, v209
	v_exp_f32_e32 v210, v210
	v_exp_f32_e32 v211, v211
	v_add_f32_e32 v208, 1.0, v208
	v_add_f32_e32 v209, 1.0, v209
	v_add_f32_e32 v210, 1.0, v210
	v_add_f32_e32 v211, 1.0, v211
	v_rcp_f32_e32 v208, v208
	v_rcp_f32_e32 v209, v209
	v_rcp_f32_e32 v210, v210
	v_rcp_f32_e32 v211, v211
	v_mul_f32_e32 v18, v18, v208
	v_mul_f32_e32 v19, v19, v209
	v_mul_f32_e32 v20, v20, v210
	v_mul_f32_e32 v21, v21, v211
	v_mul_f32_e32 v18, v22, v18
	v_mul_f32_e32 v19, v23, v19
	v_mul_f32_e32 v20, v24, v20
	v_mul_f32_e32 v21, v25, v21
	v_cvt_pk_bf16_f32 v18, v18, v19
	v_cvt_pk_bf16_f32 v19, v20, v21
	ds_bpermute_b32 v92, v250, v18
	ds_bpermute_b32 v93, v250, v19
	v_mul_f32_e32 v208, 0xbfb8aa3b, v10
	v_mul_f32_e32 v209, 0xbfb8aa3b, v11
	v_mul_f32_e32 v210, 0xbfb8aa3b, v12
	v_mul_f32_e32 v211, 0xbfb8aa3b, v13
	v_exp_f32_e32 v208, v208
	v_exp_f32_e32 v209, v209
	v_exp_f32_e32 v210, v210
	v_exp_f32_e32 v211, v211
	v_add_f32_e32 v208, 1.0, v208
	v_add_f32_e32 v209, 1.0, v209
	v_add_f32_e32 v210, 1.0, v210
	v_add_f32_e32 v211, 1.0, v211
	v_rcp_f32_e32 v208, v208
	v_rcp_f32_e32 v209, v209
	v_rcp_f32_e32 v210, v210
	v_rcp_f32_e32 v211, v211
	v_mul_f32_e32 v10, v10, v208
	v_mul_f32_e32 v11, v11, v209
	v_mul_f32_e32 v12, v12, v210
	v_mul_f32_e32 v13, v13, v211
	v_mul_f32_e32 v10, v14, v10
	v_mul_f32_e32 v11, v15, v11
	v_mul_f32_e32 v12, v16, v12
	v_mul_f32_e32 v13, v17, v13
	v_cvt_pk_bf16_f32 v10, v10, v11
	v_cvt_pk_bf16_f32 v11, v12, v13
	ds_bpermute_b32 v84, v250, v10
	ds_bpermute_b32 v85, v250, v11
	v_mul_f32_e32 v208, 0xbfb8aa3b, v2
	v_mul_f32_e32 v209, 0xbfb8aa3b, v3
	v_mul_f32_e32 v210, 0xbfb8aa3b, v4
	v_mul_f32_e32 v211, 0xbfb8aa3b, v5
	v_exp_f32_e32 v208, v208
	v_exp_f32_e32 v209, v209
	v_exp_f32_e32 v210, v210
	v_exp_f32_e32 v211, v211
	v_add_f32_e32 v208, 1.0, v208
	v_add_f32_e32 v209, 1.0, v209
	v_add_f32_e32 v210, 1.0, v210
	v_add_f32_e32 v211, 1.0, v211
	v_rcp_f32_e32 v208, v208
	v_rcp_f32_e32 v209, v209
	v_rcp_f32_e32 v210, v210
	v_rcp_f32_e32 v211, v211
	v_mul_f32_e32 v2, v2, v208
	v_mul_f32_e32 v3, v3, v209
	v_mul_f32_e32 v4, v4, v210
	v_mul_f32_e32 v5, v5, v211
	v_mul_f32_e32 v2, v6, v2
	v_mul_f32_e32 v3, v7, v3
	v_mul_f32_e32 v4, v8, v4
	v_mul_f32_e32 v5, v9, v5
	v_cvt_pk_bf16_f32 v2, v2, v3
	v_cvt_pk_bf16_f32 v3, v4, v5
	ds_bpermute_b32 v76, v250, v2
	ds_bpermute_b32 v77, v250, v3
	s_waitcnt lgkmcnt(6)
	v_add_u32_e32 v221, 0xb0000, v247
	s_and_saveexec_b64 s[30:31], s[20:21]
	global_store_dwordx4 v221, v[98:101], s[10:11]
	s_mov_b64 exec, s[30:31]
	s_waitcnt lgkmcnt(4)
	v_add_u32_e32 v251, 0xc6000, v247
	s_and_saveexec_b64 s[30:31], s[22:23]
	global_store_dwordx4 v251, v[90:93], s[10:11]
	s_mov_b64 exec, s[30:31]
	s_waitcnt lgkmcnt(2)
	v_add_u32_e32 v221, 0xdc000, v247
	s_and_saveexec_b64 s[30:31], s[24:25]
	global_store_dwordx4 v221, v[82:85], s[10:11]
	s_mov_b64 exec, s[30:31]
	s_waitcnt lgkmcnt(0)
	v_add_u32_e32 v251, 0xf2000, v247
	s_and_saveexec_b64 s[30:31], s[26:27]
	global_store_dwordx4 v251, v[74:77], s[10:11]
	s_mov_b64 exec, s[30:31]
